# hyena: prefetch of the phyT rows read by the stage prologue/epilogues, issued before the LDS-only FFT passes
# speedup vs baseline: 1.3825x; 1.0148x over previous
; __device__ __forceinline__ void phase_hyena(KP kp_, int hf){ asm volatile("" : "+s"(kp_)); const Params p=load_params(kp_);
;     ...
;     const u16* rv=phyT+(size_t)cl*16384; const u16* r1=phyT+(size_t)(512+cl)*16384; const u16* r2=phyT+(size_t)(1024+cl)*16384; const u16* rz=phyT+(size_t)(1536+cl)*16384;
.LBB0_1333:
	s_cmp_lg_u32 s89, 0
	s_cbranch_scc1 .Lmy_pf_skipb
	v_lshlrev_b32_e32 v232, 4, v154
	s_lshl_b32 s100, s90, 15
	v_add_u32_e32 v233, 0x2000, v232
	v_add_u32_e32 v234, 0x4000, v232
	v_add_u32_e32 v235, 0x6000, v232
	s_add_u32 s98, s70, 0x42bd000
	s_addc_u32 s99, s71, 0
	s_add_u32 s98, s98, s100
	s_addc_u32 s99, s99, 0
	global_load_dwordx4 v[228:231], v232, s[98:99]
	global_load_dwordx4 v[228:231], v233, s[98:99]
	global_load_dwordx4 v[228:231], v234, s[98:99]
	global_load_dwordx4 v[228:231], v235, s[98:99]

; HD float2 cmul(float2 a, float2 b){ return make_float2(a.x*b.x - a.y*b.y, a.x*b.y + a.y*b.x); }
; __device__ __forceinline__ void fft_mid(float2* Z, const f16x2* Hp, int tid){
;   _Pragma("unroll 4") for (int i=0;i<8;++i){ int base=(tid<<2)+i*2048;
;     u32x4 hw=*(const u32x4*)(Hp+base);
;     unsigned hw0=hw[0], hw1=hw[1], hw2=hw[2], hw3=hw[3];
;     float2 a0=Z[base], a1=Z[base+1], a2=Z[base+2], a3=Z[base+3];
;     float2 s02=make_float2(a0.x+a2.x,a0.y+a2.y), d02=make_float2(a0.x-a2.x,a0.y-a2.y);
;     float2 s13=make_float2(a1.x+a3.x,a1.y+a3.y), d13=make_float2(a1.x-a3.x,a1.y-a3.y);
;     float2 y0=make_float2(s02.x+s13.x,s02.y+s13.y), y2=make_float2(s02.x-s13.x,s02.y-s13.y);
;     float2 y1=make_float2(d02.x+d13.y,d02.y-d13.x);
;     float2 y3=make_float2(d02.x-d13.y,d02.y+d13.x);
;     f16x2 h0=__builtin_bit_cast(f16x2,hw0), h1=__builtin_bit_cast(f16x2,hw1), h2=__builtin_bit_cast(f16x2,hw2), h3=__builtin_bit_cast(f16x2,hw3);
;     float2 b0=cmul(y0,make_float2((float)h0[0],(float)h0[1])), b1=cmul(y1,make_float2((float)h1[0],(float)h1[1]));
;     float2 b2=cmul(y2,make_float2((float)h2[0],(float)h2[1])), b3=cmul(y3,make_float2((float)h3[0],(float)h3[1]));
;     float2 t02=make_float2(b0.x+b2.x,b0.y+b2.y), e02=make_float2(b0.x-b2.x,b0.y-b2.y);
;     float2 t13=make_float2(b1.x+b3.x,b1.y+b3.y), e13=make_float2(b1.x-b3.x,b1.y-b3.y);
;     Z[base]=make_float2(t02.x+t13.x,t02.y+t13.y); Z[base+2]=make_float2(t02.x-t13.x,t02.y-t13.y);
;     Z[base+1]=make_float2(e02.x-e13.y,e02.y+e13.x);
;     Z[base+3]=make_float2(e02.x+e13.y,e02.y-e13.x);
;   }
.LBB0_1335:
	flat_load_dwordx4 v[6:9], v[0:1]
	v_add_u32_e32 v4, s12, v203
	ds_read_b128 v[10:13], v4
	ds_read_b128 v[20:23], v4 offset:16
	v_ashrrev_i32_e32 v3, 31, v2
	s_add_i32 s12, s12, 0x10000
	s_mov_b64 s[18:19], 0x8000
	s_waitcnt lgkmcnt(0)
	v_mov_b32_e32 v24, v11
	v_mov_b32_e32 v26, v21
	v_mov_b32_e32 v28, v11
	v_mov_b32_e32 v29, v13
	v_mov_b32_e32 v30, v21
	v_mov_b32_e32 v31, v23
	v_mov_b32_e32 v11, v12
	v_mov_b32_e32 v21, v22
	v_mov_b32_e32 v25, v12
	v_pk_add_f32 v[28:29], v[28:29], v[30:31]
	v_pk_add_f32 v[30:31], v[10:11], v[20:21]
	v_mov_b32_e32 v11, v13
	v_mov_b32_e32 v27, v22
	v_mov_b32_e32 v21, v23
	v_pk_add_f32 v[22:23], v[28:29], v[28:29] op_sel:[0,1] op_sel_hi:[0,1]
	v_pk_add_f32 v[10:11], v[10:11], v[20:21] neg_lo:[0,1] neg_hi:[0,1]
	v_pk_add_f32 v[20:21], v[30:31], v[30:31] op_sel:[0,1] op_sel_hi:[0,1]
	v_pk_add_f32 v[24:25], v[24:25], v[26:27] neg_lo:[0,1] neg_hi:[0,1]
	v_lshl_add_u64 v[0:1], v[0:1], 0, s[18:19]
	s_cmp_lg_u32 s12, 0x20000
	s_waitcnt vmcnt(0)
	v_cvt_f32_f16_sdwa v13, v6 dst_sel:DWORD dst_unused:UNUSED_PAD src0_sel:WORD_1
	v_cvt_f32_f16_e32 v12, v6
	v_pk_mul_f32 v[22:23], v[22:23], v[12:13] op_sel:[0,1] op_sel_hi:[1,0]
	s_nop 0
	v_pk_fma_f32 v[26:27], v[20:21], v[12:13], v[22:23] neg_lo:[0,0,1] neg_hi:[0,0,1]
	v_pk_fma_f32 v[12:13], v[20:21], v[12:13], v[22:23]
	v_pk_add_f32 v[20:21], v[24:25], v[24:25] op_sel:[0,1] op_sel_hi:[0,1] neg_lo:[0,1] neg_hi:[0,1]
	v_mov_b32_e32 v27, v13
	v_cvt_f32_f16_sdwa v13, v7 dst_sel:DWORD dst_unused:UNUSED_PAD src0_sel:WORD_1
	v_cvt_f32_f16_e32 v12, v7
	v_pk_add_f32 v[6:7], v[10:11], v[10:11] op_sel:[0,1] op_sel_hi:[0,1]
	v_pk_mul_f32 v[20:21], v[20:21], v[12:13] op_sel:[0,1] op_sel_hi:[1,0]
	s_nop 0
	v_pk_fma_f32 v[22:23], v[6:7], v[12:13], v[20:21] neg_lo:[0,0,1] neg_hi:[0,0,1]
	v_pk_fma_f32 v[6:7], v[6:7], v[12:13], v[20:21]
	v_pk_add_f32 v[20:21], v[28:29], v[28:29] op_sel:[0,1] op_sel_hi:[0,1] neg_lo:[0,1] neg_hi:[0,1]
	v_mov_b32_e32 v23, v7
	v_cvt_f32_f16_sdwa v7, v8 dst_sel:DWORD dst_unused:UNUSED_PAD src0_sel:WORD_1
	v_cvt_f32_f16_e32 v6, v8
	v_pk_add_f32 v[12:13], v[30:31], v[30:31] op_sel:[0,1] op_sel_hi:[0,1] neg_lo:[0,1] neg_hi:[0,1]
	v_pk_mul_f32 v[20:21], v[20:21], v[6:7] op_sel:[0,1] op_sel_hi:[1,0]
	s_nop 0
	v_pk_fma_f32 v[28:29], v[12:13], v[6:7], v[20:21] neg_lo:[0,0,1] neg_hi:[0,0,1]
	v_pk_fma_f32 v[6:7], v[12:13], v[6:7], v[20:21]
	s_nop 0
	v_mov_b32_e32 v29, v7
	v_cvt_f32_f16_sdwa v7, v9 dst_sel:DWORD dst_unused:UNUSED_PAD src0_sel:WORD_1
	v_cvt_f32_f16_e32 v6, v9
	v_pk_add_f32 v[8:9], v[10:11], v[10:11] op_sel:[0,1] op_sel_hi:[0,1] neg_lo:[0,1] neg_hi:[0,1]
	v_pk_add_f32 v[10:11], v[24:25], v[24:25] op_sel:[0,1] op_sel_hi:[0,1]
	v_pk_mul_f32 v[10:11], v[10:11], v[6:7] op_sel:[0,1] op_sel_hi:[1,0]
	s_nop 0
	v_pk_fma_f32 v[12:13], v[8:9], v[6:7], v[10:11] neg_lo:[0,0,1] neg_hi:[0,0,1]
	v_pk_fma_f32 v[6:7], v[8:9], v[6:7], v[10:11]
	v_pk_add_f32 v[8:9], v[26:27], v[28:29]
	v_mov_b32_e32 v13, v7
	v_pk_add_f32 v[10:11], v[22:23], v[12:13]
	v_pk_add_f32 v[12:13], v[22:23], v[12:13] neg_lo:[0,1] neg_hi:[0,1]
	v_pk_add_f32 v[6:7], v[8:9], v[10:11]
	v_pk_add_f32 v[10:11], v[8:9], v[10:11] neg_lo:[0,1] neg_hi:[0,1]
	v_pk_add_f32 v[8:9], v[26:27], v[28:29] neg_lo:[0,1] neg_hi:[0,1]
	s_nop 0
	v_pk_add_f32 v[20:21], v[8:9], v[12:13] op_sel:[0,1] op_sel_hi:[1,0] neg_lo:[0,1] neg_hi:[0,1]
	v_pk_add_f32 v[12:13], v[8:9], v[12:13] op_sel:[0,1] op_sel_hi:[1,0]
	v_mov_b32_e32 v8, v20
	v_mov_b32_e32 v9, v13
	ds_write_b128 v4, v[6:9]
	v_add_u32_e32 v6, 0xfffff000, v2
	v_mov_b32_e32 v13, v21
	v_ashrrev_i32_e32 v7, 31, v6
	ds_write_b128 v4, v[10:13] offset:16
	v_lshl_add_u64 v[6:7], v[6:7], 2, s[68:69]
	flat_load_dwordx4 v[6:9], v[6:7]
	ds_read_b128 v[10:13], v4 offset:16384
	ds_read_b128 v[20:23], v4 offset:16400
	s_waitcnt lgkmcnt(0)
	v_mov_b32_e32 v24, v11
	v_mov_b32_e32 v26, v21
	v_mov_b32_e32 v28, v11
	v_mov_b32_e32 v29, v13
	v_mov_b32_e32 v30, v21
	v_mov_b32_e32 v31, v23
	v_mov_b32_e32 v11, v12
	v_mov_b32_e32 v21, v22
	v_mov_b32_e32 v25, v12
	v_pk_add_f32 v[28:29], v[28:29], v[30:31]
	v_pk_add_f32 v[30:31], v[10:11], v[20:21]
	v_mov_b32_e32 v11, v13
	v_mov_b32_e32 v27, v22
	v_mov_b32_e32 v21, v23
	v_pk_add_f32 v[22:23], v[28:29], v[28:29] op_sel:[0,1] op_sel_hi:[0,1]
	v_pk_add_f32 v[24:25], v[24:25], v[26:27] neg_lo:[0,1] neg_hi:[0,1]
	v_pk_add_f32 v[10:11], v[10:11], v[20:21] neg_lo:[0,1] neg_hi:[0,1]
	v_pk_add_f32 v[20:21], v[30:31], v[30:31] op_sel:[0,1] op_sel_hi:[0,1]
	s_waitcnt vmcnt(0)
; HD float2 cmul(float2 a, float2 b){ return make_float2(a.x*b.x - a.y*b.y, a.x*b.y + a.y*b.x); }
; __device__ __forceinline__ void fft_mid(float2* Z, const f16x2* Hp, int tid){
;   _Pragma("unroll 4") for (int i=0;i<8;++i){ int base=(tid<<2)+i*2048;
;     u32x4 hw=*(const u32x4*)(Hp+base);
;     unsigned hw0=hw[0], hw1=hw[1], hw2=hw[2], hw3=hw[3];
;     float2 a0=Z[base], a1=Z[base+1], a2=Z[base+2], a3=Z[base+3];
;     float2 s02=make_float2(a0.x+a2.x,a0.y+a2.y), d02=make_float2(a0.x-a2.x,a0.y-a2.y);
;     float2 s13=make_float2(a1.x+a3.x,a1.y+a3.y), d13=make_float2(a1.x-a3.x,a1.y-a3.y);
;     float2 y0=make_float2(s02.x+s13.x,s02.y+s13.y), y2=make_float2(s02.x-s13.x,s02.y-s13.y);
;     float2 y1=make_float2(d02.x+d13.y,d02.y-d13.x);
;     float2 y3=make_float2(d02.x-d13.y,d02.y+d13.x);
;     f16x2 h0=__builtin_bit_cast(f16x2,hw0), h1=__builtin_bit_cast(f16x2,hw1), h2=__builtin_bit_cast(f16x2,hw2), h3=__builtin_bit_cast(f16x2,hw3);
;     float2 b0=cmul(y0,make_float2((float)h0[0],(float)h0[1])), b1=cmul(y1,make_float2((float)h1[0],(float)h1[1]));
;     float2 b2=cmul(y2,make_float2((float)h2[0],(float)h2[1])), b3=cmul(y3,make_float2((float)h3[0],(float)h3[1]));
;     float2 t02=make_float2(b0.x+b2.x,b0.y+b2.y), e02=make_float2(b0.x-b2.x,b0.y-b2.y);
;     float2 t13=make_float2(b1.x+b3.x,b1.y+b3.y), e13=make_float2(b1.x-b3.x,b1.y-b3.y);
;     Z[base]=make_float2(t02.x+t13.x,t02.y+t13.y); Z[base+2]=make_float2(t02.x-t13.x,t02.y-t13.y);
;     Z[base+1]=make_float2(e02.x-e13.y,e02.y+e13.x);
;     Z[base+3]=make_float2(e02.x+e13.y,e02.y-e13.x);
;   }
	v_cvt_f32_f16_e32 v12, v6
	v_cvt_f32_f16_sdwa v13, v6 dst_sel:DWORD dst_unused:UNUSED_PAD src0_sel:WORD_1
	v_cvt_f32_f16_e32 v6, v7
	v_cvt_f32_f16_sdwa v7, v7 dst_sel:DWORD dst_unused:UNUSED_PAD src0_sel:WORD_1
	v_pk_mul_f32 v[22:23], v[22:23], v[12:13] op_sel:[0,1] op_sel_hi:[1,0]
	s_nop 0
	v_pk_fma_f32 v[26:27], v[20:21], v[12:13], v[22:23] neg_lo:[0,0,1] neg_hi:[0,0,1]
	v_pk_fma_f32 v[12:13], v[20:21], v[12:13], v[22:23]
	v_pk_add_f32 v[20:21], v[24:25], v[24:25] op_sel:[0,1] op_sel_hi:[0,1] neg_lo:[0,1] neg_hi:[0,1]
	v_mov_b32_e32 v27, v13
	v_pk_add_f32 v[12:13], v[10:11], v[10:11] op_sel:[0,1] op_sel_hi:[0,1]
	v_pk_mul_f32 v[20:21], v[20:21], v[6:7] op_sel:[0,1] op_sel_hi:[1,0]
	s_nop 0
	v_pk_fma_f32 v[22:23], v[12:13], v[6:7], v[20:21] neg_lo:[0,0,1] neg_hi:[0,0,1]
	v_pk_fma_f32 v[6:7], v[12:13], v[6:7], v[20:21]
	v_pk_add_f32 v[20:21], v[28:29], v[28:29] op_sel:[0,1] op_sel_hi:[0,1] neg_lo:[0,1] neg_hi:[0,1]
	v_mov_b32_e32 v23, v7
	v_cvt_f32_f16_e32 v6, v8
	v_cvt_f32_f16_sdwa v7, v8 dst_sel:DWORD dst_unused:UNUSED_PAD src0_sel:WORD_1
	v_pk_add_f32 v[12:13], v[30:31], v[30:31] op_sel:[0,1] op_sel_hi:[0,1] neg_lo:[0,1] neg_hi:[0,1]
	v_pk_mul_f32 v[20:21], v[20:21], v[6:7] op_sel:[0,1] op_sel_hi:[1,0]
	s_nop 0
	v_pk_fma_f32 v[28:29], v[12:13], v[6:7], v[20:21] neg_lo:[0,0,1] neg_hi:[0,0,1]
	v_pk_fma_f32 v[6:7], v[12:13], v[6:7], v[20:21]
	s_nop 0
	v_mov_b32_e32 v29, v7
	v_cvt_f32_f16_e32 v6, v9
	v_cvt_f32_f16_sdwa v7, v9 dst_sel:DWORD dst_unused:UNUSED_PAD src0_sel:WORD_1
	v_pk_add_f32 v[8:9], v[10:11], v[10:11] op_sel:[0,1] op_sel_hi:[0,1] neg_lo:[0,1] neg_hi:[0,1]
	v_pk_add_f32 v[10:11], v[24:25], v[24:25] op_sel:[0,1] op_sel_hi:[0,1]
	v_pk_mul_f32 v[10:11], v[10:11], v[6:7] op_sel:[0,1] op_sel_hi:[1,0]
	s_nop 0
	v_pk_fma_f32 v[12:13], v[8:9], v[6:7], v[10:11] neg_lo:[0,0,1] neg_hi:[0,0,1]
	v_pk_fma_f32 v[6:7], v[8:9], v[6:7], v[10:11]
	v_pk_add_f32 v[8:9], v[26:27], v[28:29]
	v_mov_b32_e32 v13, v7
	v_pk_add_f32 v[10:11], v[22:23], v[12:13]
	v_pk_add_f32 v[12:13], v[22:23], v[12:13] neg_lo:[0,1] neg_hi:[0,1]
	v_pk_add_f32 v[6:7], v[8:9], v[10:11]
	v_pk_add_f32 v[10:11], v[8:9], v[10:11] neg_lo:[0,1] neg_hi:[0,1]
	v_pk_add_f32 v[8:9], v[26:27], v[28:29] neg_lo:[0,1] neg_hi:[0,1]
	s_nop 0
	v_pk_add_f32 v[20:21], v[8:9], v[12:13] op_sel:[0,1] op_sel_hi:[1,0] neg_lo:[0,1] neg_hi:[0,1]
	v_pk_add_f32 v[12:13], v[8:9], v[12:13] op_sel:[0,1] op_sel_hi:[1,0]
	v_mov_b32_e32 v8, v20
	v_mov_b32_e32 v9, v13
	ds_write_b128 v4, v[6:9] offset:16384
	v_add_u32_e32 v6, 0xfffff800, v2
	v_mov_b32_e32 v13, v21
	v_ashrrev_i32_e32 v7, 31, v6
	ds_write_b128 v4, v[10:13] offset:16400
	v_lshl_add_u64 v[6:7], v[6:7], 2, s[68:69]
	flat_load_dwordx4 v[6:9], v[6:7]
	ds_read_b128 v[10:13], v4 offset:32768
	ds_read_b128 v[20:23], v4 offset:32784
	s_waitcnt lgkmcnt(0)
	v_mov_b32_e32 v24, v11
	v_mov_b32_e32 v26, v21
	v_mov_b32_e32 v28, v11
	v_mov_b32_e32 v29, v13
	v_mov_b32_e32 v30, v21
	v_mov_b32_e32 v31, v23
	v_mov_b32_e32 v11, v12
	v_mov_b32_e32 v21, v22
	v_mov_b32_e32 v25, v12
	v_pk_add_f32 v[28:29], v[28:29], v[30:31]
	v_pk_add_f32 v[30:31], v[10:11], v[20:21]
	v_mov_b32_e32 v11, v13
	v_mov_b32_e32 v27, v22
	v_mov_b32_e32 v21, v23
	v_pk_add_f32 v[22:23], v[28:29], v[28:29] op_sel:[0,1] op_sel_hi:[0,1]
	v_pk_add_f32 v[24:25], v[24:25], v[26:27] neg_lo:[0,1] neg_hi:[0,1]
	v_pk_add_f32 v[10:11], v[10:11], v[20:21] neg_lo:[0,1] neg_hi:[0,1]
	v_pk_add_f32 v[20:21], v[30:31], v[30:31] op_sel:[0,1] op_sel_hi:[0,1]
	s_waitcnt vmcnt(0)
	v_cvt_f32_f16_e32 v12, v6
	v_cvt_f32_f16_sdwa v13, v6 dst_sel:DWORD dst_unused:UNUSED_PAD src0_sel:WORD_1
	v_cvt_f32_f16_e32 v6, v7
	v_cvt_f32_f16_sdwa v7, v7 dst_sel:DWORD dst_unused:UNUSED_PAD src0_sel:WORD_1
	v_pk_mul_f32 v[22:23], v[22:23], v[12:13] op_sel:[0,1] op_sel_hi:[1,0]
	s_nop 0
	v_pk_fma_f32 v[26:27], v[20:21], v[12:13], v[22:23] neg_lo:[0,0,1] neg_hi:[0,0,1]
	v_pk_fma_f32 v[12:13], v[20:21], v[12:13], v[22:23]
	v_pk_add_f32 v[20:21], v[24:25], v[24:25] op_sel:[0,1] op_sel_hi:[0,1] neg_lo:[0,1] neg_hi:[0,1]
	v_mov_b32_e32 v27, v13
	v_pk_add_f32 v[12:13], v[10:11], v[10:11] op_sel:[0,1] op_sel_hi:[0,1]
	v_pk_mul_f32 v[20:21], v[20:21], v[6:7] op_sel:[0,1] op_sel_hi:[1,0]
	s_nop 0
	v_pk_fma_f32 v[22:23], v[12:13], v[6:7], v[20:21] neg_lo:[0,0,1] neg_hi:[0,0,1]
	v_pk_fma_f32 v[6:7], v[12:13], v[6:7], v[20:21]
	v_pk_add_f32 v[20:21], v[28:29], v[28:29] op_sel:[0,1] op_sel_hi:[0,1] neg_lo:[0,1] neg_hi:[0,1]
	v_mov_b32_e32 v23, v7
	v_cvt_f32_f16_e32 v6, v8
	v_cvt_f32_f16_sdwa v7, v8 dst_sel:DWORD dst_unused:UNUSED_PAD src0_sel:WORD_1
	v_pk_add_f32 v[12:13], v[30:31], v[30:31] op_sel:[0,1] op_sel_hi:[0,1] neg_lo:[0,1] neg_hi:[0,1]
	v_pk_mul_f32 v[20:21], v[20:21], v[6:7] op_sel:[0,1] op_sel_hi:[1,0]
	s_nop 0
	v_pk_fma_f32 v[28:29], v[12:13], v[6:7], v[20:21] neg_lo:[0,0,1] neg_hi:[0,0,1]
	v_pk_fma_f32 v[6:7], v[12:13], v[6:7], v[20:21]
	s_nop 0
	v_mov_b32_e32 v29, v7
	v_cvt_f32_f16_e32 v6, v9
	v_cvt_f32_f16_sdwa v7, v9 dst_sel:DWORD dst_unused:UNUSED_PAD src0_sel:WORD_1
	v_pk_add_f32 v[8:9], v[10:11], v[10:11] op_sel:[0,1] op_sel_hi:[0,1] neg_lo:[0,1] neg_hi:[0,1]
	v_pk_add_f32 v[10:11], v[24:25], v[24:25] op_sel:[0,1] op_sel_hi:[0,1]
	v_pk_mul_f32 v[10:11], v[10:11], v[6:7] op_sel:[0,1] op_sel_hi:[1,0]
	s_nop 0
	v_pk_fma_f32 v[12:13], v[8:9], v[6:7], v[10:11] neg_lo:[0,0,1] neg_hi:[0,0,1]
	v_pk_fma_f32 v[6:7], v[8:9], v[6:7], v[10:11]
	v_pk_add_f32 v[8:9], v[26:27], v[28:29]
	v_mov_b32_e32 v13, v7
	v_pk_add_f32 v[10:11], v[22:23], v[12:13]
	v_pk_add_f32 v[12:13], v[22:23], v[12:13] neg_lo:[0,1] neg_hi:[0,1]
	v_pk_add_f32 v[6:7], v[8:9], v[10:11]
	v_pk_add_f32 v[10:11], v[8:9], v[10:11] neg_lo:[0,1] neg_hi:[0,1]
	v_pk_add_f32 v[8:9], v[26:27], v[28:29] neg_lo:[0,1] neg_hi:[0,1]
	s_nop 0
	v_pk_add_f32 v[20:21], v[8:9], v[12:13] op_sel:[0,1] op_sel_hi:[1,0] neg_lo:[0,1] neg_hi:[0,1]
	v_pk_add_f32 v[12:13], v[8:9], v[12:13] op_sel:[0,1] op_sel_hi:[1,0]
	v_mov_b32_e32 v8, v20
	v_mov_b32_e32 v9, v13
	v_mov_b32_e32 v13, v21
	ds_write_b128 v4, v[6:9] offset:32768
	ds_write_b128 v4, v[10:13] offset:32784
	v_lshl_add_u64 v[6:7], v[2:3], 2, s[68:69]
	flat_load_dwordx4 v[6:9], v[6:7]
	ds_read_b128 v[10:13], v4 offset:49152
	ds_read_b128 v[20:23], v4 offset:49168
	v_add_u32_e32 v2, 0x2000, v2
	s_waitcnt lgkmcnt(0)
; HD float2 cmul(float2 a, float2 b){ return make_float2(a.x*b.x - a.y*b.y, a.x*b.y + a.y*b.x); }
; template<bool INV, int LQ, bool BARRIER=true>
; HD void fft_pass(float2* Z, const float2* twA, const float2* twB, int tid){
;     ...
;     int j=tid&(q-1); int base0=((tid>>LQ)<<(LQ+2))+j;
;     float2 w1=make_float2(1.f,0.f), w2=w1, w3=w1;
;     if (LQ>0){ int k=j*tws; w1=cmul(twA[k>>6],twB[k&63]); w2=cmul(w1,w1); w3=cmul(w2,w1); }
;     _Pragma("unroll") for (int i=0;i<8;++i){ int base=base0+i*2048; bf4c<INV,(LQ==0)>(Z,base,base+q,base+2*q,base+3*q,w1,w2,w3); }
; __device__ __forceinline__ void fft_mid(float2* Z, const f16x2* Hp, int tid){
;   _Pragma("unroll 4") for (int i=0;i<8;++i){ int base=(tid<<2)+i*2048;
;     u32x4 hw=*(const u32x4*)(Hp+base);
;     unsigned hw0=hw[0], hw1=hw[1], hw2=hw[2], hw3=hw[3];
;     float2 a0=Z[base], a1=Z[base+1], a2=Z[base+2], a3=Z[base+3];
;     float2 s02=make_float2(a0.x+a2.x,a0.y+a2.y), d02=make_float2(a0.x-a2.x,a0.y-a2.y);
;     float2 s13=make_float2(a1.x+a3.x,a1.y+a3.y), d13=make_float2(a1.x-a3.x,a1.y-a3.y);
;     float2 y0=make_float2(s02.x+s13.x,s02.y+s13.y), y2=make_float2(s02.x-s13.x,s02.y-s13.y);
;     float2 y1=make_float2(d02.x+d13.y,d02.y-d13.x);
;     float2 y3=make_float2(d02.x-d13.y,d02.y+d13.x);
;     f16x2 h0=__builtin_bit_cast(f16x2,hw0), h1=__builtin_bit_cast(f16x2,hw1), h2=__builtin_bit_cast(f16x2,hw2), h3=__builtin_bit_cast(f16x2,hw3);
;     float2 b0=cmul(y0,make_float2((float)h0[0],(float)h0[1])), b1=cmul(y1,make_float2((float)h1[0],(float)h1[1]));
;     float2 b2=cmul(y2,make_float2((float)h2[0],(float)h2[1])), b3=cmul(y3,make_float2((float)h3[0],(float)h3[1]));
;     float2 t02=make_float2(b0.x+b2.x,b0.y+b2.y), e02=make_float2(b0.x-b2.x,b0.y-b2.y);
;     float2 t13=make_float2(b1.x+b3.x,b1.y+b3.y), e13=make_float2(b1.x-b3.x,b1.y-b3.y);
;     Z[base]=make_float2(t02.x+t13.x,t02.y+t13.y); Z[base+2]=make_float2(t02.x-t13.x,t02.y-t13.y);
;     Z[base+1]=make_float2(e02.x-e13.y,e02.y+e13.x);
;     Z[base+3]=make_float2(e02.x+e13.y,e02.y-e13.x);
;   }
	v_mov_b32_e32 v24, v11
	v_mov_b32_e32 v26, v21
	v_mov_b32_e32 v28, v11
	v_mov_b32_e32 v29, v13
	v_mov_b32_e32 v30, v21
	v_mov_b32_e32 v31, v23
	v_mov_b32_e32 v11, v12
	v_mov_b32_e32 v21, v22
	v_mov_b32_e32 v25, v12
	v_pk_add_f32 v[28:29], v[28:29], v[30:31]
	v_pk_add_f32 v[30:31], v[10:11], v[20:21]
	v_mov_b32_e32 v11, v13
	v_mov_b32_e32 v27, v22
	v_mov_b32_e32 v21, v23
	v_pk_add_f32 v[22:23], v[28:29], v[28:29] op_sel:[0,1] op_sel_hi:[0,1]
	v_pk_add_f32 v[24:25], v[24:25], v[26:27] neg_lo:[0,1] neg_hi:[0,1]
	v_pk_add_f32 v[10:11], v[10:11], v[20:21] neg_lo:[0,1] neg_hi:[0,1]
	v_pk_add_f32 v[20:21], v[30:31], v[30:31] op_sel:[0,1] op_sel_hi:[0,1]
	s_waitcnt vmcnt(0)
	v_cvt_f32_f16_e32 v12, v6
	v_cvt_f32_f16_sdwa v13, v6 dst_sel:DWORD dst_unused:UNUSED_PAD src0_sel:WORD_1
	v_cvt_f32_f16_e32 v6, v7
	v_cvt_f32_f16_sdwa v7, v7 dst_sel:DWORD dst_unused:UNUSED_PAD src0_sel:WORD_1
	v_pk_mul_f32 v[22:23], v[22:23], v[12:13] op_sel:[0,1] op_sel_hi:[1,0]
	s_nop 0
	v_pk_fma_f32 v[26:27], v[20:21], v[12:13], v[22:23] neg_lo:[0,0,1] neg_hi:[0,0,1]
	v_pk_fma_f32 v[12:13], v[20:21], v[12:13], v[22:23]
	v_pk_add_f32 v[20:21], v[24:25], v[24:25] op_sel:[0,1] op_sel_hi:[0,1] neg_lo:[0,1] neg_hi:[0,1]
	v_mov_b32_e32 v27, v13
	v_pk_add_f32 v[12:13], v[10:11], v[10:11] op_sel:[0,1] op_sel_hi:[0,1]
	v_pk_mul_f32 v[20:21], v[20:21], v[6:7] op_sel:[0,1] op_sel_hi:[1,0]
	s_nop 0
	v_pk_fma_f32 v[22:23], v[12:13], v[6:7], v[20:21] neg_lo:[0,0,1] neg_hi:[0,0,1]
	v_pk_fma_f32 v[6:7], v[12:13], v[6:7], v[20:21]
	v_pk_add_f32 v[20:21], v[28:29], v[28:29] op_sel:[0,1] op_sel_hi:[0,1] neg_lo:[0,1] neg_hi:[0,1]
	v_mov_b32_e32 v23, v7
	v_cvt_f32_f16_e32 v6, v8
	v_cvt_f32_f16_sdwa v7, v8 dst_sel:DWORD dst_unused:UNUSED_PAD src0_sel:WORD_1
	v_pk_add_f32 v[12:13], v[30:31], v[30:31] op_sel:[0,1] op_sel_hi:[0,1] neg_lo:[0,1] neg_hi:[0,1]
	v_pk_mul_f32 v[20:21], v[20:21], v[6:7] op_sel:[0,1] op_sel_hi:[1,0]
	s_nop 0
	v_pk_fma_f32 v[28:29], v[12:13], v[6:7], v[20:21] neg_lo:[0,0,1] neg_hi:[0,0,1]
	v_pk_fma_f32 v[6:7], v[12:13], v[6:7], v[20:21]
	s_nop 0
	v_mov_b32_e32 v29, v7
	v_cvt_f32_f16_e32 v6, v9
	v_cvt_f32_f16_sdwa v7, v9 dst_sel:DWORD dst_unused:UNUSED_PAD src0_sel:WORD_1
	v_pk_add_f32 v[8:9], v[10:11], v[10:11] op_sel:[0,1] op_sel_hi:[0,1] neg_lo:[0,1] neg_hi:[0,1]
	v_pk_add_f32 v[10:11], v[24:25], v[24:25] op_sel:[0,1] op_sel_hi:[0,1]
	v_pk_mul_f32 v[10:11], v[10:11], v[6:7] op_sel:[0,1] op_sel_hi:[1,0]
	s_nop 0
	v_pk_fma_f32 v[12:13], v[8:9], v[6:7], v[10:11] neg_lo:[0,0,1] neg_hi:[0,0,1]
	v_pk_fma_f32 v[6:7], v[8:9], v[6:7], v[10:11]
	v_pk_add_f32 v[8:9], v[26:27], v[28:29]
	v_mov_b32_e32 v13, v7
	v_pk_add_f32 v[10:11], v[22:23], v[12:13]
	v_pk_add_f32 v[12:13], v[22:23], v[12:13] neg_lo:[0,1] neg_hi:[0,1]
	v_pk_add_f32 v[6:7], v[8:9], v[10:11]
	v_pk_add_f32 v[10:11], v[8:9], v[10:11] neg_lo:[0,1] neg_hi:[0,1]
	v_pk_add_f32 v[8:9], v[26:27], v[28:29] neg_lo:[0,1] neg_hi:[0,1]
	s_nop 0
	v_pk_add_f32 v[20:21], v[8:9], v[12:13] op_sel:[0,1] op_sel_hi:[1,0] neg_lo:[0,1] neg_hi:[0,1]
	v_pk_add_f32 v[12:13], v[8:9], v[12:13] op_sel:[0,1] op_sel_hi:[1,0]
	v_mov_b32_e32 v8, v20
	v_mov_b32_e32 v9, v13
	v_mov_b32_e32 v13, v21
	ds_write_b128 v4, v[6:9] offset:49152
	ds_write_b128 v4, v[10:13] offset:49168
	s_cbranch_scc1 .LBB0_1335
	v_lshlrev_b32_e32 v232, 4, v154
	s_lshl_b32 s100, s90, 15
	v_add_u32_e32 v233, 0x2000, v232
	v_add_u32_e32 v234, 0x4000, v232
	v_add_u32_e32 v235, 0x6000, v232
	s_add_u32 s98, s70, 0x42bd000
	s_addc_u32 s99, s71, 0
	s_add_u32 s98, s98, s100
	s_addc_u32 s99, s99, 0
	s_cmp_eq_u32 s89, 1
	s_cbranch_scc1 .Lmy_pf_st1
	s_add_u32 s98, s98, 0x2000000
	s_addc_u32 s99, s99, 0
.Lmy_pf_st1:
	global_load_dwordx4 v[228:231], v232, s[98:99]
	global_load_dwordx4 v[228:231], v233, s[98:99]
	global_load_dwordx4 v[228:231], v234, s[98:99]
	global_load_dwordx4 v[228:231], v235, s[98:99]
	s_add_u32 s98, s98, 0x1000000
	s_addc_u32 s99, s99, 0
	global_load_dwordx4 v[228:231], v232, s[98:99]
	global_load_dwordx4 v[228:231], v233, s[98:99]
	global_load_dwordx4 v[228:231], v234, s[98:99]
	global_load_dwordx4 v[228:231], v235, s[98:99]
	s_waitcnt lgkmcnt(0)
	v_mov_b32_e32 v12, s91
	ds_read_b64 v[0:1], v219
	ds_read_b64 v[2:3], v12
	s_mov_b64 s[12:13], -1
	s_and_b64 vcc, exec, s[50:51]
	s_waitcnt lgkmcnt(0)
	v_pk_mul_f32 v[4:5], v[0:1], v[2:3]
	v_pk_mul_f32 v[2:3], v[0:1], v[2:3] op_sel:[1,0] op_sel_hi:[0,1]
	v_mov_b32_e32 v6, v4
	v_mov_b32_e32 v7, v2
	v_mov_b32_e32 v2, v5
	v_pk_add_f32 v[0:1], v[6:7], v[2:3] neg_lo:[0,1] neg_hi:[0,1]
	v_pk_add_f32 v[4:5], v[6:7], v[2:3]
	v_mov_b32_e32 v8, v0
	v_mov_b32_e32 v9, v5
	v_mul_f32_e32 v2, v5, v5
	v_pk_mul_f32 v[6:7], v[8:9], v[4:5] op_sel:[0,1] op_sel_hi:[1,0]
	v_pk_fma_f32 v[2:3], v[8:9], v[8:9], v[2:3] op_sel_hi:[1,1,0] neg_lo:[0,0,1] neg_hi:[0,0,1]
	v_pk_add_f32 v[6:7], v[6:7], v[6:7]
	v_mov_b32_e32 v10, v2
	v_mov_b32_e32 v11, v6
	v_pk_mul_f32 v[8:9], v[8:9], v[10:11]
	v_pk_mov_b32 v[10:11], v[4:5], v[6:7] op_sel:[1,0]
	v_mov_b32_e32 v20, v2
	v_mov_b32_e32 v21, v0
	v_pk_mul_f32 v[10:11], v[10:11], v[20:21]
	ds_read2_b64 v[20:23], v186 offset1:4
	ds_read2_b64 v[24:27], v186 offset0:8 offset1:12
	v_pk_add_f32 v[10:11], v[10:11], v[10:11] op_sel:[0,1] op_sel_hi:[0,1]
	v_pk_add_f32 v[8:9], v[8:9], v[8:9] op_sel:[0,1] op_sel_hi:[0,1] neg_lo:[0,1] neg_hi:[0,1]
	s_waitcnt lgkmcnt(1)
	v_pk_mul_f32 v[28:29], v[4:5], v[22:23] op_sel:[1,0]
	s_nop 0
	v_pk_fma_f32 v[30:31], v[0:1], v[22:23], v[28:29] op_sel:[0,0,1] op_sel_hi:[1,1,0]
	v_pk_fma_f32 v[22:23], v[0:1], v[22:23], v[28:29] op_sel:[0,0,1] op_sel_hi:[0,1,0] neg_lo:[0,0,1] neg_hi:[0,0,1]
	v_mov_b32_e32 v31, v23
	s_waitcnt lgkmcnt(0)
; HD float2 cmul(float2 a, float2 b){ return make_float2(a.x*b.x - a.y*b.y, a.x*b.y + a.y*b.x); }
; HD float2 cmulc(float2 a, float2 b){ return make_float2(a.x*b.x + a.y*b.y, a.y*b.x - a.x*b.y); }
; template<bool INV, bool NOTW>
; HD void bf4c(float2* Z, int i0, int i1, int i2, int i3, float2 w1, float2 w2, float2 w3){
;   float2 a0=Z[i0], a1=Z[i1], a2=Z[i2], a3=Z[i3];
;   if (INV && !NOTW){ a1=cmulc(a1,w1); a2=cmulc(a2,w2); a3=cmulc(a3,w3); }
;   float2 s02=make_float2(a0.x+a2.x,a0.y+a2.y), d02=make_float2(a0.x-a2.x,a0.y-a2.y);
;   float2 s13=make_float2(a1.x+a3.x,a1.y+a3.y), d13=make_float2(a1.x-a3.x,a1.y-a3.y);
;   float2 y0=make_float2(s02.x+s13.x,s02.y+s13.y), y2=make_float2(s02.x-s13.x,s02.y-s13.y);
;   float2 ym=make_float2(d02.x+d13.y,d02.y-d13.x);
;   float2 yp=make_float2(d02.x-d13.y,d02.y+d13.x);
;   float2 y1, y3;
;   if (INV){ y1=yp; y3=ym; } else if (NOTW){ y1=ym; y3=yp; } else { y1=cmul(ym,w1); y2=cmul(y2,w2); y3=cmul(yp,w3); }
;   Z[i0]=y0; Z[i1]=y1; Z[i2]=y2; Z[i3]=y3;
; }
; template<bool INV, int LQ, bool BARRIER=true>
; HD void fft_pass(float2* Z, const float2* twA, const float2* twB, int tid){
;     ...
;     int j=tid&(q-1); int base0=((tid>>LQ)<<(LQ+2))+j;
;     float2 w1=make_float2(1.f,0.f), w2=w1, w3=w1;
;     if (LQ>0){ int k=j*tws; w1=cmul(twA[k>>6],twB[k&63]); w2=cmul(w1,w1); w3=cmul(w2,w1); }
;     _Pragma("unroll") for (int i=0;i<8;++i){ int base=base0+i*2048; bf4c<INV,(LQ==0)>(Z,base,base+q,base+2*q,base+3*q,w1,w2,w3); }
	v_pk_mul_f32 v[22:23], v[6:7], v[24:25] op_sel_hi:[0,1]
	v_pk_fma_f32 v[28:29], v[2:3], v[24:25], v[22:23] op_sel:[0,0,1] op_sel_hi:[1,1,0]
	v_pk_fma_f32 v[22:23], v[2:3], v[24:25], v[22:23] op_sel:[0,0,1] op_sel_hi:[0,1,0] neg_lo:[0,0,1] neg_hi:[0,0,1]
	v_mov_b32_e32 v29, v23
	v_pk_mul_f32 v[22:23], v[10:11], v[26:27]
	s_nop 0
	v_pk_fma_f32 v[24:25], v[8:9], v[26:27], v[22:23] op_sel:[0,0,1] op_sel_hi:[1,1,0]
	v_pk_fma_f32 v[22:23], v[8:9], v[26:27], v[22:23] op_sel:[0,0,1] op_sel_hi:[1,1,0] neg_lo:[0,0,1] neg_hi:[0,0,1]
	s_nop 0
	v_mov_b32_e32 v25, v23
	v_pk_add_f32 v[22:23], v[20:21], v[28:29]
	v_pk_add_f32 v[26:27], v[30:31], v[24:25]
	v_pk_add_f32 v[20:21], v[20:21], v[28:29] neg_lo:[0,1] neg_hi:[0,1]
	v_pk_add_f32 v[24:25], v[30:31], v[24:25] neg_lo:[0,1] neg_hi:[0,1]
	v_pk_add_f32 v[80:81], v[22:23], v[26:27]
	v_pk_add_f32 v[28:29], v[20:21], v[24:25] op_sel:[0,1] op_sel_hi:[1,0]
	v_pk_add_f32 v[20:21], v[20:21], v[24:25] op_sel:[0,1] op_sel_hi:[1,0] neg_lo:[0,1] neg_hi:[0,1]
	v_mov_b32_e32 v24, v28
	v_mov_b32_e32 v25, v21
	v_mov_b32_e32 v21, v29
	ds_write2_b64 v186, v[80:81], v[20:21] offset1:4
	v_pk_add_f32 v[20:21], v[22:23], v[26:27] neg_lo:[0,1] neg_hi:[0,1]
	ds_write2_b64 v186, v[20:21], v[24:25] offset0:8 offset1:12
	ds_read2_b64 v[20:23], v17 offset1:4
	ds_read2_b64 v[24:27], v17 offset0:8 offset1:12
	s_waitcnt lgkmcnt(1)
	v_pk_mul_f32 v[28:29], v[4:5], v[22:23] op_sel:[1,0]
	s_nop 0
	v_pk_fma_f32 v[30:31], v[0:1], v[22:23], v[28:29] op_sel:[0,0,1] op_sel_hi:[1,1,0]
	v_pk_fma_f32 v[22:23], v[0:1], v[22:23], v[28:29] op_sel:[0,0,1] op_sel_hi:[0,1,0] neg_lo:[0,0,1] neg_hi:[0,0,1]
	v_mov_b32_e32 v31, v23
	s_waitcnt lgkmcnt(0)
	v_pk_mul_f32 v[22:23], v[6:7], v[24:25] op_sel_hi:[0,1]
	v_pk_fma_f32 v[28:29], v[2:3], v[24:25], v[22:23] op_sel:[0,0,1] op_sel_hi:[1,1,0]
	v_pk_fma_f32 v[22:23], v[2:3], v[24:25], v[22:23] op_sel:[0,0,1] op_sel_hi:[0,1,0] neg_lo:[0,0,1] neg_hi:[0,0,1]
	v_mov_b32_e32 v29, v23
	v_pk_mul_f32 v[22:23], v[10:11], v[26:27]
	s_nop 0
	v_pk_fma_f32 v[24:25], v[8:9], v[26:27], v[22:23] op_sel:[0,0,1] op_sel_hi:[1,1,0]
	v_pk_fma_f32 v[22:23], v[8:9], v[26:27], v[22:23] op_sel:[0,0,1] op_sel_hi:[1,1,0] neg_lo:[0,0,1] neg_hi:[0,0,1]
	s_nop 0
	v_mov_b32_e32 v25, v23
	v_pk_add_f32 v[22:23], v[20:21], v[28:29]
	v_pk_add_f32 v[26:27], v[30:31], v[24:25]
	v_pk_add_f32 v[20:21], v[20:21], v[28:29] neg_lo:[0,1] neg_hi:[0,1]
	v_pk_add_f32 v[24:25], v[30:31], v[24:25] neg_lo:[0,1] neg_hi:[0,1]
	v_pk_add_f32 v[80:81], v[22:23], v[26:27]
	v_pk_add_f32 v[28:29], v[20:21], v[24:25] op_sel:[0,1] op_sel_hi:[1,0]
	v_pk_add_f32 v[20:21], v[20:21], v[24:25] op_sel:[0,1] op_sel_hi:[1,0] neg_lo:[0,1] neg_hi:[0,1]
	v_mov_b32_e32 v24, v28
	v_mov_b32_e32 v25, v21
	v_mov_b32_e32 v21, v29
	ds_write2_b64 v17, v[80:81], v[20:21] offset1:4
	v_pk_add_f32 v[20:21], v[22:23], v[26:27] neg_lo:[0,1] neg_hi:[0,1]
	ds_write2_b64 v17, v[20:21], v[24:25] offset0:8 offset1:12
	ds_read2_b64 v[20:23], v18 offset1:4
	ds_read2_b64 v[24:27], v18 offset0:8 offset1:12
	s_waitcnt lgkmcnt(1)
	v_pk_mul_f32 v[28:29], v[4:5], v[22:23] op_sel:[1,0]
	s_nop 0
	v_pk_fma_f32 v[30:31], v[0:1], v[22:23], v[28:29] op_sel:[0,0,1] op_sel_hi:[1,1,0]
	v_pk_fma_f32 v[22:23], v[0:1], v[22:23], v[28:29] op_sel:[0,0,1] op_sel_hi:[0,1,0] neg_lo:[0,0,1] neg_hi:[0,0,1]
	v_mov_b32_e32 v31, v23
	s_waitcnt lgkmcnt(0)
	v_pk_mul_f32 v[22:23], v[6:7], v[24:25] op_sel_hi:[0,1]
	v_pk_fma_f32 v[28:29], v[2:3], v[24:25], v[22:23] op_sel:[0,0,1] op_sel_hi:[1,1,0]
	v_pk_fma_f32 v[22:23], v[2:3], v[24:25], v[22:23] op_sel:[0,0,1] op_sel_hi:[0,1,0] neg_lo:[0,0,1] neg_hi:[0,0,1]
	v_mov_b32_e32 v29, v23
	v_pk_mul_f32 v[22:23], v[10:11], v[26:27]
	s_nop 0
	v_pk_fma_f32 v[24:25], v[8:9], v[26:27], v[22:23] op_sel:[0,0,1] op_sel_hi:[1,1,0]
	v_pk_fma_f32 v[22:23], v[8:9], v[26:27], v[22:23] op_sel:[0,0,1] op_sel_hi:[1,1,0] neg_lo:[0,0,1] neg_hi:[0,0,1]
	s_nop 0
	v_mov_b32_e32 v25, v23
	v_pk_add_f32 v[22:23], v[20:21], v[28:29]
	v_pk_add_f32 v[26:27], v[30:31], v[24:25]
	v_pk_add_f32 v[20:21], v[20:21], v[28:29] neg_lo:[0,1] neg_hi:[0,1]
	v_pk_add_f32 v[24:25], v[30:31], v[24:25] neg_lo:[0,1] neg_hi:[0,1]
	v_pk_add_f32 v[80:81], v[22:23], v[26:27]
	v_pk_add_f32 v[28:29], v[20:21], v[24:25] op_sel:[0,1] op_sel_hi:[1,0]
	v_pk_add_f32 v[20:21], v[20:21], v[24:25] op_sel:[0,1] op_sel_hi:[1,0] neg_lo:[0,1] neg_hi:[0,1]
	v_mov_b32_e32 v24, v28
	v_mov_b32_e32 v25, v21
	v_mov_b32_e32 v21, v29
	ds_write2_b64 v18, v[80:81], v[20:21] offset1:4
	v_pk_add_f32 v[20:21], v[22:23], v[26:27] neg_lo:[0,1] neg_hi:[0,1]
	ds_write2_b64 v18, v[20:21], v[24:25] offset0:8 offset1:12
	ds_read2_b64 v[20:23], v19 offset1:4
	ds_read2_b64 v[24:27], v19 offset0:8 offset1:12
	s_waitcnt lgkmcnt(1)
	v_pk_mul_f32 v[28:29], v[4:5], v[22:23] op_sel:[1,0]
	s_nop 0
	v_pk_fma_f32 v[30:31], v[0:1], v[22:23], v[28:29] op_sel:[0,0,1] op_sel_hi:[1,1,0]
	v_pk_fma_f32 v[22:23], v[0:1], v[22:23], v[28:29] op_sel:[0,0,1] op_sel_hi:[0,1,0] neg_lo:[0,0,1] neg_hi:[0,0,1]
	v_mov_b32_e32 v31, v23
	s_waitcnt lgkmcnt(0)
; HD float2 cmul(float2 a, float2 b){ return make_float2(a.x*b.x - a.y*b.y, a.x*b.y + a.y*b.x); }
; HD float2 cmulc(float2 a, float2 b){ return make_float2(a.x*b.x + a.y*b.y, a.y*b.x - a.x*b.y); }
; template<bool INV, bool NOTW>
; HD void bf4c(float2* Z, int i0, int i1, int i2, int i3, float2 w1, float2 w2, float2 w3){
;   float2 a0=Z[i0], a1=Z[i1], a2=Z[i2], a3=Z[i3];
;   if (INV && !NOTW){ a1=cmulc(a1,w1); a2=cmulc(a2,w2); a3=cmulc(a3,w3); }
;   float2 s02=make_float2(a0.x+a2.x,a0.y+a2.y), d02=make_float2(a0.x-a2.x,a0.y-a2.y);
;   float2 s13=make_float2(a1.x+a3.x,a1.y+a3.y), d13=make_float2(a1.x-a3.x,a1.y-a3.y);
;   float2 y0=make_float2(s02.x+s13.x,s02.y+s13.y), y2=make_float2(s02.x-s13.x,s02.y-s13.y);
;   float2 ym=make_float2(d02.x+d13.y,d02.y-d13.x);
;   float2 yp=make_float2(d02.x-d13.y,d02.y+d13.x);
;   float2 y1, y3;
;   if (INV){ y1=yp; y3=ym; } else if (NOTW){ y1=ym; y3=yp; } else { y1=cmul(ym,w1); y2=cmul(y2,w2); y3=cmul(yp,w3); }
;   Z[i0]=y0; Z[i1]=y1; Z[i2]=y2; Z[i3]=y3;
; }
; template<bool INV, int LQ, bool BARRIER=true>
; HD void fft_pass(float2* Z, const float2* twA, const float2* twB, int tid){
;     ...
;     int j=tid&(q-1); int base0=((tid>>LQ)<<(LQ+2))+j;
;     float2 w1=make_float2(1.f,0.f), w2=w1, w3=w1;
;     if (LQ>0){ int k=j*tws; w1=cmul(twA[k>>6],twB[k&63]); w2=cmul(w1,w1); w3=cmul(w2,w1); }
;     _Pragma("unroll") for (int i=0;i<8;++i){ int base=base0+i*2048; bf4c<INV,(LQ==0)>(Z,base,base+q,base+2*q,base+3*q,w1,w2,w3); }
	v_pk_mul_f32 v[22:23], v[6:7], v[24:25] op_sel_hi:[0,1]
	v_pk_fma_f32 v[28:29], v[2:3], v[24:25], v[22:23] op_sel:[0,0,1] op_sel_hi:[1,1,0]
	v_pk_fma_f32 v[22:23], v[2:3], v[24:25], v[22:23] op_sel:[0,0,1] op_sel_hi:[0,1,0] neg_lo:[0,0,1] neg_hi:[0,0,1]
	v_mov_b32_e32 v29, v23
	v_pk_mul_f32 v[22:23], v[10:11], v[26:27]
	s_nop 0
	v_pk_fma_f32 v[24:25], v[8:9], v[26:27], v[22:23] op_sel:[0,0,1] op_sel_hi:[1,1,0]
	v_pk_fma_f32 v[22:23], v[8:9], v[26:27], v[22:23] op_sel:[0,0,1] op_sel_hi:[1,1,0] neg_lo:[0,0,1] neg_hi:[0,0,1]
	s_nop 0
	v_mov_b32_e32 v25, v23
	v_pk_add_f32 v[22:23], v[20:21], v[28:29]
	v_pk_add_f32 v[26:27], v[30:31], v[24:25]
	v_pk_add_f32 v[20:21], v[20:21], v[28:29] neg_lo:[0,1] neg_hi:[0,1]
	v_pk_add_f32 v[24:25], v[30:31], v[24:25] neg_lo:[0,1] neg_hi:[0,1]
	v_pk_add_f32 v[80:81], v[22:23], v[26:27]
	v_pk_add_f32 v[28:29], v[20:21], v[24:25] op_sel:[0,1] op_sel_hi:[1,0]
	v_pk_add_f32 v[20:21], v[20:21], v[24:25] op_sel:[0,1] op_sel_hi:[1,0] neg_lo:[0,1] neg_hi:[0,1]
	v_mov_b32_e32 v24, v28
	v_mov_b32_e32 v25, v21
	v_mov_b32_e32 v21, v29
	ds_write2_b64 v19, v[80:81], v[20:21] offset1:4
	v_pk_add_f32 v[20:21], v[22:23], v[26:27] neg_lo:[0,1] neg_hi:[0,1]
	ds_write2_b64 v19, v[20:21], v[24:25] offset0:8 offset1:12
	ds_read_b64 v[18:19], v187
	ds_read_b64 v[20:21], v188
	ds_read_b64 v[22:23], v189
	ds_read_b64 v[24:25], v190
	s_waitcnt lgkmcnt(2)
	v_pk_mul_f32 v[26:27], v[4:5], v[20:21] op_sel:[1,0]
	s_nop 0
	v_pk_fma_f32 v[28:29], v[0:1], v[20:21], v[26:27] op_sel:[0,0,1] op_sel_hi:[1,1,0]
	v_pk_fma_f32 v[20:21], v[0:1], v[20:21], v[26:27] op_sel:[0,0,1] op_sel_hi:[0,1,0] neg_lo:[0,0,1] neg_hi:[0,0,1]
	v_mov_b32_e32 v29, v21
	s_waitcnt lgkmcnt(1)
	v_pk_mul_f32 v[20:21], v[6:7], v[22:23] op_sel_hi:[0,1]
	v_pk_fma_f32 v[26:27], v[2:3], v[22:23], v[20:21] op_sel:[0,0,1] op_sel_hi:[1,1,0]
	v_pk_fma_f32 v[20:21], v[2:3], v[22:23], v[20:21] op_sel:[0,0,1] op_sel_hi:[0,1,0] neg_lo:[0,0,1] neg_hi:[0,0,1]
	v_mov_b32_e32 v27, v21
	s_waitcnt lgkmcnt(0)
	v_pk_mul_f32 v[20:21], v[10:11], v[24:25]
	s_nop 0
	v_pk_fma_f32 v[22:23], v[8:9], v[24:25], v[20:21] op_sel:[0,0,1] op_sel_hi:[1,1,0]
	v_pk_fma_f32 v[20:21], v[8:9], v[24:25], v[20:21] op_sel:[0,0,1] op_sel_hi:[1,1,0] neg_lo:[0,0,1] neg_hi:[0,0,1]
	s_nop 0
	v_mov_b32_e32 v23, v21
	v_pk_add_f32 v[20:21], v[18:19], v[26:27]
	v_pk_add_f32 v[24:25], v[28:29], v[22:23]
	v_pk_add_f32 v[18:19], v[18:19], v[26:27] neg_lo:[0,1] neg_hi:[0,1]
	v_pk_add_f32 v[22:23], v[28:29], v[22:23] neg_lo:[0,1] neg_hi:[0,1]
	v_pk_add_f32 v[30:31], v[20:21], v[24:25]
	v_pk_add_f32 v[26:27], v[18:19], v[22:23] op_sel:[0,1] op_sel_hi:[1,0]
	v_pk_add_f32 v[18:19], v[18:19], v[22:23] op_sel:[0,1] op_sel_hi:[1,0] neg_lo:[0,1] neg_hi:[0,1]
	v_mov_b32_e32 v22, v26
	v_mov_b32_e32 v23, v19
	v_mov_b32_e32 v19, v27
	ds_write_b64 v187, v[30:31]
	ds_write_b64 v188, v[18:19]
	v_pk_add_f32 v[18:19], v[20:21], v[24:25] neg_lo:[0,1] neg_hi:[0,1]
	ds_write_b64 v189, v[18:19]
	ds_write_b64 v190, v[22:23]
	ds_read_b64 v[18:19], v191
	ds_read_b64 v[20:21], v192
	ds_read_b64 v[22:23], v193
	ds_read_b64 v[24:25], v194
	s_waitcnt lgkmcnt(2)
	v_pk_mul_f32 v[26:27], v[4:5], v[20:21] op_sel:[1,0]
	s_nop 0
	v_pk_fma_f32 v[28:29], v[0:1], v[20:21], v[26:27] op_sel:[0,0,1] op_sel_hi:[1,1,0]
	v_pk_fma_f32 v[20:21], v[0:1], v[20:21], v[26:27] op_sel:[0,0,1] op_sel_hi:[0,1,0] neg_lo:[0,0,1] neg_hi:[0,0,1]
	v_mov_b32_e32 v29, v21
	s_waitcnt lgkmcnt(1)
	v_pk_mul_f32 v[20:21], v[6:7], v[22:23] op_sel_hi:[0,1]
	v_pk_fma_f32 v[26:27], v[2:3], v[22:23], v[20:21] op_sel:[0,0,1] op_sel_hi:[1,1,0]
	v_pk_fma_f32 v[20:21], v[2:3], v[22:23], v[20:21] op_sel:[0,0,1] op_sel_hi:[0,1,0] neg_lo:[0,0,1] neg_hi:[0,0,1]
	v_mov_b32_e32 v27, v21
	s_waitcnt lgkmcnt(0)
	v_pk_mul_f32 v[20:21], v[10:11], v[24:25]
	s_nop 0
	v_pk_fma_f32 v[22:23], v[8:9], v[24:25], v[20:21] op_sel:[0,0,1] op_sel_hi:[1,1,0]
	v_pk_fma_f32 v[20:21], v[8:9], v[24:25], v[20:21] op_sel:[0,0,1] op_sel_hi:[1,1,0] neg_lo:[0,0,1] neg_hi:[0,0,1]
	s_nop 0
	v_mov_b32_e32 v23, v21
	v_pk_add_f32 v[20:21], v[18:19], v[26:27]
	v_pk_add_f32 v[24:25], v[28:29], v[22:23]
	v_pk_add_f32 v[18:19], v[18:19], v[26:27] neg_lo:[0,1] neg_hi:[0,1]
	v_pk_add_f32 v[22:23], v[28:29], v[22:23] neg_lo:[0,1] neg_hi:[0,1]
	v_pk_add_f32 v[30:31], v[20:21], v[24:25]
	v_pk_add_f32 v[26:27], v[18:19], v[22:23] op_sel:[0,1] op_sel_hi:[1,0]
	v_pk_add_f32 v[18:19], v[18:19], v[22:23] op_sel:[0,1] op_sel_hi:[1,0] neg_lo:[0,1] neg_hi:[0,1]
	v_mov_b32_e32 v22, v26
	v_mov_b32_e32 v23, v19
	v_mov_b32_e32 v19, v27
	ds_write_b64 v191, v[30:31]
	ds_write_b64 v192, v[18:19]
	v_pk_add_f32 v[18:19], v[20:21], v[24:25] neg_lo:[0,1] neg_hi:[0,1]
	ds_write_b64 v193, v[18:19]
	ds_write_b64 v194, v[22:23]
	ds_read_b64 v[18:19], v195
	ds_read_b64 v[20:21], v196
	ds_read_b64 v[22:23], v197
	ds_read_b64 v[24:25], v198
	s_waitcnt lgkmcnt(2)
	v_pk_mul_f32 v[26:27], v[4:5], v[20:21] op_sel:[1,0]
	s_nop 0
	v_pk_fma_f32 v[28:29], v[0:1], v[20:21], v[26:27] op_sel:[0,0,1] op_sel_hi:[1,1,0]
	v_pk_fma_f32 v[20:21], v[0:1], v[20:21], v[26:27] op_sel:[0,0,1] op_sel_hi:[0,1,0] neg_lo:[0,0,1] neg_hi:[0,0,1]
	v_mov_b32_e32 v29, v21
	s_waitcnt lgkmcnt(1)
	v_pk_mul_f32 v[20:21], v[6:7], v[22:23] op_sel_hi:[0,1]
	v_pk_fma_f32 v[26:27], v[2:3], v[22:23], v[20:21] op_sel:[0,0,1] op_sel_hi:[1,1,0]
	v_pk_fma_f32 v[20:21], v[2:3], v[22:23], v[20:21] op_sel:[0,0,1] op_sel_hi:[0,1,0] neg_lo:[0,0,1] neg_hi:[0,0,1]
	v_mov_b32_e32 v27, v21
	s_waitcnt lgkmcnt(0)
; HD float2 cmul(float2 a, float2 b){ return make_float2(a.x*b.x - a.y*b.y, a.x*b.y + a.y*b.x); }
; HD float2 cmulc(float2 a, float2 b){ return make_float2(a.x*b.x + a.y*b.y, a.y*b.x - a.x*b.y); }
; template<bool INV, bool NOTW>
; HD void bf4c(float2* Z, int i0, int i1, int i2, int i3, float2 w1, float2 w2, float2 w3){
;   float2 a0=Z[i0], a1=Z[i1], a2=Z[i2], a3=Z[i3];
;   if (INV && !NOTW){ a1=cmulc(a1,w1); a2=cmulc(a2,w2); a3=cmulc(a3,w3); }
;   float2 s02=make_float2(a0.x+a2.x,a0.y+a2.y), d02=make_float2(a0.x-a2.x,a0.y-a2.y);
;   float2 s13=make_float2(a1.x+a3.x,a1.y+a3.y), d13=make_float2(a1.x-a3.x,a1.y-a3.y);
;   float2 y0=make_float2(s02.x+s13.x,s02.y+s13.y), y2=make_float2(s02.x-s13.x,s02.y-s13.y);
;   float2 ym=make_float2(d02.x+d13.y,d02.y-d13.x);
;   float2 yp=make_float2(d02.x-d13.y,d02.y+d13.x);
;   float2 y1, y3;
;   if (INV){ y1=yp; y3=ym; } else if (NOTW){ y1=ym; y3=yp; } else { y1=cmul(ym,w1); y2=cmul(y2,w2); y3=cmul(yp,w3); }
;   Z[i0]=y0; Z[i1]=y1; Z[i2]=y2; Z[i3]=y3;
; }
; template<bool INV, int LQ, bool BARRIER=true>
; HD void fft_pass(float2* Z, const float2* twA, const float2* twB, int tid){
;     ...
;     int j=tid&(q-1); int base0=((tid>>LQ)<<(LQ+2))+j;
;     float2 w1=make_float2(1.f,0.f), w2=w1, w3=w1;
;     if (LQ>0){ int k=j*tws; w1=cmul(twA[k>>6],twB[k&63]); w2=cmul(w1,w1); w3=cmul(w2,w1); }
;     _Pragma("unroll") for (int i=0;i<8;++i){ int base=base0+i*2048; bf4c<INV,(LQ==0)>(Z,base,base+q,base+2*q,base+3*q,w1,w2,w3); }
	v_pk_mul_f32 v[20:21], v[10:11], v[24:25]
	s_nop 0
	v_pk_fma_f32 v[22:23], v[8:9], v[24:25], v[20:21] op_sel:[0,0,1] op_sel_hi:[1,1,0]
	v_pk_fma_f32 v[20:21], v[8:9], v[24:25], v[20:21] op_sel:[0,0,1] op_sel_hi:[1,1,0] neg_lo:[0,0,1] neg_hi:[0,0,1]
	s_nop 0
	v_mov_b32_e32 v23, v21
	v_pk_add_f32 v[20:21], v[18:19], v[26:27]
	v_pk_add_f32 v[24:25], v[28:29], v[22:23]
	v_pk_add_f32 v[18:19], v[18:19], v[26:27] neg_lo:[0,1] neg_hi:[0,1]
	v_pk_add_f32 v[22:23], v[28:29], v[22:23] neg_lo:[0,1] neg_hi:[0,1]
	v_pk_add_f32 v[30:31], v[20:21], v[24:25]
	v_pk_add_f32 v[26:27], v[18:19], v[22:23] op_sel:[0,1] op_sel_hi:[1,0]
	v_pk_add_f32 v[18:19], v[18:19], v[22:23] op_sel:[0,1] op_sel_hi:[1,0] neg_lo:[0,1] neg_hi:[0,1]
	v_mov_b32_e32 v22, v26
	v_mov_b32_e32 v23, v19
	v_mov_b32_e32 v19, v27
	ds_write_b64 v195, v[30:31]
	ds_write_b64 v196, v[18:19]
	v_pk_add_f32 v[18:19], v[20:21], v[24:25] neg_lo:[0,1] neg_hi:[0,1]
	ds_write_b64 v197, v[18:19]
	ds_write_b64 v198, v[22:23]
	ds_read_b64 v[18:19], v199
	ds_read_b64 v[20:21], v200
	ds_read_b64 v[22:23], v201
	ds_read_b64 v[24:25], v202
	s_waitcnt lgkmcnt(2)
	v_pk_mul_f32 v[4:5], v[4:5], v[20:21] op_sel:[1,0]
	s_nop 0
	v_pk_fma_f32 v[26:27], v[0:1], v[20:21], v[4:5] op_sel:[0,0,1] op_sel_hi:[1,1,0]
	v_pk_fma_f32 v[0:1], v[0:1], v[20:21], v[4:5] op_sel:[0,0,1] op_sel_hi:[0,1,0] neg_lo:[0,0,1] neg_hi:[0,0,1]
	v_mov_b32_e32 v27, v1
	s_waitcnt lgkmcnt(1)
	v_pk_mul_f32 v[0:1], v[6:7], v[22:23] op_sel_hi:[0,1]
	v_pk_fma_f32 v[4:5], v[2:3], v[22:23], v[0:1] op_sel:[0,0,1] op_sel_hi:[1,1,0]
	v_pk_fma_f32 v[0:1], v[2:3], v[22:23], v[0:1] op_sel:[0,0,1] op_sel_hi:[0,1,0] neg_lo:[0,0,1] neg_hi:[0,0,1]
	v_mov_b32_e32 v5, v1
	s_waitcnt lgkmcnt(0)
	v_pk_mul_f32 v[0:1], v[10:11], v[24:25]
	s_nop 0
	v_pk_fma_f32 v[2:3], v[8:9], v[24:25], v[0:1] op_sel:[0,0,1] op_sel_hi:[1,1,0]
	v_pk_fma_f32 v[0:1], v[8:9], v[24:25], v[0:1] op_sel:[0,0,1] op_sel_hi:[1,1,0] neg_lo:[0,0,1] neg_hi:[0,0,1]
	s_nop 0
	v_mov_b32_e32 v3, v1
	v_pk_add_f32 v[0:1], v[18:19], v[4:5]
	v_pk_add_f32 v[6:7], v[26:27], v[2:3]
	v_pk_add_f32 v[4:5], v[18:19], v[4:5] neg_lo:[0,1] neg_hi:[0,1]
	v_pk_add_f32 v[2:3], v[26:27], v[2:3] neg_lo:[0,1] neg_hi:[0,1]
	v_pk_add_f32 v[8:9], v[0:1], v[6:7]
	v_pk_add_f32 v[10:11], v[4:5], v[2:3] op_sel:[0,1] op_sel_hi:[1,0]
	v_pk_add_f32 v[2:3], v[4:5], v[2:3] op_sel:[0,1] op_sel_hi:[1,0] neg_lo:[0,1] neg_hi:[0,1]
	v_pk_add_f32 v[0:1], v[0:1], v[6:7] neg_lo:[0,1] neg_hi:[0,1]
	v_mov_b32_e32 v4, v10
	v_mov_b32_e32 v5, v3
	v_mov_b32_e32 v3, v11
	ds_write_b64 v199, v[8:9]
	ds_write_b64 v200, v[2:3]
	ds_write_b64 v201, v[0:1]
	ds_write_b64 v202, v[4:5]
	s_waitcnt lgkmcnt(0)
	ds_read_b64 v[0:1], v218
	ds_read_b64 v[2:3], v12
	s_waitcnt lgkmcnt(0)
	v_pk_mul_f32 v[4:5], v[0:1], v[2:3]
	v_pk_mul_f32 v[2:3], v[0:1], v[2:3] op_sel:[1,0] op_sel_hi:[0,1]
	v_mov_b32_e32 v6, v4
	v_mov_b32_e32 v7, v2
	v_mov_b32_e32 v2, v5
	v_pk_add_f32 v[0:1], v[6:7], v[2:3] neg_lo:[0,1] neg_hi:[0,1]
	v_pk_add_f32 v[4:5], v[6:7], v[2:3]
	v_mov_b32_e32 v8, v0
	v_mov_b32_e32 v9, v5
	v_mul_f32_e32 v2, v5, v5
	v_pk_mul_f32 v[6:7], v[8:9], v[4:5] op_sel:[0,1] op_sel_hi:[1,0]
	v_pk_fma_f32 v[2:3], v[8:9], v[8:9], v[2:3] op_sel_hi:[1,1,0] neg_lo:[0,0,1] neg_hi:[0,0,1]
	v_pk_add_f32 v[6:7], v[6:7], v[6:7]
	v_mov_b32_e32 v10, v2
	v_mov_b32_e32 v11, v6
	v_pk_mul_f32 v[8:9], v[8:9], v[10:11]
	v_pk_mov_b32 v[10:11], v[4:5], v[6:7] op_sel:[1,0]
	v_mov_b32_e32 v18, v2
	v_mov_b32_e32 v19, v0
	v_pk_mul_f32 v[10:11], v[10:11], v[18:19]
	ds_read2_b64 v[18:21], v169 offset1:16
	ds_read2_b64 v[22:25], v169 offset0:32 offset1:48
	v_pk_add_f32 v[10:11], v[10:11], v[10:11] op_sel:[0,1] op_sel_hi:[0,1]
	v_pk_add_f32 v[8:9], v[8:9], v[8:9] op_sel:[0,1] op_sel_hi:[0,1] neg_lo:[0,1] neg_hi:[0,1]
	s_waitcnt lgkmcnt(1)
	v_pk_mul_f32 v[26:27], v[4:5], v[20:21] op_sel:[1,0]
	s_nop 0
	v_pk_fma_f32 v[28:29], v[0:1], v[20:21], v[26:27] op_sel:[0,0,1] op_sel_hi:[1,1,0]
	v_pk_fma_f32 v[20:21], v[0:1], v[20:21], v[26:27] op_sel:[0,0,1] op_sel_hi:[0,1,0] neg_lo:[0,0,1] neg_hi:[0,0,1]
	v_mov_b32_e32 v29, v21
	s_waitcnt lgkmcnt(0)
	v_pk_mul_f32 v[20:21], v[6:7], v[22:23] op_sel_hi:[0,1]
	v_pk_fma_f32 v[26:27], v[2:3], v[22:23], v[20:21] op_sel:[0,0,1] op_sel_hi:[1,1,0]
	v_pk_fma_f32 v[20:21], v[2:3], v[22:23], v[20:21] op_sel:[0,0,1] op_sel_hi:[0,1,0] neg_lo:[0,0,1] neg_hi:[0,0,1]
	v_mov_b32_e32 v27, v21
	v_pk_mul_f32 v[20:21], v[10:11], v[24:25]
	s_nop 0
	v_pk_fma_f32 v[22:23], v[8:9], v[24:25], v[20:21] op_sel:[0,0,1] op_sel_hi:[1,1,0]
	v_pk_fma_f32 v[20:21], v[8:9], v[24:25], v[20:21] op_sel:[0,0,1] op_sel_hi:[1,1,0] neg_lo:[0,0,1] neg_hi:[0,0,1]
	s_nop 0
	v_mov_b32_e32 v23, v21
	v_pk_add_f32 v[20:21], v[18:19], v[26:27]
	v_pk_add_f32 v[24:25], v[28:29], v[22:23]
	v_pk_add_f32 v[18:19], v[18:19], v[26:27] neg_lo:[0,1] neg_hi:[0,1]
	v_pk_add_f32 v[22:23], v[28:29], v[22:23] neg_lo:[0,1] neg_hi:[0,1]
	v_pk_add_f32 v[30:31], v[20:21], v[24:25]
	v_pk_add_f32 v[26:27], v[18:19], v[22:23] op_sel:[0,1] op_sel_hi:[1,0]
	v_pk_add_f32 v[18:19], v[18:19], v[22:23] op_sel:[0,1] op_sel_hi:[1,0] neg_lo:[0,1] neg_hi:[0,1]
	v_mov_b32_e32 v22, v26
	v_mov_b32_e32 v23, v19
	v_mov_b32_e32 v19, v27
	ds_write2_b64 v169, v[30:31], v[18:19] offset1:16
	v_pk_add_f32 v[18:19], v[20:21], v[24:25] neg_lo:[0,1] neg_hi:[0,1]
	ds_write2_b64 v169, v[18:19], v[22:23] offset0:32 offset1:48
	ds_read2_b64 v[18:21], v14 offset1:16
	ds_read2_b64 v[22:25], v14 offset0:32 offset1:48
	s_waitcnt lgkmcnt(1)
	v_pk_mul_f32 v[26:27], v[4:5], v[20:21] op_sel:[1,0]
	s_nop 0
	v_pk_fma_f32 v[28:29], v[0:1], v[20:21], v[26:27] op_sel:[0,0,1] op_sel_hi:[1,1,0]
	v_pk_fma_f32 v[20:21], v[0:1], v[20:21], v[26:27] op_sel:[0,0,1] op_sel_hi:[0,1,0] neg_lo:[0,0,1] neg_hi:[0,0,1]
	v_mov_b32_e32 v29, v21
	s_waitcnt lgkmcnt(0)
; HD float2 cmul(float2 a, float2 b){ return make_float2(a.x*b.x - a.y*b.y, a.x*b.y + a.y*b.x); }
; HD float2 cmulc(float2 a, float2 b){ return make_float2(a.x*b.x + a.y*b.y, a.y*b.x - a.x*b.y); }
; template<bool INV, bool NOTW>
; HD void bf4c(float2* Z, int i0, int i1, int i2, int i3, float2 w1, float2 w2, float2 w3){
;   float2 a0=Z[i0], a1=Z[i1], a2=Z[i2], a3=Z[i3];
;   if (INV && !NOTW){ a1=cmulc(a1,w1); a2=cmulc(a2,w2); a3=cmulc(a3,w3); }
;   float2 s02=make_float2(a0.x+a2.x,a0.y+a2.y), d02=make_float2(a0.x-a2.x,a0.y-a2.y);
;   float2 s13=make_float2(a1.x+a3.x,a1.y+a3.y), d13=make_float2(a1.x-a3.x,a1.y-a3.y);
;   float2 y0=make_float2(s02.x+s13.x,s02.y+s13.y), y2=make_float2(s02.x-s13.x,s02.y-s13.y);
;   float2 ym=make_float2(d02.x+d13.y,d02.y-d13.x);
;   float2 yp=make_float2(d02.x-d13.y,d02.y+d13.x);
;   float2 y1, y3;
;   if (INV){ y1=yp; y3=ym; } else if (NOTW){ y1=ym; y3=yp; } else { y1=cmul(ym,w1); y2=cmul(y2,w2); y3=cmul(yp,w3); }
;   Z[i0]=y0; Z[i1]=y1; Z[i2]=y2; Z[i3]=y3;
; }
; template<bool INV, int LQ, bool BARRIER=true>
; HD void fft_pass(float2* Z, const float2* twA, const float2* twB, int tid){
;     ...
;     int j=tid&(q-1); int base0=((tid>>LQ)<<(LQ+2))+j;
;     float2 w1=make_float2(1.f,0.f), w2=w1, w3=w1;
;     if (LQ>0){ int k=j*tws; w1=cmul(twA[k>>6],twB[k&63]); w2=cmul(w1,w1); w3=cmul(w2,w1); }
;     _Pragma("unroll") for (int i=0;i<8;++i){ int base=base0+i*2048; bf4c<INV,(LQ==0)>(Z,base,base+q,base+2*q,base+3*q,w1,w2,w3); }
	v_pk_mul_f32 v[20:21], v[6:7], v[22:23] op_sel_hi:[0,1]
	v_pk_fma_f32 v[26:27], v[2:3], v[22:23], v[20:21] op_sel:[0,0,1] op_sel_hi:[1,1,0]
	v_pk_fma_f32 v[20:21], v[2:3], v[22:23], v[20:21] op_sel:[0,0,1] op_sel_hi:[0,1,0] neg_lo:[0,0,1] neg_hi:[0,0,1]
	v_mov_b32_e32 v27, v21
	v_pk_mul_f32 v[20:21], v[10:11], v[24:25]
	s_nop 0
	v_pk_fma_f32 v[22:23], v[8:9], v[24:25], v[20:21] op_sel:[0,0,1] op_sel_hi:[1,1,0]
	v_pk_fma_f32 v[20:21], v[8:9], v[24:25], v[20:21] op_sel:[0,0,1] op_sel_hi:[1,1,0] neg_lo:[0,0,1] neg_hi:[0,0,1]
	s_nop 0
	v_mov_b32_e32 v23, v21
	v_pk_add_f32 v[20:21], v[18:19], v[26:27]
	v_pk_add_f32 v[24:25], v[28:29], v[22:23]
	v_pk_add_f32 v[18:19], v[18:19], v[26:27] neg_lo:[0,1] neg_hi:[0,1]
	v_pk_add_f32 v[22:23], v[28:29], v[22:23] neg_lo:[0,1] neg_hi:[0,1]
	v_pk_add_f32 v[30:31], v[20:21], v[24:25]
	v_pk_add_f32 v[26:27], v[18:19], v[22:23] op_sel:[0,1] op_sel_hi:[1,0]
	v_pk_add_f32 v[18:19], v[18:19], v[22:23] op_sel:[0,1] op_sel_hi:[1,0] neg_lo:[0,1] neg_hi:[0,1]
	v_mov_b32_e32 v22, v26
	v_mov_b32_e32 v23, v19
	v_mov_b32_e32 v19, v27
	ds_write2_b64 v14, v[30:31], v[18:19] offset1:16
	v_pk_add_f32 v[18:19], v[20:21], v[24:25] neg_lo:[0,1] neg_hi:[0,1]
	ds_write2_b64 v14, v[18:19], v[22:23] offset0:32 offset1:48
	ds_read2_b64 v[18:21], v15 offset1:16
	ds_read2_b64 v[22:25], v15 offset0:32 offset1:48
	s_waitcnt lgkmcnt(1)
	v_pk_mul_f32 v[26:27], v[4:5], v[20:21] op_sel:[1,0]
	s_nop 0
	v_pk_fma_f32 v[28:29], v[0:1], v[20:21], v[26:27] op_sel:[0,0,1] op_sel_hi:[1,1,0]
	v_pk_fma_f32 v[20:21], v[0:1], v[20:21], v[26:27] op_sel:[0,0,1] op_sel_hi:[0,1,0] neg_lo:[0,0,1] neg_hi:[0,0,1]
	v_mov_b32_e32 v29, v21
	s_waitcnt lgkmcnt(0)
	v_pk_mul_f32 v[20:21], v[6:7], v[22:23] op_sel_hi:[0,1]
	v_pk_fma_f32 v[26:27], v[2:3], v[22:23], v[20:21] op_sel:[0,0,1] op_sel_hi:[1,1,0]
	v_pk_fma_f32 v[20:21], v[2:3], v[22:23], v[20:21] op_sel:[0,0,1] op_sel_hi:[0,1,0] neg_lo:[0,0,1] neg_hi:[0,0,1]
	v_mov_b32_e32 v27, v21
	v_pk_mul_f32 v[20:21], v[10:11], v[24:25]
	s_nop 0
	v_pk_fma_f32 v[22:23], v[8:9], v[24:25], v[20:21] op_sel:[0,0,1] op_sel_hi:[1,1,0]
	v_pk_fma_f32 v[20:21], v[8:9], v[24:25], v[20:21] op_sel:[0,0,1] op_sel_hi:[1,1,0] neg_lo:[0,0,1] neg_hi:[0,0,1]
	s_nop 0
	v_mov_b32_e32 v23, v21
	v_pk_add_f32 v[20:21], v[18:19], v[26:27]
	v_pk_add_f32 v[24:25], v[28:29], v[22:23]
	v_pk_add_f32 v[18:19], v[18:19], v[26:27] neg_lo:[0,1] neg_hi:[0,1]
	v_pk_add_f32 v[22:23], v[28:29], v[22:23] neg_lo:[0,1] neg_hi:[0,1]
	v_pk_add_f32 v[30:31], v[20:21], v[24:25]
	v_pk_add_f32 v[26:27], v[18:19], v[22:23] op_sel:[0,1] op_sel_hi:[1,0]
	v_pk_add_f32 v[18:19], v[18:19], v[22:23] op_sel:[0,1] op_sel_hi:[1,0] neg_lo:[0,1] neg_hi:[0,1]
	v_mov_b32_e32 v22, v26
	v_mov_b32_e32 v23, v19
	v_mov_b32_e32 v19, v27
	ds_write2_b64 v15, v[30:31], v[18:19] offset1:16
	v_pk_add_f32 v[18:19], v[20:21], v[24:25] neg_lo:[0,1] neg_hi:[0,1]
	ds_write2_b64 v15, v[18:19], v[22:23] offset0:32 offset1:48
	ds_read2_b64 v[18:21], v16 offset1:16
	ds_read2_b64 v[22:25], v16 offset0:32 offset1:48
	s_waitcnt lgkmcnt(1)
	v_pk_mul_f32 v[14:15], v[4:5], v[20:21] op_sel:[1,0]
	s_nop 0
	v_pk_fma_f32 v[26:27], v[0:1], v[20:21], v[14:15] op_sel:[0,0,1] op_sel_hi:[1,1,0]
	v_pk_fma_f32 v[14:15], v[0:1], v[20:21], v[14:15] op_sel:[0,0,1] op_sel_hi:[0,1,0] neg_lo:[0,0,1] neg_hi:[0,0,1]
	v_mov_b32_e32 v27, v15
	s_waitcnt lgkmcnt(0)
	v_pk_mul_f32 v[14:15], v[6:7], v[22:23] op_sel_hi:[0,1]
	v_pk_fma_f32 v[20:21], v[2:3], v[22:23], v[14:15] op_sel:[0,0,1] op_sel_hi:[1,1,0]
	v_pk_fma_f32 v[14:15], v[2:3], v[22:23], v[14:15] op_sel:[0,0,1] op_sel_hi:[0,1,0] neg_lo:[0,0,1] neg_hi:[0,0,1]
	v_mov_b32_e32 v21, v15
	v_pk_mul_f32 v[14:15], v[10:11], v[24:25]
	s_nop 0
	v_pk_fma_f32 v[22:23], v[8:9], v[24:25], v[14:15] op_sel:[0,0,1] op_sel_hi:[1,1,0]
	v_pk_fma_f32 v[14:15], v[8:9], v[24:25], v[14:15] op_sel:[0,0,1] op_sel_hi:[1,1,0] neg_lo:[0,0,1] neg_hi:[0,0,1]
	s_nop 0
	v_mov_b32_e32 v23, v15
	v_pk_add_f32 v[14:15], v[18:19], v[20:21]
	v_pk_add_f32 v[18:19], v[18:19], v[20:21] neg_lo:[0,1] neg_hi:[0,1]
	v_pk_add_f32 v[20:21], v[26:27], v[22:23] neg_lo:[0,1] neg_hi:[0,1]
	v_pk_add_f32 v[24:25], v[26:27], v[22:23]
	v_pk_add_f32 v[22:23], v[18:19], v[20:21] op_sel:[0,1] op_sel_hi:[1,0]
	v_pk_add_f32 v[18:19], v[18:19], v[20:21] op_sel:[0,1] op_sel_hi:[1,0] neg_lo:[0,1] neg_hi:[0,1]
	v_pk_add_f32 v[28:29], v[14:15], v[24:25]
	v_mov_b32_e32 v20, v22
	v_mov_b32_e32 v21, v19
	v_mov_b32_e32 v19, v23
	v_pk_add_f32 v[14:15], v[14:15], v[24:25] neg_lo:[0,1] neg_hi:[0,1]
	ds_write2_b64 v16, v[28:29], v[18:19] offset1:16
	ds_write2_b64 v16, v[14:15], v[20:21] offset0:32 offset1:48
	ds_read_b64 v[14:15], v170
	ds_read_b64 v[16:17], v171
	ds_read_b64 v[18:19], v172
	ds_read_b64 v[20:21], v173
	s_waitcnt lgkmcnt(2)
	v_pk_mul_f32 v[22:23], v[4:5], v[16:17] op_sel:[1,0]
	s_nop 0
	v_pk_fma_f32 v[24:25], v[0:1], v[16:17], v[22:23] op_sel:[0,0,1] op_sel_hi:[1,1,0]
	v_pk_fma_f32 v[16:17], v[0:1], v[16:17], v[22:23] op_sel:[0,0,1] op_sel_hi:[0,1,0] neg_lo:[0,0,1] neg_hi:[0,0,1]
	v_mov_b32_e32 v25, v17
	s_waitcnt lgkmcnt(1)
	v_pk_mul_f32 v[16:17], v[6:7], v[18:19] op_sel_hi:[0,1]
	v_pk_fma_f32 v[22:23], v[2:3], v[18:19], v[16:17] op_sel:[0,0,1] op_sel_hi:[1,1,0]
	v_pk_fma_f32 v[16:17], v[2:3], v[18:19], v[16:17] op_sel:[0,0,1] op_sel_hi:[0,1,0] neg_lo:[0,0,1] neg_hi:[0,0,1]
	v_mov_b32_e32 v23, v17
	s_waitcnt lgkmcnt(0)
; HD float2 cmul(float2 a, float2 b){ return make_float2(a.x*b.x - a.y*b.y, a.x*b.y + a.y*b.x); }
; HD float2 cmulc(float2 a, float2 b){ return make_float2(a.x*b.x + a.y*b.y, a.y*b.x - a.x*b.y); }
; template<bool INV, bool NOTW>
; HD void bf4c(float2* Z, int i0, int i1, int i2, int i3, float2 w1, float2 w2, float2 w3){
;   float2 a0=Z[i0], a1=Z[i1], a2=Z[i2], a3=Z[i3];
;   if (INV && !NOTW){ a1=cmulc(a1,w1); a2=cmulc(a2,w2); a3=cmulc(a3,w3); }
;   float2 s02=make_float2(a0.x+a2.x,a0.y+a2.y), d02=make_float2(a0.x-a2.x,a0.y-a2.y);
;   float2 s13=make_float2(a1.x+a3.x,a1.y+a3.y), d13=make_float2(a1.x-a3.x,a1.y-a3.y);
;   float2 y0=make_float2(s02.x+s13.x,s02.y+s13.y), y2=make_float2(s02.x-s13.x,s02.y-s13.y);
;   float2 ym=make_float2(d02.x+d13.y,d02.y-d13.x);
;   float2 yp=make_float2(d02.x-d13.y,d02.y+d13.x);
;   float2 y1, y3;
;   if (INV){ y1=yp; y3=ym; } else if (NOTW){ y1=ym; y3=yp; } else { y1=cmul(ym,w1); y2=cmul(y2,w2); y3=cmul(yp,w3); }
;   Z[i0]=y0; Z[i1]=y1; Z[i2]=y2; Z[i3]=y3;
; }
; template<bool INV, int LQ, bool BARRIER=true>
; HD void fft_pass(float2* Z, const float2* twA, const float2* twB, int tid){
;     ...
;     int j=tid&(q-1); int base0=((tid>>LQ)<<(LQ+2))+j;
;     float2 w1=make_float2(1.f,0.f), w2=w1, w3=w1;
;     if (LQ>0){ int k=j*tws; w1=cmul(twA[k>>6],twB[k&63]); w2=cmul(w1,w1); w3=cmul(w2,w1); }
;     _Pragma("unroll") for (int i=0;i<8;++i){ int base=base0+i*2048; bf4c<INV,(LQ==0)>(Z,base,base+q,base+2*q,base+3*q,w1,w2,w3); }
	v_pk_mul_f32 v[16:17], v[10:11], v[20:21]
	s_nop 0
	v_pk_fma_f32 v[18:19], v[8:9], v[20:21], v[16:17] op_sel:[0,0,1] op_sel_hi:[1,1,0]
	v_pk_fma_f32 v[16:17], v[8:9], v[20:21], v[16:17] op_sel:[0,0,1] op_sel_hi:[1,1,0] neg_lo:[0,0,1] neg_hi:[0,0,1]
	s_nop 0
	v_mov_b32_e32 v19, v17
	v_pk_add_f32 v[16:17], v[14:15], v[22:23]
	v_pk_add_f32 v[20:21], v[24:25], v[18:19]
	v_pk_add_f32 v[14:15], v[14:15], v[22:23] neg_lo:[0,1] neg_hi:[0,1]
	v_pk_add_f32 v[18:19], v[24:25], v[18:19] neg_lo:[0,1] neg_hi:[0,1]
	v_pk_add_f32 v[26:27], v[16:17], v[20:21]
	v_pk_add_f32 v[22:23], v[14:15], v[18:19] op_sel:[0,1] op_sel_hi:[1,0]
	v_pk_add_f32 v[14:15], v[14:15], v[18:19] op_sel:[0,1] op_sel_hi:[1,0] neg_lo:[0,1] neg_hi:[0,1]
	v_mov_b32_e32 v18, v22
	v_mov_b32_e32 v19, v15
	v_mov_b32_e32 v15, v23
	ds_write_b64 v170, v[26:27]
	ds_write_b64 v171, v[14:15]
	v_pk_add_f32 v[14:15], v[16:17], v[20:21] neg_lo:[0,1] neg_hi:[0,1]
	ds_write_b64 v172, v[14:15]
	ds_write_b64 v173, v[18:19]
	ds_read_b64 v[14:15], v174
	ds_read_b64 v[16:17], v175
	ds_read_b64 v[18:19], v176
	ds_read_b64 v[20:21], v177
	s_waitcnt lgkmcnt(2)
	v_pk_mul_f32 v[22:23], v[4:5], v[16:17] op_sel:[1,0]
	s_nop 0
	v_pk_fma_f32 v[24:25], v[0:1], v[16:17], v[22:23] op_sel:[0,0,1] op_sel_hi:[1,1,0]
	v_pk_fma_f32 v[16:17], v[0:1], v[16:17], v[22:23] op_sel:[0,0,1] op_sel_hi:[0,1,0] neg_lo:[0,0,1] neg_hi:[0,0,1]
	v_mov_b32_e32 v25, v17
	s_waitcnt lgkmcnt(1)
	v_pk_mul_f32 v[16:17], v[6:7], v[18:19] op_sel_hi:[0,1]
	v_pk_fma_f32 v[22:23], v[2:3], v[18:19], v[16:17] op_sel:[0,0,1] op_sel_hi:[1,1,0]
	v_pk_fma_f32 v[16:17], v[2:3], v[18:19], v[16:17] op_sel:[0,0,1] op_sel_hi:[0,1,0] neg_lo:[0,0,1] neg_hi:[0,0,1]
	v_mov_b32_e32 v23, v17
	s_waitcnt lgkmcnt(0)
	v_pk_mul_f32 v[16:17], v[10:11], v[20:21]
	s_nop 0
	v_pk_fma_f32 v[18:19], v[8:9], v[20:21], v[16:17] op_sel:[0,0,1] op_sel_hi:[1,1,0]
	v_pk_fma_f32 v[16:17], v[8:9], v[20:21], v[16:17] op_sel:[0,0,1] op_sel_hi:[1,1,0] neg_lo:[0,0,1] neg_hi:[0,0,1]
	s_nop 0
	v_mov_b32_e32 v19, v17
	v_pk_add_f32 v[16:17], v[14:15], v[22:23]
	v_pk_add_f32 v[20:21], v[24:25], v[18:19]
	v_pk_add_f32 v[14:15], v[14:15], v[22:23] neg_lo:[0,1] neg_hi:[0,1]
	v_pk_add_f32 v[18:19], v[24:25], v[18:19] neg_lo:[0,1] neg_hi:[0,1]
	v_pk_add_f32 v[26:27], v[16:17], v[20:21]
	v_pk_add_f32 v[22:23], v[14:15], v[18:19] op_sel:[0,1] op_sel_hi:[1,0]
	v_pk_add_f32 v[14:15], v[14:15], v[18:19] op_sel:[0,1] op_sel_hi:[1,0] neg_lo:[0,1] neg_hi:[0,1]
	v_mov_b32_e32 v18, v22
	v_mov_b32_e32 v19, v15
	v_mov_b32_e32 v15, v23
	ds_write_b64 v174, v[26:27]
	ds_write_b64 v175, v[14:15]
	v_pk_add_f32 v[14:15], v[16:17], v[20:21] neg_lo:[0,1] neg_hi:[0,1]
	ds_write_b64 v176, v[14:15]
	ds_write_b64 v177, v[18:19]
	ds_read_b64 v[14:15], v178
	ds_read_b64 v[16:17], v179
	ds_read_b64 v[18:19], v180
	ds_read_b64 v[20:21], v181
	s_waitcnt lgkmcnt(2)
	v_pk_mul_f32 v[22:23], v[4:5], v[16:17] op_sel:[1,0]
	s_nop 0
	v_pk_fma_f32 v[24:25], v[0:1], v[16:17], v[22:23] op_sel:[0,0,1] op_sel_hi:[1,1,0]
	v_pk_fma_f32 v[16:17], v[0:1], v[16:17], v[22:23] op_sel:[0,0,1] op_sel_hi:[0,1,0] neg_lo:[0,0,1] neg_hi:[0,0,1]
	v_mov_b32_e32 v25, v17
	s_waitcnt lgkmcnt(1)
	v_pk_mul_f32 v[16:17], v[6:7], v[18:19] op_sel_hi:[0,1]
	v_pk_fma_f32 v[22:23], v[2:3], v[18:19], v[16:17] op_sel:[0,0,1] op_sel_hi:[1,1,0]
	v_pk_fma_f32 v[16:17], v[2:3], v[18:19], v[16:17] op_sel:[0,0,1] op_sel_hi:[0,1,0] neg_lo:[0,0,1] neg_hi:[0,0,1]
	v_mov_b32_e32 v23, v17
	s_waitcnt lgkmcnt(0)
	v_pk_mul_f32 v[16:17], v[10:11], v[20:21]
	s_nop 0
	v_pk_fma_f32 v[18:19], v[8:9], v[20:21], v[16:17] op_sel:[0,0,1] op_sel_hi:[1,1,0]
	v_pk_fma_f32 v[16:17], v[8:9], v[20:21], v[16:17] op_sel:[0,0,1] op_sel_hi:[1,1,0] neg_lo:[0,0,1] neg_hi:[0,0,1]
	s_nop 0
	v_mov_b32_e32 v19, v17
	v_pk_add_f32 v[16:17], v[14:15], v[22:23]
	v_pk_add_f32 v[20:21], v[24:25], v[18:19]
	v_pk_add_f32 v[14:15], v[14:15], v[22:23] neg_lo:[0,1] neg_hi:[0,1]
	v_pk_add_f32 v[18:19], v[24:25], v[18:19] neg_lo:[0,1] neg_hi:[0,1]
	v_pk_add_f32 v[26:27], v[16:17], v[20:21]
	v_pk_add_f32 v[22:23], v[14:15], v[18:19] op_sel:[0,1] op_sel_hi:[1,0]
	v_pk_add_f32 v[14:15], v[14:15], v[18:19] op_sel:[0,1] op_sel_hi:[1,0] neg_lo:[0,1] neg_hi:[0,1]
	v_mov_b32_e32 v18, v22
	v_mov_b32_e32 v19, v15
	v_mov_b32_e32 v15, v23
	ds_write_b64 v178, v[26:27]
	ds_write_b64 v179, v[14:15]
	v_pk_add_f32 v[14:15], v[16:17], v[20:21] neg_lo:[0,1] neg_hi:[0,1]
	ds_write_b64 v180, v[14:15]
	ds_write_b64 v181, v[18:19]
	ds_read_b64 v[14:15], v182
	ds_read_b64 v[16:17], v183
	ds_read_b64 v[18:19], v184
	ds_read_b64 v[20:21], v185
	s_waitcnt lgkmcnt(2)
	v_pk_mul_f32 v[4:5], v[4:5], v[16:17] op_sel:[1,0]
	s_nop 0
	v_pk_fma_f32 v[22:23], v[0:1], v[16:17], v[4:5] op_sel:[0,0,1] op_sel_hi:[1,1,0]
	v_pk_fma_f32 v[0:1], v[0:1], v[16:17], v[4:5] op_sel:[0,0,1] op_sel_hi:[0,1,0] neg_lo:[0,0,1] neg_hi:[0,0,1]
	v_mov_b32_e32 v23, v1
	s_waitcnt lgkmcnt(1)
	v_pk_mul_f32 v[0:1], v[6:7], v[18:19] op_sel_hi:[0,1]
	v_pk_fma_f32 v[4:5], v[2:3], v[18:19], v[0:1] op_sel:[0,0,1] op_sel_hi:[1,1,0]
	v_pk_fma_f32 v[0:1], v[2:3], v[18:19], v[0:1] op_sel:[0,0,1] op_sel_hi:[0,1,0] neg_lo:[0,0,1] neg_hi:[0,0,1]
	v_mov_b32_e32 v5, v1
	s_waitcnt lgkmcnt(0)
	v_pk_mul_f32 v[0:1], v[10:11], v[20:21]
	s_nop 0
	v_pk_fma_f32 v[2:3], v[8:9], v[20:21], v[0:1] op_sel:[0,0,1] op_sel_hi:[1,1,0]
	v_pk_fma_f32 v[0:1], v[8:9], v[20:21], v[0:1] op_sel:[0,0,1] op_sel_hi:[1,1,0] neg_lo:[0,0,1] neg_hi:[0,0,1]
	s_nop 0
	v_mov_b32_e32 v3, v1
	v_pk_add_f32 v[0:1], v[14:15], v[4:5]
	v_pk_add_f32 v[6:7], v[22:23], v[2:3]
	v_pk_add_f32 v[4:5], v[14:15], v[4:5] neg_lo:[0,1] neg_hi:[0,1]
	v_pk_add_f32 v[2:3], v[22:23], v[2:3] neg_lo:[0,1] neg_hi:[0,1]
	v_pk_add_f32 v[8:9], v[0:1], v[6:7]
	v_pk_add_f32 v[10:11], v[4:5], v[2:3] op_sel:[0,1] op_sel_hi:[1,0]
	v_pk_add_f32 v[2:3], v[4:5], v[2:3] op_sel:[0,1] op_sel_hi:[1,0] neg_lo:[0,1] neg_hi:[0,1]
	v_pk_add_f32 v[0:1], v[0:1], v[6:7] neg_lo:[0,1] neg_hi:[0,1]
	v_mov_b32_e32 v4, v10
	v_mov_b32_e32 v5, v3
	v_mov_b32_e32 v3, v11
	ds_write_b64 v182, v[8:9]
	ds_write_b64 v183, v[2:3]
	ds_write_b64 v184, v[0:1]
	ds_write_b64 v185, v[4:5]
	s_waitcnt lgkmcnt(0)
; HD float2 cmul(float2 a, float2 b){ return make_float2(a.x*b.x - a.y*b.y, a.x*b.y + a.y*b.x); }
; HD float2 cmulc(float2 a, float2 b){ return make_float2(a.x*b.x + a.y*b.y, a.y*b.x - a.x*b.y); }
; template<bool INV, bool NOTW>
; HD void bf4c(float2* Z, int i0, int i1, int i2, int i3, float2 w1, float2 w2, float2 w3){
;   float2 a0=Z[i0], a1=Z[i1], a2=Z[i2], a3=Z[i3];
;   if (INV && !NOTW){ a1=cmulc(a1,w1); a2=cmulc(a2,w2); a3=cmulc(a3,w3); }
;   float2 s02=make_float2(a0.x+a2.x,a0.y+a2.y), d02=make_float2(a0.x-a2.x,a0.y-a2.y);
;   float2 s13=make_float2(a1.x+a3.x,a1.y+a3.y), d13=make_float2(a1.x-a3.x,a1.y-a3.y);
;   float2 y0=make_float2(s02.x+s13.x,s02.y+s13.y), y2=make_float2(s02.x-s13.x,s02.y-s13.y);
;   float2 ym=make_float2(d02.x+d13.y,d02.y-d13.x);
;   float2 yp=make_float2(d02.x-d13.y,d02.y+d13.x);
;   float2 y1, y3;
;   if (INV){ y1=yp; y3=ym; } else if (NOTW){ y1=ym; y3=yp; } else { y1=cmul(ym,w1); y2=cmul(y2,w2); y3=cmul(yp,w3); }
;   Z[i0]=y0; Z[i1]=y1; Z[i2]=y2; Z[i3]=y3;
; }
; template<bool INV, int LQ, bool BARRIER=true>
; HD void fft_pass(float2* Z, const float2* twA, const float2* twB, int tid){
;     ...
;     int j=tid&(q-1); int base0=((tid>>LQ)<<(LQ+2))+j;
;     float2 w1=make_float2(1.f,0.f), w2=w1, w3=w1;
;     if (LQ>0){ int k=j*tws; w1=cmul(twA[k>>6],twB[k&63]); w2=cmul(w1,w1); w3=cmul(w2,w1); }
;     _Pragma("unroll") for (int i=0;i<8;++i){ int base=base0+i*2048; bf4c<INV,(LQ==0)>(Z,base,base+q,base+2*q,base+3*q,w1,w2,w3); }
	ds_read_b64 v[0:1], v150
	ds_read_b64 v[2:3], v12
	s_waitcnt lgkmcnt(0)
	v_pk_mul_f32 v[4:5], v[0:1], v[2:3]
	v_pk_mul_f32 v[2:3], v[0:1], v[2:3] op_sel:[1,0] op_sel_hi:[0,1]
	v_mov_b32_e32 v6, v4
	v_mov_b32_e32 v7, v2
	v_mov_b32_e32 v2, v5
	v_pk_add_f32 v[0:1], v[6:7], v[2:3] neg_lo:[0,1] neg_hi:[0,1]
	v_pk_add_f32 v[4:5], v[6:7], v[2:3]
	v_mov_b32_e32 v8, v0
	v_mov_b32_e32 v9, v5
	v_mul_f32_e32 v2, v5, v5
	v_pk_mul_f32 v[6:7], v[8:9], v[4:5] op_sel:[0,1] op_sel_hi:[1,0]
	v_pk_fma_f32 v[2:3], v[8:9], v[8:9], v[2:3] op_sel_hi:[1,1,0] neg_lo:[0,0,1] neg_hi:[0,0,1]
	v_pk_add_f32 v[6:7], v[6:7], v[6:7]
	v_mov_b32_e32 v10, v2
	v_mov_b32_e32 v11, v6
	v_pk_mul_f32 v[8:9], v[8:9], v[10:11]
	v_pk_mov_b32 v[10:11], v[4:5], v[6:7] op_sel:[1,0]
	v_mov_b32_e32 v12, v2
	v_mov_b32_e32 v13, v0
	v_pk_mul_f32 v[10:11], v[10:11], v[12:13]
	ds_read2st64_b64 v[12:15], v151 offset1:1
	ds_read2st64_b64 v[16:19], v151 offset0:2 offset1:3
	v_pk_add_f32 v[10:11], v[10:11], v[10:11] op_sel:[0,1] op_sel_hi:[0,1]
	v_pk_add_f32 v[8:9], v[8:9], v[8:9] op_sel:[0,1] op_sel_hi:[0,1] neg_lo:[0,1] neg_hi:[0,1]
	s_waitcnt lgkmcnt(1)
	v_pk_mul_f32 v[20:21], v[4:5], v[14:15] op_sel:[1,0]
	s_nop 0
	v_pk_fma_f32 v[22:23], v[0:1], v[14:15], v[20:21] op_sel:[0,0,1] op_sel_hi:[1,1,0]
	v_pk_fma_f32 v[14:15], v[0:1], v[14:15], v[20:21] op_sel:[0,0,1] op_sel_hi:[0,1,0] neg_lo:[0,0,1] neg_hi:[0,0,1]
	v_mov_b32_e32 v23, v15
	s_waitcnt lgkmcnt(0)
	v_pk_mul_f32 v[14:15], v[6:7], v[16:17] op_sel_hi:[0,1]
	v_pk_fma_f32 v[20:21], v[2:3], v[16:17], v[14:15] op_sel:[0,0,1] op_sel_hi:[1,1,0]
	v_pk_fma_f32 v[14:15], v[2:3], v[16:17], v[14:15] op_sel:[0,0,1] op_sel_hi:[0,1,0] neg_lo:[0,0,1] neg_hi:[0,0,1]
	v_mov_b32_e32 v21, v15
	v_pk_mul_f32 v[14:15], v[10:11], v[18:19]
	s_nop 0
	v_pk_fma_f32 v[16:17], v[8:9], v[18:19], v[14:15] op_sel:[0,0,1] op_sel_hi:[1,1,0]
	v_pk_fma_f32 v[14:15], v[8:9], v[18:19], v[14:15] op_sel:[0,0,1] op_sel_hi:[1,1,0] neg_lo:[0,0,1] neg_hi:[0,0,1]
	s_nop 0
	v_mov_b32_e32 v17, v15
	v_pk_add_f32 v[14:15], v[12:13], v[20:21]
	v_pk_add_f32 v[18:19], v[22:23], v[16:17]
	v_pk_add_f32 v[12:13], v[12:13], v[20:21] neg_lo:[0,1] neg_hi:[0,1]
	v_pk_add_f32 v[16:17], v[22:23], v[16:17] neg_lo:[0,1] neg_hi:[0,1]
	v_pk_add_f32 v[24:25], v[14:15], v[18:19]
	v_pk_add_f32 v[20:21], v[12:13], v[16:17] op_sel:[0,1] op_sel_hi:[1,0]
	v_pk_add_f32 v[12:13], v[12:13], v[16:17] op_sel:[0,1] op_sel_hi:[1,0] neg_lo:[0,1] neg_hi:[0,1]
	v_mov_b32_e32 v16, v20
	v_mov_b32_e32 v17, v13
	v_mov_b32_e32 v13, v21
	ds_write2st64_b64 v151, v[24:25], v[12:13] offset1:1
	v_pk_add_f32 v[12:13], v[14:15], v[18:19] neg_lo:[0,1] neg_hi:[0,1]
	ds_write2st64_b64 v151, v[12:13], v[16:17] offset0:2 offset1:3
	ds_read2st64_b64 v[12:15], v151 offset0:32 offset1:33
	ds_read2st64_b64 v[16:19], v151 offset0:34 offset1:35
	s_waitcnt lgkmcnt(1)
	v_pk_mul_f32 v[20:21], v[4:5], v[14:15] op_sel:[1,0]
	s_nop 0
	v_pk_fma_f32 v[22:23], v[0:1], v[14:15], v[20:21] op_sel:[0,0,1] op_sel_hi:[1,1,0]
	v_pk_fma_f32 v[14:15], v[0:1], v[14:15], v[20:21] op_sel:[0,0,1] op_sel_hi:[0,1,0] neg_lo:[0,0,1] neg_hi:[0,0,1]
	v_mov_b32_e32 v23, v15
	s_waitcnt lgkmcnt(0)
	v_pk_mul_f32 v[14:15], v[6:7], v[16:17] op_sel_hi:[0,1]
	v_pk_fma_f32 v[20:21], v[2:3], v[16:17], v[14:15] op_sel:[0,0,1] op_sel_hi:[1,1,0]
	v_pk_fma_f32 v[14:15], v[2:3], v[16:17], v[14:15] op_sel:[0,0,1] op_sel_hi:[0,1,0] neg_lo:[0,0,1] neg_hi:[0,0,1]
	v_mov_b32_e32 v21, v15
	v_pk_mul_f32 v[14:15], v[10:11], v[18:19]
	s_nop 0
	v_pk_fma_f32 v[16:17], v[8:9], v[18:19], v[14:15] op_sel:[0,0,1] op_sel_hi:[1,1,0]
	v_pk_fma_f32 v[14:15], v[8:9], v[18:19], v[14:15] op_sel:[0,0,1] op_sel_hi:[1,1,0] neg_lo:[0,0,1] neg_hi:[0,0,1]
	s_nop 0
	v_mov_b32_e32 v17, v15
	v_pk_add_f32 v[14:15], v[12:13], v[20:21]
	v_pk_add_f32 v[18:19], v[22:23], v[16:17]
	v_pk_add_f32 v[12:13], v[12:13], v[20:21] neg_lo:[0,1] neg_hi:[0,1]
	v_pk_add_f32 v[16:17], v[22:23], v[16:17] neg_lo:[0,1] neg_hi:[0,1]
	v_pk_add_f32 v[24:25], v[14:15], v[18:19]
	v_pk_add_f32 v[20:21], v[12:13], v[16:17] op_sel:[0,1] op_sel_hi:[1,0]
	v_pk_add_f32 v[12:13], v[12:13], v[16:17] op_sel:[0,1] op_sel_hi:[1,0] neg_lo:[0,1] neg_hi:[0,1]
	v_mov_b32_e32 v16, v20
	v_mov_b32_e32 v17, v13
	v_mov_b32_e32 v13, v21
	ds_write2st64_b64 v151, v[24:25], v[12:13] offset0:32 offset1:33
	v_pk_add_f32 v[12:13], v[14:15], v[18:19] neg_lo:[0,1] neg_hi:[0,1]
	ds_write2st64_b64 v151, v[12:13], v[16:17] offset0:34 offset1:35
	ds_read2st64_b64 v[12:15], v151 offset0:64 offset1:65
	ds_read2st64_b64 v[16:19], v151 offset0:66 offset1:67
	s_waitcnt lgkmcnt(1)
	v_pk_mul_f32 v[20:21], v[4:5], v[14:15] op_sel:[1,0]
	s_nop 0
	v_pk_fma_f32 v[22:23], v[0:1], v[14:15], v[20:21] op_sel:[0,0,1] op_sel_hi:[1,1,0]
	v_pk_fma_f32 v[14:15], v[0:1], v[14:15], v[20:21] op_sel:[0,0,1] op_sel_hi:[0,1,0] neg_lo:[0,0,1] neg_hi:[0,0,1]
	v_mov_b32_e32 v23, v15
	s_waitcnt lgkmcnt(0)
	v_pk_mul_f32 v[14:15], v[6:7], v[16:17] op_sel_hi:[0,1]
	v_pk_fma_f32 v[20:21], v[2:3], v[16:17], v[14:15] op_sel:[0,0,1] op_sel_hi:[1,1,0]
	v_pk_fma_f32 v[14:15], v[2:3], v[16:17], v[14:15] op_sel:[0,0,1] op_sel_hi:[0,1,0] neg_lo:[0,0,1] neg_hi:[0,0,1]
	v_mov_b32_e32 v21, v15
	v_pk_mul_f32 v[14:15], v[10:11], v[18:19]
	s_nop 0
	v_pk_fma_f32 v[16:17], v[8:9], v[18:19], v[14:15] op_sel:[0,0,1] op_sel_hi:[1,1,0]
	v_pk_fma_f32 v[14:15], v[8:9], v[18:19], v[14:15] op_sel:[0,0,1] op_sel_hi:[1,1,0] neg_lo:[0,0,1] neg_hi:[0,0,1]
	s_nop 0
	v_mov_b32_e32 v17, v15
	v_pk_add_f32 v[14:15], v[12:13], v[20:21]
	v_pk_add_f32 v[18:19], v[22:23], v[16:17]
	v_pk_add_f32 v[12:13], v[12:13], v[20:21] neg_lo:[0,1] neg_hi:[0,1]
	v_pk_add_f32 v[16:17], v[22:23], v[16:17] neg_lo:[0,1] neg_hi:[0,1]
	v_pk_add_f32 v[24:25], v[14:15], v[18:19]
	v_pk_add_f32 v[20:21], v[12:13], v[16:17] op_sel:[0,1] op_sel_hi:[1,0]
	v_pk_add_f32 v[12:13], v[12:13], v[16:17] op_sel:[0,1] op_sel_hi:[1,0] neg_lo:[0,1] neg_hi:[0,1]
	v_mov_b32_e32 v16, v20
	v_mov_b32_e32 v17, v13
	v_mov_b32_e32 v13, v21
	ds_write2st64_b64 v151, v[24:25], v[12:13] offset0:64 offset1:65
	v_pk_add_f32 v[12:13], v[14:15], v[18:19] neg_lo:[0,1] neg_hi:[0,1]
	ds_write2st64_b64 v151, v[12:13], v[16:17] offset0:66 offset1:67
	ds_read2st64_b64 v[12:15], v151 offset0:96 offset1:97
	ds_read2st64_b64 v[16:19], v151 offset0:98 offset1:99
	s_waitcnt lgkmcnt(1)
; HD float2 cmul(float2 a, float2 b){ return make_float2(a.x*b.x - a.y*b.y, a.x*b.y + a.y*b.x); }
; HD float2 cmulc(float2 a, float2 b){ return make_float2(a.x*b.x + a.y*b.y, a.y*b.x - a.x*b.y); }
; template<bool INV, bool NOTW>
; HD void bf4c(float2* Z, int i0, int i1, int i2, int i3, float2 w1, float2 w2, float2 w3){
;   float2 a0=Z[i0], a1=Z[i1], a2=Z[i2], a3=Z[i3];
;   if (INV && !NOTW){ a1=cmulc(a1,w1); a2=cmulc(a2,w2); a3=cmulc(a3,w3); }
;   float2 s02=make_float2(a0.x+a2.x,a0.y+a2.y), d02=make_float2(a0.x-a2.x,a0.y-a2.y);
;   float2 s13=make_float2(a1.x+a3.x,a1.y+a3.y), d13=make_float2(a1.x-a3.x,a1.y-a3.y);
;   float2 y0=make_float2(s02.x+s13.x,s02.y+s13.y), y2=make_float2(s02.x-s13.x,s02.y-s13.y);
;   float2 ym=make_float2(d02.x+d13.y,d02.y-d13.x);
;   float2 yp=make_float2(d02.x-d13.y,d02.y+d13.x);
;   float2 y1, y3;
;   if (INV){ y1=yp; y3=ym; } else if (NOTW){ y1=ym; y3=yp; } else { y1=cmul(ym,w1); y2=cmul(y2,w2); y3=cmul(yp,w3); }
;   Z[i0]=y0; Z[i1]=y1; Z[i2]=y2; Z[i3]=y3;
; }
; template<bool INV, int LQ, bool BARRIER=true>
; HD void fft_pass(float2* Z, const float2* twA, const float2* twB, int tid){
;     ...
;     int j=tid&(q-1); int base0=((tid>>LQ)<<(LQ+2))+j;
;     float2 w1=make_float2(1.f,0.f), w2=w1, w3=w1;
;     if (LQ>0){ int k=j*tws; w1=cmul(twA[k>>6],twB[k&63]); w2=cmul(w1,w1); w3=cmul(w2,w1); }
;     _Pragma("unroll") for (int i=0;i<8;++i){ int base=base0+i*2048; bf4c<INV,(LQ==0)>(Z,base,base+q,base+2*q,base+3*q,w1,w2,w3); }
	v_pk_mul_f32 v[20:21], v[4:5], v[14:15] op_sel:[1,0]
	s_nop 0
	v_pk_fma_f32 v[22:23], v[0:1], v[14:15], v[20:21] op_sel:[0,0,1] op_sel_hi:[1,1,0]
	v_pk_fma_f32 v[14:15], v[0:1], v[14:15], v[20:21] op_sel:[0,0,1] op_sel_hi:[0,1,0] neg_lo:[0,0,1] neg_hi:[0,0,1]
	v_mov_b32_e32 v23, v15
	s_waitcnt lgkmcnt(0)
	v_pk_mul_f32 v[14:15], v[6:7], v[16:17] op_sel_hi:[0,1]
	v_pk_fma_f32 v[20:21], v[2:3], v[16:17], v[14:15] op_sel:[0,0,1] op_sel_hi:[1,1,0]
	v_pk_fma_f32 v[14:15], v[2:3], v[16:17], v[14:15] op_sel:[0,0,1] op_sel_hi:[0,1,0] neg_lo:[0,0,1] neg_hi:[0,0,1]
	v_mov_b32_e32 v21, v15
	v_pk_mul_f32 v[14:15], v[10:11], v[18:19]
	s_nop 0
	v_pk_fma_f32 v[16:17], v[8:9], v[18:19], v[14:15] op_sel:[0,0,1] op_sel_hi:[1,1,0]
	v_pk_fma_f32 v[14:15], v[8:9], v[18:19], v[14:15] op_sel:[0,0,1] op_sel_hi:[1,1,0] neg_lo:[0,0,1] neg_hi:[0,0,1]
	s_nop 0
	v_mov_b32_e32 v17, v15
	v_pk_add_f32 v[14:15], v[12:13], v[20:21]
	v_pk_add_f32 v[18:19], v[22:23], v[16:17]
	v_pk_add_f32 v[12:13], v[12:13], v[20:21] neg_lo:[0,1] neg_hi:[0,1]
	v_pk_add_f32 v[16:17], v[22:23], v[16:17] neg_lo:[0,1] neg_hi:[0,1]
	v_pk_add_f32 v[24:25], v[14:15], v[18:19]
	v_pk_add_f32 v[20:21], v[12:13], v[16:17] op_sel:[0,1] op_sel_hi:[1,0]
	v_pk_add_f32 v[12:13], v[12:13], v[16:17] op_sel:[0,1] op_sel_hi:[1,0] neg_lo:[0,1] neg_hi:[0,1]
	v_mov_b32_e32 v16, v20
	v_mov_b32_e32 v17, v13
	v_mov_b32_e32 v13, v21
	ds_write2st64_b64 v151, v[24:25], v[12:13] offset0:96 offset1:97
	v_pk_add_f32 v[12:13], v[14:15], v[18:19] neg_lo:[0,1] neg_hi:[0,1]
	ds_write2st64_b64 v151, v[12:13], v[16:17] offset0:98 offset1:99
	ds_read_b64 v[12:13], v152
	ds_read_b64 v[14:15], v153
	ds_read_b64 v[16:17], v155
	ds_read_b64 v[18:19], v156
	s_waitcnt lgkmcnt(2)
	v_pk_mul_f32 v[20:21], v[4:5], v[14:15] op_sel:[1,0]
	s_nop 0
	v_pk_fma_f32 v[22:23], v[0:1], v[14:15], v[20:21] op_sel:[0,0,1] op_sel_hi:[1,1,0]
	v_pk_fma_f32 v[14:15], v[0:1], v[14:15], v[20:21] op_sel:[0,0,1] op_sel_hi:[0,1,0] neg_lo:[0,0,1] neg_hi:[0,0,1]
	v_mov_b32_e32 v23, v15
	s_waitcnt lgkmcnt(1)
	v_pk_mul_f32 v[14:15], v[6:7], v[16:17] op_sel_hi:[0,1]
	v_pk_fma_f32 v[20:21], v[2:3], v[16:17], v[14:15] op_sel:[0,0,1] op_sel_hi:[1,1,0]
	v_pk_fma_f32 v[14:15], v[2:3], v[16:17], v[14:15] op_sel:[0,0,1] op_sel_hi:[0,1,0] neg_lo:[0,0,1] neg_hi:[0,0,1]
	v_mov_b32_e32 v21, v15
	s_waitcnt lgkmcnt(0)
	v_pk_mul_f32 v[14:15], v[10:11], v[18:19]
	s_nop 0
	v_pk_fma_f32 v[16:17], v[8:9], v[18:19], v[14:15] op_sel:[0,0,1] op_sel_hi:[1,1,0]
	v_pk_fma_f32 v[14:15], v[8:9], v[18:19], v[14:15] op_sel:[0,0,1] op_sel_hi:[1,1,0] neg_lo:[0,0,1] neg_hi:[0,0,1]
	s_nop 0
	v_mov_b32_e32 v17, v15
	v_pk_add_f32 v[14:15], v[12:13], v[20:21]
	v_pk_add_f32 v[18:19], v[22:23], v[16:17]
	v_pk_add_f32 v[12:13], v[12:13], v[20:21] neg_lo:[0,1] neg_hi:[0,1]
	v_pk_add_f32 v[16:17], v[22:23], v[16:17] neg_lo:[0,1] neg_hi:[0,1]
	v_pk_add_f32 v[24:25], v[14:15], v[18:19]
	v_pk_add_f32 v[20:21], v[12:13], v[16:17] op_sel:[0,1] op_sel_hi:[1,0]
	v_pk_add_f32 v[12:13], v[12:13], v[16:17] op_sel:[0,1] op_sel_hi:[1,0] neg_lo:[0,1] neg_hi:[0,1]
	v_mov_b32_e32 v16, v20
	v_mov_b32_e32 v17, v13
	v_mov_b32_e32 v13, v21
	ds_write_b64 v152, v[24:25]
	ds_write_b64 v153, v[12:13]
	v_pk_add_f32 v[12:13], v[14:15], v[18:19] neg_lo:[0,1] neg_hi:[0,1]
	ds_write_b64 v155, v[12:13]
	ds_write_b64 v156, v[16:17]
	ds_read_b64 v[12:13], v157
	ds_read_b64 v[14:15], v158
	ds_read_b64 v[16:17], v159
	ds_read_b64 v[18:19], v160
	s_waitcnt lgkmcnt(2)
	v_pk_mul_f32 v[20:21], v[4:5], v[14:15] op_sel:[1,0]
	s_nop 0
	v_pk_fma_f32 v[22:23], v[0:1], v[14:15], v[20:21] op_sel:[0,0,1] op_sel_hi:[1,1,0]
	v_pk_fma_f32 v[14:15], v[0:1], v[14:15], v[20:21] op_sel:[0,0,1] op_sel_hi:[0,1,0] neg_lo:[0,0,1] neg_hi:[0,0,1]
	v_mov_b32_e32 v23, v15
	s_waitcnt lgkmcnt(1)
	v_pk_mul_f32 v[14:15], v[6:7], v[16:17] op_sel_hi:[0,1]
	v_pk_fma_f32 v[20:21], v[2:3], v[16:17], v[14:15] op_sel:[0,0,1] op_sel_hi:[1,1,0]
	v_pk_fma_f32 v[14:15], v[2:3], v[16:17], v[14:15] op_sel:[0,0,1] op_sel_hi:[0,1,0] neg_lo:[0,0,1] neg_hi:[0,0,1]
	v_mov_b32_e32 v21, v15
	s_waitcnt lgkmcnt(0)
	v_pk_mul_f32 v[14:15], v[10:11], v[18:19]
	s_nop 0
	v_pk_fma_f32 v[16:17], v[8:9], v[18:19], v[14:15] op_sel:[0,0,1] op_sel_hi:[1,1,0]
	v_pk_fma_f32 v[14:15], v[8:9], v[18:19], v[14:15] op_sel:[0,0,1] op_sel_hi:[1,1,0] neg_lo:[0,0,1] neg_hi:[0,0,1]
	s_nop 0
	v_mov_b32_e32 v17, v15
	v_pk_add_f32 v[14:15], v[12:13], v[20:21]
	v_pk_add_f32 v[18:19], v[22:23], v[16:17]
	v_pk_add_f32 v[12:13], v[12:13], v[20:21] neg_lo:[0,1] neg_hi:[0,1]
	v_pk_add_f32 v[16:17], v[22:23], v[16:17] neg_lo:[0,1] neg_hi:[0,1]
	v_pk_add_f32 v[24:25], v[14:15], v[18:19]
	v_pk_add_f32 v[20:21], v[12:13], v[16:17] op_sel:[0,1] op_sel_hi:[1,0]
	v_pk_add_f32 v[12:13], v[12:13], v[16:17] op_sel:[0,1] op_sel_hi:[1,0] neg_lo:[0,1] neg_hi:[0,1]
	v_mov_b32_e32 v16, v20
	v_mov_b32_e32 v17, v13
	v_mov_b32_e32 v13, v21
	ds_write_b64 v157, v[24:25]
	ds_write_b64 v158, v[12:13]
	v_pk_add_f32 v[12:13], v[14:15], v[18:19] neg_lo:[0,1] neg_hi:[0,1]
	ds_write_b64 v159, v[12:13]
	ds_write_b64 v160, v[16:17]
	ds_read_b64 v[12:13], v161
	ds_read_b64 v[14:15], v162
	ds_read_b64 v[16:17], v163
	ds_read_b64 v[18:19], v164
	s_waitcnt lgkmcnt(2)
	v_pk_mul_f32 v[20:21], v[4:5], v[14:15] op_sel:[1,0]
	s_nop 0
	v_pk_fma_f32 v[22:23], v[0:1], v[14:15], v[20:21] op_sel:[0,0,1] op_sel_hi:[1,1,0]
	v_pk_fma_f32 v[14:15], v[0:1], v[14:15], v[20:21] op_sel:[0,0,1] op_sel_hi:[0,1,0] neg_lo:[0,0,1] neg_hi:[0,0,1]
	v_mov_b32_e32 v23, v15
	s_waitcnt lgkmcnt(1)
	v_pk_mul_f32 v[14:15], v[6:7], v[16:17] op_sel_hi:[0,1]
	v_pk_fma_f32 v[20:21], v[2:3], v[16:17], v[14:15] op_sel:[0,0,1] op_sel_hi:[1,1,0]
	v_pk_fma_f32 v[14:15], v[2:3], v[16:17], v[14:15] op_sel:[0,0,1] op_sel_hi:[0,1,0] neg_lo:[0,0,1] neg_hi:[0,0,1]
	v_mov_b32_e32 v21, v15
	s_waitcnt lgkmcnt(0)
; HD float2 cmul(float2 a, float2 b){ return make_float2(a.x*b.x - a.y*b.y, a.x*b.y + a.y*b.x); }
; HD float2 cmulc(float2 a, float2 b){ return make_float2(a.x*b.x + a.y*b.y, a.y*b.x - a.x*b.y); }
; template<bool INV, bool NOTW>
; HD void bf4c(float2* Z, int i0, int i1, int i2, int i3, float2 w1, float2 w2, float2 w3){
;   float2 a0=Z[i0], a1=Z[i1], a2=Z[i2], a3=Z[i3];
;   if (INV && !NOTW){ a1=cmulc(a1,w1); a2=cmulc(a2,w2); a3=cmulc(a3,w3); }
;   float2 s02=make_float2(a0.x+a2.x,a0.y+a2.y), d02=make_float2(a0.x-a2.x,a0.y-a2.y);
;   float2 s13=make_float2(a1.x+a3.x,a1.y+a3.y), d13=make_float2(a1.x-a3.x,a1.y-a3.y);
;   float2 y0=make_float2(s02.x+s13.x,s02.y+s13.y), y2=make_float2(s02.x-s13.x,s02.y-s13.y);
;   float2 ym=make_float2(d02.x+d13.y,d02.y-d13.x);
;   float2 yp=make_float2(d02.x-d13.y,d02.y+d13.x);
;   float2 y1, y3;
;   if (INV){ y1=yp; y3=ym; } else if (NOTW){ y1=ym; y3=yp; } else { y1=cmul(ym,w1); y2=cmul(y2,w2); y3=cmul(yp,w3); }
;   Z[i0]=y0; Z[i1]=y1; Z[i2]=y2; Z[i3]=y3;
; }
; template<bool INV, int LQ, bool BARRIER=true>
; HD void fft_pass(float2* Z, const float2* twA, const float2* twB, int tid){
;     ...
;     int j=tid&(q-1); int base0=((tid>>LQ)<<(LQ+2))+j;
;     float2 w1=make_float2(1.f,0.f), w2=w1, w3=w1;
;     if (LQ>0){ int k=j*tws; w1=cmul(twA[k>>6],twB[k&63]); w2=cmul(w1,w1); w3=cmul(w2,w1); }
;     _Pragma("unroll") for (int i=0;i<8;++i){ int base=base0+i*2048; bf4c<INV,(LQ==0)>(Z,base,base+q,base+2*q,base+3*q,w1,w2,w3); }
;   }
;   if (BARRIER) __syncthreads(); else asm volatile("s_waitcnt lgkmcnt(0)" ::: "memory");
	v_pk_mul_f32 v[14:15], v[10:11], v[18:19]
	s_nop 0
	v_pk_fma_f32 v[16:17], v[8:9], v[18:19], v[14:15] op_sel:[0,0,1] op_sel_hi:[1,1,0]
	v_pk_fma_f32 v[14:15], v[8:9], v[18:19], v[14:15] op_sel:[0,0,1] op_sel_hi:[1,1,0] neg_lo:[0,0,1] neg_hi:[0,0,1]
	s_nop 0
	v_mov_b32_e32 v17, v15
	v_pk_add_f32 v[14:15], v[12:13], v[20:21]
	v_pk_add_f32 v[18:19], v[22:23], v[16:17]
	v_pk_add_f32 v[12:13], v[12:13], v[20:21] neg_lo:[0,1] neg_hi:[0,1]
	v_pk_add_f32 v[16:17], v[22:23], v[16:17] neg_lo:[0,1] neg_hi:[0,1]
	v_pk_add_f32 v[24:25], v[14:15], v[18:19]
	v_pk_add_f32 v[20:21], v[12:13], v[16:17] op_sel:[0,1] op_sel_hi:[1,0]
	v_pk_add_f32 v[12:13], v[12:13], v[16:17] op_sel:[0,1] op_sel_hi:[1,0] neg_lo:[0,1] neg_hi:[0,1]
	v_mov_b32_e32 v16, v20
	v_mov_b32_e32 v17, v13
	v_mov_b32_e32 v13, v21
	ds_write_b64 v161, v[24:25]
	ds_write_b64 v162, v[12:13]
	v_pk_add_f32 v[12:13], v[14:15], v[18:19] neg_lo:[0,1] neg_hi:[0,1]
	ds_write_b64 v163, v[12:13]
	ds_write_b64 v164, v[16:17]
	ds_read_b64 v[12:13], v165
	ds_read_b64 v[14:15], v166
	ds_read_b64 v[16:17], v167
	ds_read_b64 v[18:19], v168
	s_waitcnt lgkmcnt(2)
	v_pk_mul_f32 v[4:5], v[4:5], v[14:15] op_sel:[1,0]
	s_nop 0
	v_pk_fma_f32 v[20:21], v[0:1], v[14:15], v[4:5] op_sel:[0,0,1] op_sel_hi:[1,1,0]
	v_pk_fma_f32 v[0:1], v[0:1], v[14:15], v[4:5] op_sel:[0,0,1] op_sel_hi:[0,1,0] neg_lo:[0,0,1] neg_hi:[0,0,1]
	v_mov_b32_e32 v21, v1
	s_waitcnt lgkmcnt(1)
	v_pk_mul_f32 v[0:1], v[6:7], v[16:17] op_sel_hi:[0,1]
	v_pk_fma_f32 v[4:5], v[2:3], v[16:17], v[0:1] op_sel:[0,0,1] op_sel_hi:[1,1,0]
	v_pk_fma_f32 v[0:1], v[2:3], v[16:17], v[0:1] op_sel:[0,0,1] op_sel_hi:[0,1,0] neg_lo:[0,0,1] neg_hi:[0,0,1]
	v_mov_b32_e32 v5, v1
	s_waitcnt lgkmcnt(0)
	v_pk_mul_f32 v[0:1], v[10:11], v[18:19]
	s_nop 0
	v_pk_fma_f32 v[2:3], v[8:9], v[18:19], v[0:1] op_sel:[0,0,1] op_sel_hi:[1,1,0]
	v_pk_fma_f32 v[0:1], v[8:9], v[18:19], v[0:1] op_sel:[0,0,1] op_sel_hi:[1,1,0] neg_lo:[0,0,1] neg_hi:[0,0,1]
	s_nop 0
	v_mov_b32_e32 v3, v1
	v_pk_add_f32 v[0:1], v[12:13], v[4:5]
	v_pk_add_f32 v[6:7], v[20:21], v[2:3]
	v_pk_add_f32 v[4:5], v[12:13], v[4:5] neg_lo:[0,1] neg_hi:[0,1]
	v_pk_add_f32 v[2:3], v[20:21], v[2:3] neg_lo:[0,1] neg_hi:[0,1]
	v_pk_add_f32 v[8:9], v[0:1], v[6:7]
	v_pk_add_f32 v[10:11], v[4:5], v[2:3] op_sel:[0,1] op_sel_hi:[1,0]
	v_pk_add_f32 v[2:3], v[4:5], v[2:3] op_sel:[0,1] op_sel_hi:[1,0] neg_lo:[0,1] neg_hi:[0,1]
	v_pk_add_f32 v[0:1], v[0:1], v[6:7] neg_lo:[0,1] neg_hi:[0,1]
	v_mov_b32_e32 v5, v3
	v_mov_b32_e32 v3, v11
	v_mov_b32_e32 v4, v10
	ds_write_b64 v165, v[8:9]
	ds_write_b64 v166, v[2:3]
	ds_write_b64 v167, v[0:1]
	ds_write_b64 v168, v[4:5]
	s_waitcnt lgkmcnt(0)
	s_barrier
	ds_read_b64 v[0:1], v121
	ds_read_b64 v[2:3], v122
	s_waitcnt lgkmcnt(0)
	v_pk_mul_f32 v[4:5], v[0:1], v[2:3]
	v_pk_mul_f32 v[2:3], v[0:1], v[2:3] op_sel:[1,0] op_sel_hi:[0,1]
	v_mov_b32_e32 v6, v4
	v_mov_b32_e32 v7, v2
	v_mov_b32_e32 v2, v5
	v_pk_add_f32 v[0:1], v[6:7], v[2:3] neg_lo:[0,1] neg_hi:[0,1]
	v_pk_add_f32 v[4:5], v[6:7], v[2:3]
	v_mov_b32_e32 v8, v0
	v_mov_b32_e32 v9, v5
	v_mul_f32_e32 v2, v5, v5
	v_pk_mul_f32 v[6:7], v[8:9], v[4:5] op_sel:[0,1] op_sel_hi:[1,0]
	v_pk_fma_f32 v[2:3], v[8:9], v[8:9], v[2:3] op_sel_hi:[1,1,0] neg_lo:[0,0,1] neg_hi:[0,0,1]
	v_pk_add_f32 v[6:7], v[6:7], v[6:7]
	v_mov_b32_e32 v10, v2
	v_mov_b32_e32 v11, v6
	v_pk_mul_f32 v[8:9], v[8:9], v[10:11]
	v_pk_mov_b32 v[10:11], v[4:5], v[6:7] op_sel:[1,0]
	v_mov_b32_e32 v12, v2
	v_mov_b32_e32 v13, v0
	v_pk_mul_f32 v[10:11], v[10:11], v[12:13]
	ds_read2st64_b64 v[12:15], v123 offset1:4
	ds_read2st64_b64 v[16:19], v123 offset0:8 offset1:12
	v_pk_add_f32 v[10:11], v[10:11], v[10:11] op_sel:[0,1] op_sel_hi:[0,1]
	v_pk_add_f32 v[8:9], v[8:9], v[8:9] op_sel:[0,1] op_sel_hi:[0,1] neg_lo:[0,1] neg_hi:[0,1]
	s_waitcnt lgkmcnt(1)
	v_pk_mul_f32 v[20:21], v[4:5], v[14:15] op_sel:[1,0]
	s_nop 0
	v_pk_fma_f32 v[22:23], v[0:1], v[14:15], v[20:21] op_sel:[0,0,1] op_sel_hi:[1,1,0]
	v_pk_fma_f32 v[14:15], v[0:1], v[14:15], v[20:21] op_sel:[0,0,1] op_sel_hi:[0,1,0] neg_lo:[0,0,1] neg_hi:[0,0,1]
	v_mov_b32_e32 v23, v15
	s_waitcnt lgkmcnt(0)
	v_pk_mul_f32 v[14:15], v[6:7], v[16:17] op_sel_hi:[0,1]
	v_pk_fma_f32 v[20:21], v[2:3], v[16:17], v[14:15] op_sel:[0,0,1] op_sel_hi:[1,1,0]
	v_pk_fma_f32 v[14:15], v[2:3], v[16:17], v[14:15] op_sel:[0,0,1] op_sel_hi:[0,1,0] neg_lo:[0,0,1] neg_hi:[0,0,1]
	v_mov_b32_e32 v21, v15
	v_pk_mul_f32 v[14:15], v[10:11], v[18:19]
	s_nop 0
	v_pk_fma_f32 v[16:17], v[8:9], v[18:19], v[14:15] op_sel:[0,0,1] op_sel_hi:[1,1,0]
	v_pk_fma_f32 v[14:15], v[8:9], v[18:19], v[14:15] op_sel:[0,0,1] op_sel_hi:[1,1,0] neg_lo:[0,0,1] neg_hi:[0,0,1]
	s_nop 0
	v_mov_b32_e32 v17, v15
	v_pk_add_f32 v[14:15], v[12:13], v[20:21]
	v_pk_add_f32 v[18:19], v[22:23], v[16:17]
	v_pk_add_f32 v[12:13], v[12:13], v[20:21] neg_lo:[0,1] neg_hi:[0,1]
	v_pk_add_f32 v[16:17], v[22:23], v[16:17] neg_lo:[0,1] neg_hi:[0,1]
	v_pk_add_f32 v[24:25], v[14:15], v[18:19]
	v_pk_add_f32 v[20:21], v[12:13], v[16:17] op_sel:[0,1] op_sel_hi:[1,0]
	v_pk_add_f32 v[12:13], v[12:13], v[16:17] op_sel:[0,1] op_sel_hi:[1,0] neg_lo:[0,1] neg_hi:[0,1]
	v_mov_b32_e32 v16, v20
	v_mov_b32_e32 v17, v13
	v_mov_b32_e32 v13, v21
	ds_write2st64_b64 v123, v[24:25], v[12:13] offset1:4
	v_pk_add_f32 v[12:13], v[14:15], v[18:19] neg_lo:[0,1] neg_hi:[0,1]
	ds_write2st64_b64 v123, v[12:13], v[16:17] offset0:8 offset1:12
	ds_read2st64_b64 v[12:15], v123 offset0:32 offset1:36
	ds_read2st64_b64 v[16:19], v123 offset0:40 offset1:44
	s_waitcnt lgkmcnt(1)
	v_pk_mul_f32 v[20:21], v[4:5], v[14:15] op_sel:[1,0]
	s_nop 0
	v_pk_fma_f32 v[22:23], v[0:1], v[14:15], v[20:21] op_sel:[0,0,1] op_sel_hi:[1,1,0]
	v_pk_fma_f32 v[14:15], v[0:1], v[14:15], v[20:21] op_sel:[0,0,1] op_sel_hi:[0,1,0] neg_lo:[0,0,1] neg_hi:[0,0,1]
	v_mov_b32_e32 v23, v15
	s_waitcnt lgkmcnt(0)
; HD float2 cmul(float2 a, float2 b){ return make_float2(a.x*b.x - a.y*b.y, a.x*b.y + a.y*b.x); }
; HD float2 cmulc(float2 a, float2 b){ return make_float2(a.x*b.x + a.y*b.y, a.y*b.x - a.x*b.y); }
; template<bool INV, bool NOTW>
; HD void bf4c(float2* Z, int i0, int i1, int i2, int i3, float2 w1, float2 w2, float2 w3){
;   float2 a0=Z[i0], a1=Z[i1], a2=Z[i2], a3=Z[i3];
;   if (INV && !NOTW){ a1=cmulc(a1,w1); a2=cmulc(a2,w2); a3=cmulc(a3,w3); }
;   float2 s02=make_float2(a0.x+a2.x,a0.y+a2.y), d02=make_float2(a0.x-a2.x,a0.y-a2.y);
;   float2 s13=make_float2(a1.x+a3.x,a1.y+a3.y), d13=make_float2(a1.x-a3.x,a1.y-a3.y);
;   float2 y0=make_float2(s02.x+s13.x,s02.y+s13.y), y2=make_float2(s02.x-s13.x,s02.y-s13.y);
;   float2 ym=make_float2(d02.x+d13.y,d02.y-d13.x);
;   float2 yp=make_float2(d02.x-d13.y,d02.y+d13.x);
;   float2 y1, y3;
;   if (INV){ y1=yp; y3=ym; } else if (NOTW){ y1=ym; y3=yp; } else { y1=cmul(ym,w1); y2=cmul(y2,w2); y3=cmul(yp,w3); }
;   Z[i0]=y0; Z[i1]=y1; Z[i2]=y2; Z[i3]=y3;
; }
; template<bool INV, int LQ, bool BARRIER=true>
; HD void fft_pass(float2* Z, const float2* twA, const float2* twB, int tid){
;     ...
;     int j=tid&(q-1); int base0=((tid>>LQ)<<(LQ+2))+j;
;     float2 w1=make_float2(1.f,0.f), w2=w1, w3=w1;
;     if (LQ>0){ int k=j*tws; w1=cmul(twA[k>>6],twB[k&63]); w2=cmul(w1,w1); w3=cmul(w2,w1); }
;     _Pragma("unroll") for (int i=0;i<8;++i){ int base=base0+i*2048; bf4c<INV,(LQ==0)>(Z,base,base+q,base+2*q,base+3*q,w1,w2,w3); }
	v_pk_mul_f32 v[14:15], v[6:7], v[16:17] op_sel_hi:[0,1]
	v_pk_fma_f32 v[20:21], v[2:3], v[16:17], v[14:15] op_sel:[0,0,1] op_sel_hi:[1,1,0]
	v_pk_fma_f32 v[14:15], v[2:3], v[16:17], v[14:15] op_sel:[0,0,1] op_sel_hi:[0,1,0] neg_lo:[0,0,1] neg_hi:[0,0,1]
	v_mov_b32_e32 v21, v15
	v_pk_mul_f32 v[14:15], v[10:11], v[18:19]
	s_nop 0
	v_pk_fma_f32 v[16:17], v[8:9], v[18:19], v[14:15] op_sel:[0,0,1] op_sel_hi:[1,1,0]
	v_pk_fma_f32 v[14:15], v[8:9], v[18:19], v[14:15] op_sel:[0,0,1] op_sel_hi:[1,1,0] neg_lo:[0,0,1] neg_hi:[0,0,1]
	s_nop 0
	v_mov_b32_e32 v17, v15
	v_pk_add_f32 v[14:15], v[12:13], v[20:21]
	v_pk_add_f32 v[18:19], v[22:23], v[16:17]
	v_pk_add_f32 v[12:13], v[12:13], v[20:21] neg_lo:[0,1] neg_hi:[0,1]
	v_pk_add_f32 v[16:17], v[22:23], v[16:17] neg_lo:[0,1] neg_hi:[0,1]
	v_pk_add_f32 v[24:25], v[14:15], v[18:19]
	v_pk_add_f32 v[20:21], v[12:13], v[16:17] op_sel:[0,1] op_sel_hi:[1,0]
	v_pk_add_f32 v[12:13], v[12:13], v[16:17] op_sel:[0,1] op_sel_hi:[1,0] neg_lo:[0,1] neg_hi:[0,1]
	v_mov_b32_e32 v16, v20
	v_mov_b32_e32 v17, v13
	v_mov_b32_e32 v13, v21
	ds_write2st64_b64 v123, v[24:25], v[12:13] offset0:32 offset1:36
	v_pk_add_f32 v[12:13], v[14:15], v[18:19] neg_lo:[0,1] neg_hi:[0,1]
	ds_write2st64_b64 v123, v[12:13], v[16:17] offset0:40 offset1:44
	ds_read2st64_b64 v[12:15], v123 offset0:64 offset1:68
	ds_read2st64_b64 v[16:19], v123 offset0:72 offset1:76
	s_waitcnt lgkmcnt(1)
	v_pk_mul_f32 v[20:21], v[4:5], v[14:15] op_sel:[1,0]
	s_nop 0
	v_pk_fma_f32 v[22:23], v[0:1], v[14:15], v[20:21] op_sel:[0,0,1] op_sel_hi:[1,1,0]
	v_pk_fma_f32 v[14:15], v[0:1], v[14:15], v[20:21] op_sel:[0,0,1] op_sel_hi:[0,1,0] neg_lo:[0,0,1] neg_hi:[0,0,1]
	v_mov_b32_e32 v23, v15
	s_waitcnt lgkmcnt(0)
	v_pk_mul_f32 v[14:15], v[6:7], v[16:17] op_sel_hi:[0,1]
	v_pk_fma_f32 v[20:21], v[2:3], v[16:17], v[14:15] op_sel:[0,0,1] op_sel_hi:[1,1,0]
	v_pk_fma_f32 v[14:15], v[2:3], v[16:17], v[14:15] op_sel:[0,0,1] op_sel_hi:[0,1,0] neg_lo:[0,0,1] neg_hi:[0,0,1]
	v_mov_b32_e32 v21, v15
	v_pk_mul_f32 v[14:15], v[10:11], v[18:19]
	s_nop 0
	v_pk_fma_f32 v[16:17], v[8:9], v[18:19], v[14:15] op_sel:[0,0,1] op_sel_hi:[1,1,0]
	v_pk_fma_f32 v[14:15], v[8:9], v[18:19], v[14:15] op_sel:[0,0,1] op_sel_hi:[1,1,0] neg_lo:[0,0,1] neg_hi:[0,0,1]
	s_nop 0
	v_mov_b32_e32 v17, v15
	v_pk_add_f32 v[14:15], v[12:13], v[20:21]
	v_pk_add_f32 v[18:19], v[22:23], v[16:17]
	v_pk_add_f32 v[12:13], v[12:13], v[20:21] neg_lo:[0,1] neg_hi:[0,1]
	v_pk_add_f32 v[16:17], v[22:23], v[16:17] neg_lo:[0,1] neg_hi:[0,1]
	v_pk_add_f32 v[24:25], v[14:15], v[18:19]
	v_pk_add_f32 v[20:21], v[12:13], v[16:17] op_sel:[0,1] op_sel_hi:[1,0]
	v_pk_add_f32 v[12:13], v[12:13], v[16:17] op_sel:[0,1] op_sel_hi:[1,0] neg_lo:[0,1] neg_hi:[0,1]
	v_mov_b32_e32 v16, v20
	v_mov_b32_e32 v17, v13
	v_mov_b32_e32 v13, v21
	ds_write2st64_b64 v123, v[24:25], v[12:13] offset0:64 offset1:68
	v_pk_add_f32 v[12:13], v[14:15], v[18:19] neg_lo:[0,1] neg_hi:[0,1]
	ds_write2st64_b64 v123, v[12:13], v[16:17] offset0:72 offset1:76
	ds_read2st64_b64 v[12:15], v123 offset0:96 offset1:100
	ds_read2st64_b64 v[16:19], v123 offset0:104 offset1:108
	s_waitcnt lgkmcnt(1)
	v_pk_mul_f32 v[20:21], v[4:5], v[14:15] op_sel:[1,0]
	s_nop 0
	v_pk_fma_f32 v[22:23], v[0:1], v[14:15], v[20:21] op_sel:[0,0,1] op_sel_hi:[1,1,0]
	v_pk_fma_f32 v[14:15], v[0:1], v[14:15], v[20:21] op_sel:[0,0,1] op_sel_hi:[0,1,0] neg_lo:[0,0,1] neg_hi:[0,0,1]
	v_mov_b32_e32 v23, v15
	s_waitcnt lgkmcnt(0)
	v_pk_mul_f32 v[14:15], v[6:7], v[16:17] op_sel_hi:[0,1]
	v_pk_fma_f32 v[20:21], v[2:3], v[16:17], v[14:15] op_sel:[0,0,1] op_sel_hi:[1,1,0]
	v_pk_fma_f32 v[14:15], v[2:3], v[16:17], v[14:15] op_sel:[0,0,1] op_sel_hi:[0,1,0] neg_lo:[0,0,1] neg_hi:[0,0,1]
	v_mov_b32_e32 v21, v15
	v_pk_mul_f32 v[14:15], v[10:11], v[18:19]
	s_nop 0
	v_pk_fma_f32 v[16:17], v[8:9], v[18:19], v[14:15] op_sel:[0,0,1] op_sel_hi:[1,1,0]
	v_pk_fma_f32 v[14:15], v[8:9], v[18:19], v[14:15] op_sel:[0,0,1] op_sel_hi:[1,1,0] neg_lo:[0,0,1] neg_hi:[0,0,1]
	s_nop 0
	v_mov_b32_e32 v17, v15
	v_pk_add_f32 v[14:15], v[12:13], v[20:21]
	v_pk_add_f32 v[18:19], v[22:23], v[16:17]
	v_pk_add_f32 v[12:13], v[12:13], v[20:21] neg_lo:[0,1] neg_hi:[0,1]
	v_pk_add_f32 v[16:17], v[22:23], v[16:17] neg_lo:[0,1] neg_hi:[0,1]
	v_pk_add_f32 v[24:25], v[14:15], v[18:19]
	v_pk_add_f32 v[20:21], v[12:13], v[16:17] op_sel:[0,1] op_sel_hi:[1,0]
	v_pk_add_f32 v[12:13], v[12:13], v[16:17] op_sel:[0,1] op_sel_hi:[1,0] neg_lo:[0,1] neg_hi:[0,1]
	v_mov_b32_e32 v16, v20
	v_mov_b32_e32 v17, v13
	v_mov_b32_e32 v13, v21
	ds_write2st64_b64 v123, v[24:25], v[12:13] offset0:96 offset1:100
	v_pk_add_f32 v[12:13], v[14:15], v[18:19] neg_lo:[0,1] neg_hi:[0,1]
	ds_write2st64_b64 v123, v[12:13], v[16:17] offset0:104 offset1:108
	ds_read_b64 v[12:13], v124
	ds_read_b64 v[14:15], v125
	ds_read_b64 v[16:17], v126
	ds_read_b64 v[18:19], v127
	s_waitcnt lgkmcnt(2)
	v_pk_mul_f32 v[20:21], v[4:5], v[14:15] op_sel:[1,0]
	s_nop 0
	v_pk_fma_f32 v[22:23], v[0:1], v[14:15], v[20:21] op_sel:[0,0,1] op_sel_hi:[1,1,0]
	v_pk_fma_f32 v[14:15], v[0:1], v[14:15], v[20:21] op_sel:[0,0,1] op_sel_hi:[0,1,0] neg_lo:[0,0,1] neg_hi:[0,0,1]
	v_mov_b32_e32 v23, v15
	s_waitcnt lgkmcnt(1)
	v_pk_mul_f32 v[14:15], v[6:7], v[16:17] op_sel_hi:[0,1]
	v_pk_fma_f32 v[20:21], v[2:3], v[16:17], v[14:15] op_sel:[0,0,1] op_sel_hi:[1,1,0]
	v_pk_fma_f32 v[14:15], v[2:3], v[16:17], v[14:15] op_sel:[0,0,1] op_sel_hi:[0,1,0] neg_lo:[0,0,1] neg_hi:[0,0,1]
	v_mov_b32_e32 v21, v15
	s_waitcnt lgkmcnt(0)
; HD float2 cmul(float2 a, float2 b){ return make_float2(a.x*b.x - a.y*b.y, a.x*b.y + a.y*b.x); }
; HD float2 cmulc(float2 a, float2 b){ return make_float2(a.x*b.x + a.y*b.y, a.y*b.x - a.x*b.y); }
; template<bool INV, bool NOTW>
; HD void bf4c(float2* Z, int i0, int i1, int i2, int i3, float2 w1, float2 w2, float2 w3){
;   float2 a0=Z[i0], a1=Z[i1], a2=Z[i2], a3=Z[i3];
;   if (INV && !NOTW){ a1=cmulc(a1,w1); a2=cmulc(a2,w2); a3=cmulc(a3,w3); }
;   float2 s02=make_float2(a0.x+a2.x,a0.y+a2.y), d02=make_float2(a0.x-a2.x,a0.y-a2.y);
;   float2 s13=make_float2(a1.x+a3.x,a1.y+a3.y), d13=make_float2(a1.x-a3.x,a1.y-a3.y);
;   float2 y0=make_float2(s02.x+s13.x,s02.y+s13.y), y2=make_float2(s02.x-s13.x,s02.y-s13.y);
;   float2 ym=make_float2(d02.x+d13.y,d02.y-d13.x);
;   float2 yp=make_float2(d02.x-d13.y,d02.y+d13.x);
;   float2 y1, y3;
;   if (INV){ y1=yp; y3=ym; } else if (NOTW){ y1=ym; y3=yp; } else { y1=cmul(ym,w1); y2=cmul(y2,w2); y3=cmul(yp,w3); }
;   Z[i0]=y0; Z[i1]=y1; Z[i2]=y2; Z[i3]=y3;
; }
; template<bool INV, int LQ, bool BARRIER=true>
; HD void fft_pass(float2* Z, const float2* twA, const float2* twB, int tid){
;     ...
;     int j=tid&(q-1); int base0=((tid>>LQ)<<(LQ+2))+j;
;     float2 w1=make_float2(1.f,0.f), w2=w1, w3=w1;
;     if (LQ>0){ int k=j*tws; w1=cmul(twA[k>>6],twB[k&63]); w2=cmul(w1,w1); w3=cmul(w2,w1); }
;     _Pragma("unroll") for (int i=0;i<8;++i){ int base=base0+i*2048; bf4c<INV,(LQ==0)>(Z,base,base+q,base+2*q,base+3*q,w1,w2,w3); }
;   }
;   if (BARRIER) __syncthreads(); else asm volatile("s_waitcnt lgkmcnt(0)" ::: "memory");
	v_pk_mul_f32 v[14:15], v[10:11], v[18:19]
	s_nop 0
	v_pk_fma_f32 v[16:17], v[8:9], v[18:19], v[14:15] op_sel:[0,0,1] op_sel_hi:[1,1,0]
	v_pk_fma_f32 v[14:15], v[8:9], v[18:19], v[14:15] op_sel:[0,0,1] op_sel_hi:[1,1,0] neg_lo:[0,0,1] neg_hi:[0,0,1]
	s_nop 0
	v_mov_b32_e32 v17, v15
	v_pk_add_f32 v[14:15], v[12:13], v[20:21]
	v_pk_add_f32 v[18:19], v[22:23], v[16:17]
	v_pk_add_f32 v[12:13], v[12:13], v[20:21] neg_lo:[0,1] neg_hi:[0,1]
	v_pk_add_f32 v[16:17], v[22:23], v[16:17] neg_lo:[0,1] neg_hi:[0,1]
	v_pk_add_f32 v[24:25], v[14:15], v[18:19]
	v_pk_add_f32 v[20:21], v[12:13], v[16:17] op_sel:[0,1] op_sel_hi:[1,0]
	v_pk_add_f32 v[12:13], v[12:13], v[16:17] op_sel:[0,1] op_sel_hi:[1,0] neg_lo:[0,1] neg_hi:[0,1]
	v_mov_b32_e32 v16, v20
	v_mov_b32_e32 v17, v13
	v_mov_b32_e32 v13, v21
	ds_write_b64 v124, v[24:25]
	ds_write_b64 v125, v[12:13]
	v_pk_add_f32 v[12:13], v[14:15], v[18:19] neg_lo:[0,1] neg_hi:[0,1]
	ds_write_b64 v126, v[12:13]
	ds_write_b64 v127, v[16:17]
	ds_read_b64 v[12:13], v134
	ds_read_b64 v[14:15], v135
	ds_read_b64 v[16:17], v136
	ds_read_b64 v[18:19], v137
	s_waitcnt lgkmcnt(2)
	v_pk_mul_f32 v[20:21], v[4:5], v[14:15] op_sel:[1,0]
	s_nop 0
	v_pk_fma_f32 v[22:23], v[0:1], v[14:15], v[20:21] op_sel:[0,0,1] op_sel_hi:[1,1,0]
	v_pk_fma_f32 v[14:15], v[0:1], v[14:15], v[20:21] op_sel:[0,0,1] op_sel_hi:[0,1,0] neg_lo:[0,0,1] neg_hi:[0,0,1]
	v_mov_b32_e32 v23, v15
	s_waitcnt lgkmcnt(1)
	v_pk_mul_f32 v[14:15], v[6:7], v[16:17] op_sel_hi:[0,1]
	v_pk_fma_f32 v[20:21], v[2:3], v[16:17], v[14:15] op_sel:[0,0,1] op_sel_hi:[1,1,0]
	v_pk_fma_f32 v[14:15], v[2:3], v[16:17], v[14:15] op_sel:[0,0,1] op_sel_hi:[0,1,0] neg_lo:[0,0,1] neg_hi:[0,0,1]
	v_mov_b32_e32 v21, v15
	s_waitcnt lgkmcnt(0)
	v_pk_mul_f32 v[14:15], v[10:11], v[18:19]
	s_nop 0
	v_pk_fma_f32 v[16:17], v[8:9], v[18:19], v[14:15] op_sel:[0,0,1] op_sel_hi:[1,1,0]
	v_pk_fma_f32 v[14:15], v[8:9], v[18:19], v[14:15] op_sel:[0,0,1] op_sel_hi:[1,1,0] neg_lo:[0,0,1] neg_hi:[0,0,1]
	s_nop 0
	v_mov_b32_e32 v17, v15
	v_pk_add_f32 v[14:15], v[12:13], v[20:21]
	v_pk_add_f32 v[18:19], v[22:23], v[16:17]
	v_pk_add_f32 v[12:13], v[12:13], v[20:21] neg_lo:[0,1] neg_hi:[0,1]
	v_pk_add_f32 v[16:17], v[22:23], v[16:17] neg_lo:[0,1] neg_hi:[0,1]
	v_pk_add_f32 v[24:25], v[14:15], v[18:19]
	v_pk_add_f32 v[20:21], v[12:13], v[16:17] op_sel:[0,1] op_sel_hi:[1,0]
	v_pk_add_f32 v[12:13], v[12:13], v[16:17] op_sel:[0,1] op_sel_hi:[1,0] neg_lo:[0,1] neg_hi:[0,1]
	v_mov_b32_e32 v16, v20
	v_mov_b32_e32 v17, v13
	v_mov_b32_e32 v13, v21
	ds_write_b64 v134, v[24:25]
	ds_write_b64 v135, v[12:13]
	v_pk_add_f32 v[12:13], v[14:15], v[18:19] neg_lo:[0,1] neg_hi:[0,1]
	ds_write_b64 v136, v[12:13]
	ds_write_b64 v137, v[16:17]
	ds_read_b64 v[12:13], v138
	ds_read_b64 v[14:15], v139
	ds_read_b64 v[16:17], v140
	ds_read_b64 v[18:19], v141
	s_waitcnt lgkmcnt(2)
	v_pk_mul_f32 v[20:21], v[4:5], v[14:15] op_sel:[1,0]
	s_nop 0
	v_pk_fma_f32 v[22:23], v[0:1], v[14:15], v[20:21] op_sel:[0,0,1] op_sel_hi:[1,1,0]
	v_pk_fma_f32 v[14:15], v[0:1], v[14:15], v[20:21] op_sel:[0,0,1] op_sel_hi:[0,1,0] neg_lo:[0,0,1] neg_hi:[0,0,1]
	v_mov_b32_e32 v23, v15
	s_waitcnt lgkmcnt(1)
	v_pk_mul_f32 v[14:15], v[6:7], v[16:17] op_sel_hi:[0,1]
	v_pk_fma_f32 v[20:21], v[2:3], v[16:17], v[14:15] op_sel:[0,0,1] op_sel_hi:[1,1,0]
	v_pk_fma_f32 v[14:15], v[2:3], v[16:17], v[14:15] op_sel:[0,0,1] op_sel_hi:[0,1,0] neg_lo:[0,0,1] neg_hi:[0,0,1]
	v_mov_b32_e32 v21, v15
	s_waitcnt lgkmcnt(0)
	v_pk_mul_f32 v[14:15], v[10:11], v[18:19]
	s_nop 0
	v_pk_fma_f32 v[16:17], v[8:9], v[18:19], v[14:15] op_sel:[0,0,1] op_sel_hi:[1,1,0]
	v_pk_fma_f32 v[14:15], v[8:9], v[18:19], v[14:15] op_sel:[0,0,1] op_sel_hi:[1,1,0] neg_lo:[0,0,1] neg_hi:[0,0,1]
	s_nop 0
	v_mov_b32_e32 v17, v15
	v_pk_add_f32 v[14:15], v[12:13], v[20:21]
	v_pk_add_f32 v[18:19], v[22:23], v[16:17]
	v_pk_add_f32 v[12:13], v[12:13], v[20:21] neg_lo:[0,1] neg_hi:[0,1]
	v_pk_add_f32 v[16:17], v[22:23], v[16:17] neg_lo:[0,1] neg_hi:[0,1]
	v_pk_add_f32 v[24:25], v[14:15], v[18:19]
	v_pk_add_f32 v[20:21], v[12:13], v[16:17] op_sel:[0,1] op_sel_hi:[1,0]
	v_pk_add_f32 v[12:13], v[12:13], v[16:17] op_sel:[0,1] op_sel_hi:[1,0] neg_lo:[0,1] neg_hi:[0,1]
	v_mov_b32_e32 v16, v20
	v_mov_b32_e32 v17, v13
	v_mov_b32_e32 v13, v21
	ds_write_b64 v138, v[24:25]
	ds_write_b64 v139, v[12:13]
	v_pk_add_f32 v[12:13], v[14:15], v[18:19] neg_lo:[0,1] neg_hi:[0,1]
	ds_write_b64 v140, v[12:13]
	ds_write_b64 v141, v[16:17]
	ds_read_b64 v[12:13], v142
	ds_read_b64 v[14:15], v143
	ds_read_b64 v[16:17], v144
	ds_read_b64 v[18:19], v145
	s_waitcnt lgkmcnt(2)
	v_pk_mul_f32 v[4:5], v[4:5], v[14:15] op_sel:[1,0]
	s_nop 0
	v_pk_fma_f32 v[20:21], v[0:1], v[14:15], v[4:5] op_sel:[0,0,1] op_sel_hi:[1,1,0]
	v_pk_fma_f32 v[0:1], v[0:1], v[14:15], v[4:5] op_sel:[0,0,1] op_sel_hi:[0,1,0] neg_lo:[0,0,1] neg_hi:[0,0,1]
	v_mov_b32_e32 v21, v1
	s_waitcnt lgkmcnt(1)
	v_pk_mul_f32 v[0:1], v[6:7], v[16:17] op_sel_hi:[0,1]
	v_pk_fma_f32 v[4:5], v[2:3], v[16:17], v[0:1] op_sel:[0,0,1] op_sel_hi:[1,1,0]
	v_pk_fma_f32 v[0:1], v[2:3], v[16:17], v[0:1] op_sel:[0,0,1] op_sel_hi:[0,1,0] neg_lo:[0,0,1] neg_hi:[0,0,1]
	v_mov_b32_e32 v5, v1
	s_waitcnt lgkmcnt(0)
	v_pk_mul_f32 v[0:1], v[10:11], v[18:19]
	s_nop 0
	v_pk_fma_f32 v[2:3], v[8:9], v[18:19], v[0:1] op_sel:[0,0,1] op_sel_hi:[1,1,0]
	v_pk_fma_f32 v[0:1], v[8:9], v[18:19], v[0:1] op_sel:[0,0,1] op_sel_hi:[1,1,0] neg_lo:[0,0,1] neg_hi:[0,0,1]
	s_nop 0
	v_mov_b32_e32 v3, v1
	v_pk_add_f32 v[0:1], v[12:13], v[4:5]
	v_pk_add_f32 v[6:7], v[20:21], v[2:3]
	v_pk_add_f32 v[4:5], v[12:13], v[4:5] neg_lo:[0,1] neg_hi:[0,1]
	v_pk_add_f32 v[2:3], v[20:21], v[2:3] neg_lo:[0,1] neg_hi:[0,1]
	v_pk_add_f32 v[8:9], v[0:1], v[6:7]
	v_pk_add_f32 v[10:11], v[4:5], v[2:3] op_sel:[0,1] op_sel_hi:[1,0]
	v_pk_add_f32 v[2:3], v[4:5], v[2:3] op_sel:[0,1] op_sel_hi:[1,0] neg_lo:[0,1] neg_hi:[0,1]
	v_pk_add_f32 v[0:1], v[0:1], v[6:7] neg_lo:[0,1] neg_hi:[0,1]
	v_mov_b32_e32 v5, v3
	v_mov_b32_e32 v3, v11
	v_mov_b32_e32 v4, v10
	ds_write_b64 v142, v[8:9]
	ds_write_b64 v143, v[2:3]
	ds_write_b64 v144, v[0:1]
	ds_write_b64 v145, v[4:5]
	s_waitcnt lgkmcnt(0)
	s_barrier
; HD float2 cmul(float2 a, float2 b){ return make_float2(a.x*b.x - a.y*b.y, a.x*b.y + a.y*b.x); }
; HD float2 cmulc(float2 a, float2 b){ return make_float2(a.x*b.x + a.y*b.y, a.y*b.x - a.x*b.y); }
; template<bool INV, bool NOTW>
; HD void bf4c(float2* Z, int i0, int i1, int i2, int i3, float2 w1, float2 w2, float2 w3){
;   float2 a0=Z[i0], a1=Z[i1], a2=Z[i2], a3=Z[i3];
;   if (INV && !NOTW){ a1=cmulc(a1,w1); a2=cmulc(a2,w2); a3=cmulc(a3,w3); }
;   float2 s02=make_float2(a0.x+a2.x,a0.y+a2.y), d02=make_float2(a0.x-a2.x,a0.y-a2.y);
;   float2 s13=make_float2(a1.x+a3.x,a1.y+a3.y), d13=make_float2(a1.x-a3.x,a1.y-a3.y);
;   float2 y0=make_float2(s02.x+s13.x,s02.y+s13.y), y2=make_float2(s02.x-s13.x,s02.y-s13.y);
;   float2 ym=make_float2(d02.x+d13.y,d02.y-d13.x);
;   float2 yp=make_float2(d02.x-d13.y,d02.y+d13.x);
;   float2 y1, y3;
;   if (INV){ y1=yp; y3=ym; } else if (NOTW){ y1=ym; y3=yp; } else { y1=cmul(ym,w1); y2=cmul(y2,w2); y3=cmul(yp,w3); }
;   Z[i0]=y0; Z[i1]=y1; Z[i2]=y2; Z[i3]=y3;
; }
; template<bool INV, int LQ, bool BARRIER=true>
; HD void fft_pass(float2* Z, const float2* twA, const float2* twB, int tid){
;     ...
;     _Pragma("unroll") for (int e=0;e<2;++e){ int j=tid+512*e; int k=j*tws;
;       float2 w1=cmul(twA[k>>6],twB[k&63]), w2=cmul(w1,w1), w3=cmul(w2,w1);
;       _Pragma("unroll") for (int ip=0;ip<4;++ip){ int base=ip*4096+j; bf4c<INV,false>(Z,base,base+q,base+2*q,base+3*q,w1,w2,w3); } }
	ds_read_b64 v[0:1], v100
	ds_read_b64 v[2:3], v101
	s_waitcnt lgkmcnt(0)
	v_pk_mul_f32 v[4:5], v[0:1], v[2:3]
	v_pk_mul_f32 v[0:1], v[0:1], v[2:3] op_sel:[1,0] op_sel_hi:[0,1]
	v_mov_b32_e32 v2, v4
	v_mov_b32_e32 v3, v0
	v_mov_b32_e32 v0, v5
	v_pk_add_f32 v[28:29], v[2:3], v[0:1] neg_lo:[0,1] neg_hi:[0,1]
	v_pk_add_f32 v[80:81], v[2:3], v[0:1]
	v_mov_b32_e32 v0, v28
	v_mov_b32_e32 v1, v81
	v_mul_f32_e32 v2, v81, v81
	v_pk_fma_f32 v[30:31], v[0:1], v[0:1], v[2:3] op_sel_hi:[1,1,0] neg_lo:[0,0,1] neg_hi:[0,0,1]
	v_pk_mul_f32 v[2:3], v[0:1], v[80:81] op_sel:[0,1] op_sel_hi:[1,0]
	s_nop 0
	v_pk_add_f32 v[82:83], v[2:3], v[2:3]
	v_mov_b32_e32 v2, v30
	v_mov_b32_e32 v3, v82
	v_pk_mul_f32 v[4:5], v[0:1], v[2:3]
	v_pk_mov_b32 v[0:1], v[80:81], v[82:83] op_sel:[1,0]
	v_mov_b32_e32 v3, v28
	v_pk_mul_f32 v[14:15], v[0:1], v[2:3]
	ds_read2st64_b64 v[0:3], v102 offset1:8
	ds_read2st64_b64 v[16:19], v102 offset0:16 offset1:24
	ds_read2st64_b64 v[10:13], v102 offset0:32 offset1:40
	ds_read2st64_b64 v[6:9], v102 offset0:48 offset1:56
	v_pk_add_f32 v[84:85], v[14:15], v[14:15] op_sel:[0,1] op_sel_hi:[0,1]
	s_waitcnt lgkmcnt(2)
	v_pk_mul_f32 v[20:21], v[80:81], v[16:17] op_sel:[1,0]
	s_nop 0
	v_pk_fma_f32 v[22:23], v[28:29], v[16:17], v[20:21] op_sel:[0,0,1] op_sel_hi:[1,1,0]
	v_pk_fma_f32 v[16:17], v[28:29], v[16:17], v[20:21] op_sel:[0,0,1] op_sel_hi:[0,1,0] neg_lo:[0,0,1] neg_hi:[0,0,1]
	v_mov_b32_e32 v23, v17
	s_waitcnt lgkmcnt(1)
	v_pk_mul_f32 v[16:17], v[82:83], v[10:11] op_sel_hi:[0,1]
	v_pk_fma_f32 v[20:21], v[30:31], v[10:11], v[16:17] op_sel:[0,0,1] op_sel_hi:[1,1,0]
	v_pk_fma_f32 v[10:11], v[30:31], v[10:11], v[16:17] op_sel:[0,0,1] op_sel_hi:[0,1,0] neg_lo:[0,0,1] neg_hi:[0,0,1]
	v_mov_b32_e32 v21, v11
	v_pk_add_f32 v[10:11], v[4:5], v[4:5] op_sel:[0,1] op_sel_hi:[0,1] neg_lo:[0,1] neg_hi:[0,1]
	s_waitcnt lgkmcnt(0)
	v_pk_mul_f32 v[4:5], v[84:85], v[6:7]
	s_nop 0
	v_pk_fma_f32 v[14:15], v[10:11], v[6:7], v[4:5] op_sel:[0,0,1] op_sel_hi:[1,1,0]
	v_pk_fma_f32 v[4:5], v[10:11], v[6:7], v[4:5] op_sel:[0,0,1] op_sel_hi:[1,1,0] neg_lo:[0,0,1] neg_hi:[0,0,1]
	s_nop 0
	v_mov_b32_e32 v15, v5
	v_pk_add_f32 v[4:5], v[0:1], v[20:21]
	v_pk_add_f32 v[6:7], v[22:23], v[14:15]
	v_pk_add_f32 v[0:1], v[0:1], v[20:21] neg_lo:[0,1] neg_hi:[0,1]
	v_pk_add_f32 v[14:15], v[22:23], v[14:15] neg_lo:[0,1] neg_hi:[0,1]
	v_pk_add_f32 v[16:17], v[4:5], v[6:7]
	v_pk_add_f32 v[20:21], v[0:1], v[14:15] op_sel:[0,1] op_sel_hi:[1,0]
	v_pk_add_f32 v[0:1], v[0:1], v[14:15] op_sel:[0,1] op_sel_hi:[1,0] neg_lo:[0,1] neg_hi:[0,1]
	v_mov_b32_e32 v14, v20
	v_mov_b32_e32 v15, v1
	v_mov_b32_e32 v1, v21
	ds_write_b64 v102, v[16:17]
	ds_write_b64 v102, v[0:1] offset:8192
	v_pk_add_f32 v[0:1], v[4:5], v[6:7] neg_lo:[0,1] neg_hi:[0,1]
	ds_write_b64 v102, v[0:1] offset:16384
	ds_write_b64 v102, v[14:15] offset:24576
	ds_read2st64_b64 v[4:7], v102 offset0:64 offset1:72
	ds_read2st64_b64 v[24:27], v102 offset0:80 offset1:88
	ds_read2st64_b64 v[20:23], v102 offset0:96 offset1:104
	ds_read2st64_b64 v[14:17], v102 offset0:112 offset1:120
	s_waitcnt lgkmcnt(2)
	v_pk_mul_f32 v[0:1], v[80:81], v[24:25] op_sel:[1,0]
	s_nop 0
	v_pk_fma_f32 v[222:223], v[28:29], v[24:25], v[0:1] op_sel:[0,0,1] op_sel_hi:[1,1,0]
	v_pk_fma_f32 v[0:1], v[28:29], v[24:25], v[0:1] op_sel:[0,0,1] op_sel_hi:[0,1,0] neg_lo:[0,0,1] neg_hi:[0,0,1]
	v_mov_b32_e32 v223, v1
	s_waitcnt lgkmcnt(1)
	v_pk_mul_f32 v[0:1], v[82:83], v[20:21] op_sel_hi:[0,1]
	v_pk_fma_f32 v[24:25], v[30:31], v[20:21], v[0:1] op_sel:[0,0,1] op_sel_hi:[1,1,0]
	v_pk_fma_f32 v[0:1], v[30:31], v[20:21], v[0:1] op_sel:[0,0,1] op_sel_hi:[0,1,0] neg_lo:[0,0,1] neg_hi:[0,0,1]
	v_mov_b32_e32 v25, v1
	s_waitcnt lgkmcnt(0)
	v_pk_mul_f32 v[0:1], v[84:85], v[14:15]
	s_nop 0
	v_pk_fma_f32 v[20:21], v[10:11], v[14:15], v[0:1] op_sel:[0,0,1] op_sel_hi:[1,1,0]
	v_pk_fma_f32 v[0:1], v[10:11], v[14:15], v[0:1] op_sel:[0,0,1] op_sel_hi:[1,1,0] neg_lo:[0,0,1] neg_hi:[0,0,1]
	s_nop 0
	v_mov_b32_e32 v21, v1
	v_pk_add_f32 v[0:1], v[4:5], v[24:25]
	v_pk_add_f32 v[14:15], v[222:223], v[20:21]
	v_pk_add_f32 v[4:5], v[4:5], v[24:25] neg_lo:[0,1] neg_hi:[0,1]
	v_pk_add_f32 v[20:21], v[222:223], v[20:21] neg_lo:[0,1] neg_hi:[0,1]
	v_pk_add_f32 v[224:225], v[0:1], v[14:15]
	v_pk_add_f32 v[24:25], v[4:5], v[20:21] op_sel:[0,1] op_sel_hi:[1,0]
	v_pk_add_f32 v[4:5], v[4:5], v[20:21] op_sel:[0,1] op_sel_hi:[1,0] neg_lo:[0,1] neg_hi:[0,1]
	v_pk_add_f32 v[0:1], v[0:1], v[14:15] neg_lo:[0,1] neg_hi:[0,1]
	v_mov_b32_e32 v20, v24
	v_mov_b32_e32 v21, v5
	v_mov_b32_e32 v5, v25
	ds_write_b64 v102, v[224:225] offset:32768
	ds_write_b64 v102, v[4:5] offset:40960
	ds_write_b64 v102, v[0:1] offset:49152
	ds_write_b64 v102, v[20:21] offset:57344
	ds_read_b64 v[0:1], v103
	ds_read_b64 v[4:5], v104
	ds_read_b64 v[14:15], v105
	ds_read_b64 v[20:21], v106
	s_waitcnt lgkmcnt(2)
	v_pk_mul_f32 v[24:25], v[80:81], v[4:5] op_sel:[1,0]
	s_nop 0
	v_pk_fma_f32 v[222:223], v[28:29], v[4:5], v[24:25] op_sel:[0,0,1] op_sel_hi:[1,1,0]
	v_pk_fma_f32 v[4:5], v[28:29], v[4:5], v[24:25] op_sel:[0,0,1] op_sel_hi:[0,1,0] neg_lo:[0,0,1] neg_hi:[0,0,1]
	v_mov_b32_e32 v223, v5
	s_waitcnt lgkmcnt(1)
	v_pk_mul_f32 v[4:5], v[82:83], v[14:15] op_sel_hi:[0,1]
	v_pk_fma_f32 v[24:25], v[30:31], v[14:15], v[4:5] op_sel:[0,0,1] op_sel_hi:[1,1,0]
	v_pk_fma_f32 v[4:5], v[30:31], v[14:15], v[4:5] op_sel:[0,0,1] op_sel_hi:[0,1,0] neg_lo:[0,0,1] neg_hi:[0,0,1]
	v_mov_b32_e32 v25, v5
	s_waitcnt lgkmcnt(0)
; HD float2 cmul(float2 a, float2 b){ return make_float2(a.x*b.x - a.y*b.y, a.x*b.y + a.y*b.x); }
; HD float2 cmulc(float2 a, float2 b){ return make_float2(a.x*b.x + a.y*b.y, a.y*b.x - a.x*b.y); }
; template<bool INV, bool NOTW>
; HD void bf4c(float2* Z, int i0, int i1, int i2, int i3, float2 w1, float2 w2, float2 w3){
;   float2 a0=Z[i0], a1=Z[i1], a2=Z[i2], a3=Z[i3];
;   if (INV && !NOTW){ a1=cmulc(a1,w1); a2=cmulc(a2,w2); a3=cmulc(a3,w3); }
;   float2 s02=make_float2(a0.x+a2.x,a0.y+a2.y), d02=make_float2(a0.x-a2.x,a0.y-a2.y);
;   float2 s13=make_float2(a1.x+a3.x,a1.y+a3.y), d13=make_float2(a1.x-a3.x,a1.y-a3.y);
;   float2 y0=make_float2(s02.x+s13.x,s02.y+s13.y), y2=make_float2(s02.x-s13.x,s02.y-s13.y);
;   float2 ym=make_float2(d02.x+d13.y,d02.y-d13.x);
;   float2 yp=make_float2(d02.x-d13.y,d02.y+d13.x);
;   float2 y1, y3;
;   if (INV){ y1=yp; y3=ym; } else if (NOTW){ y1=ym; y3=yp; } else { y1=cmul(ym,w1); y2=cmul(y2,w2); y3=cmul(yp,w3); }
;   Z[i0]=y0; Z[i1]=y1; Z[i2]=y2; Z[i3]=y3;
; }
; template<bool INV, int LQ, bool BARRIER=true>
; HD void fft_pass(float2* Z, const float2* twA, const float2* twB, int tid){
;     ...
;     _Pragma("unroll") for (int e=0;e<2;++e){ int j=tid+512*e; int k=j*tws;
;       float2 w1=cmul(twA[k>>6],twB[k&63]), w2=cmul(w1,w1), w3=cmul(w2,w1);
;       _Pragma("unroll") for (int ip=0;ip<4;++ip){ int base=ip*4096+j; bf4c<INV,false>(Z,base,base+q,base+2*q,base+3*q,w1,w2,w3); } }
	v_pk_mul_f32 v[4:5], v[84:85], v[20:21]
	s_nop 0
	v_pk_fma_f32 v[14:15], v[10:11], v[20:21], v[4:5] op_sel:[0,0,1] op_sel_hi:[1,1,0]
	v_pk_fma_f32 v[4:5], v[10:11], v[20:21], v[4:5] op_sel:[0,0,1] op_sel_hi:[1,1,0] neg_lo:[0,0,1] neg_hi:[0,0,1]
	s_nop 0
	v_mov_b32_e32 v15, v5
	v_pk_add_f32 v[4:5], v[0:1], v[24:25]
	v_pk_add_f32 v[20:21], v[222:223], v[14:15]
	v_pk_add_f32 v[0:1], v[0:1], v[24:25] neg_lo:[0,1] neg_hi:[0,1]
	v_pk_add_f32 v[14:15], v[222:223], v[14:15] neg_lo:[0,1] neg_hi:[0,1]
	v_pk_add_f32 v[224:225], v[4:5], v[20:21]
	v_pk_add_f32 v[24:25], v[0:1], v[14:15] op_sel:[0,1] op_sel_hi:[1,0]
	v_pk_add_f32 v[0:1], v[0:1], v[14:15] op_sel:[0,1] op_sel_hi:[1,0] neg_lo:[0,1] neg_hi:[0,1]
	v_mov_b32_e32 v14, v24
	v_mov_b32_e32 v15, v1
	v_mov_b32_e32 v1, v25
	ds_write_b64 v103, v[224:225]
	ds_write_b64 v104, v[0:1]
	v_pk_add_f32 v[0:1], v[4:5], v[20:21] neg_lo:[0,1] neg_hi:[0,1]
	ds_write_b64 v105, v[0:1]
	ds_write_b64 v106, v[14:15]
	ds_read_b64 v[0:1], v107
	ds_read_b64 v[4:5], v108
	ds_read_b64 v[14:15], v109
	ds_read_b64 v[20:21], v110
	s_waitcnt lgkmcnt(2)
	v_pk_mul_f32 v[24:25], v[80:81], v[4:5] op_sel:[1,0]
	s_nop 0
	v_pk_fma_f32 v[80:81], v[28:29], v[4:5], v[24:25] op_sel:[0,0,1] op_sel_hi:[1,1,0]
	v_pk_fma_f32 v[4:5], v[28:29], v[4:5], v[24:25] op_sel:[0,0,1] op_sel_hi:[0,1,0] neg_lo:[0,0,1] neg_hi:[0,0,1]
	v_mov_b32_e32 v81, v5
	s_waitcnt lgkmcnt(1)
	v_pk_mul_f32 v[4:5], v[82:83], v[14:15] op_sel_hi:[0,1]
	v_pk_fma_f32 v[24:25], v[30:31], v[14:15], v[4:5] op_sel:[0,0,1] op_sel_hi:[1,1,0]
	v_pk_fma_f32 v[4:5], v[30:31], v[14:15], v[4:5] op_sel:[0,0,1] op_sel_hi:[0,1,0] neg_lo:[0,0,1] neg_hi:[0,0,1]
	v_mov_b32_e32 v25, v5
	s_waitcnt lgkmcnt(0)
	v_pk_mul_f32 v[4:5], v[84:85], v[20:21]
	s_nop 0
	v_pk_fma_f32 v[14:15], v[10:11], v[20:21], v[4:5] op_sel:[0,0,1] op_sel_hi:[1,1,0]
	v_pk_fma_f32 v[4:5], v[10:11], v[20:21], v[4:5] op_sel:[0,0,1] op_sel_hi:[1,1,0] neg_lo:[0,0,1] neg_hi:[0,0,1]
	s_nop 0
	v_mov_b32_e32 v15, v5
	v_pk_add_f32 v[4:5], v[0:1], v[24:25]
	v_pk_add_f32 v[10:11], v[80:81], v[14:15]
	v_pk_add_f32 v[0:1], v[0:1], v[24:25] neg_lo:[0,1] neg_hi:[0,1]
	v_pk_add_f32 v[14:15], v[80:81], v[14:15] neg_lo:[0,1] neg_hi:[0,1]
	v_pk_add_f32 v[20:21], v[4:5], v[10:11]
	v_pk_add_f32 v[24:25], v[0:1], v[14:15] op_sel:[0,1] op_sel_hi:[1,0]
	v_pk_add_f32 v[0:1], v[0:1], v[14:15] op_sel:[0,1] op_sel_hi:[1,0] neg_lo:[0,1] neg_hi:[0,1]
	v_mov_b32_e32 v14, v24
	v_mov_b32_e32 v15, v1
	v_mov_b32_e32 v1, v25
	ds_write_b64 v107, v[20:21]
	ds_write_b64 v108, v[0:1]
	v_pk_add_f32 v[0:1], v[4:5], v[10:11] neg_lo:[0,1] neg_hi:[0,1]
	ds_write_b64 v109, v[0:1]
	ds_write_b64 v110, v[14:15]
	ds_read_b64 v[0:1], v111
	ds_read_b64 v[4:5], v112
	s_waitcnt lgkmcnt(0)
	v_pk_mul_f32 v[10:11], v[0:1], v[4:5]
	v_pk_mul_f32 v[4:5], v[0:1], v[4:5] op_sel:[1,0] op_sel_hi:[0,1]
	v_mov_b32_e32 v14, v10
	v_mov_b32_e32 v15, v4
	v_mov_b32_e32 v4, v11
	v_pk_add_f32 v[0:1], v[14:15], v[4:5] neg_lo:[0,1] neg_hi:[0,1]
	v_pk_add_f32 v[10:11], v[14:15], v[4:5]
	v_mov_b32_e32 v20, v0
	v_mov_b32_e32 v21, v11
	v_mul_f32_e32 v4, v11, v11
	v_pk_mul_f32 v[14:15], v[20:21], v[10:11] op_sel:[0,1] op_sel_hi:[1,0]
	v_pk_fma_f32 v[4:5], v[20:21], v[20:21], v[4:5] op_sel_hi:[1,1,0] neg_lo:[0,0,1] neg_hi:[0,0,1]
	v_pk_add_f32 v[14:15], v[14:15], v[14:15]
	v_mov_b32_e32 v24, v4
	v_mov_b32_e32 v25, v14
	v_pk_mul_f32 v[20:21], v[20:21], v[24:25]
	v_pk_mov_b32 v[24:25], v[10:11], v[14:15] op_sel:[1,0]
	v_mov_b32_e32 v28, v4
	v_mov_b32_e32 v29, v0
	v_pk_mul_f32 v[24:25], v[24:25], v[28:29]
	v_pk_mul_f32 v[28:29], v[10:11], v[18:19] op_sel:[1,0]
	s_nop 0
	v_pk_fma_f32 v[30:31], v[0:1], v[18:19], v[28:29] op_sel:[0,0,1] op_sel_hi:[1,1,0]
	v_pk_fma_f32 v[18:19], v[0:1], v[18:19], v[28:29] op_sel:[0,0,1] op_sel_hi:[0,1,0] neg_lo:[0,0,1] neg_hi:[0,0,1]
	v_mov_b32_e32 v31, v19
	v_pk_mul_f32 v[18:19], v[14:15], v[12:13] op_sel_hi:[0,1]
	v_pk_fma_f32 v[28:29], v[4:5], v[12:13], v[18:19] op_sel:[0,0,1] op_sel_hi:[1,1,0]
	v_pk_fma_f32 v[12:13], v[4:5], v[12:13], v[18:19] op_sel:[0,0,1] op_sel_hi:[0,1,0] neg_lo:[0,0,1] neg_hi:[0,0,1]
	v_pk_add_f32 v[18:19], v[24:25], v[24:25] op_sel:[0,1] op_sel_hi:[0,1]
	v_mov_b32_e32 v29, v13
	v_pk_add_f32 v[12:13], v[20:21], v[20:21] op_sel:[0,1] op_sel_hi:[0,1] neg_lo:[0,1] neg_hi:[0,1]
	v_pk_mul_f32 v[20:21], v[18:19], v[8:9]
	s_nop 0
	v_pk_fma_f32 v[24:25], v[12:13], v[8:9], v[20:21] op_sel:[0,0,1] op_sel_hi:[1,1,0]
	v_pk_fma_f32 v[8:9], v[12:13], v[8:9], v[20:21] op_sel:[0,0,1] op_sel_hi:[1,1,0] neg_lo:[0,0,1] neg_hi:[0,0,1]
	s_nop 0
	v_mov_b32_e32 v25, v9
	v_pk_add_f32 v[8:9], v[2:3], v[28:29]
	v_pk_add_f32 v[20:21], v[30:31], v[24:25]
	v_pk_add_f32 v[2:3], v[2:3], v[28:29] neg_lo:[0,1] neg_hi:[0,1]
	v_pk_add_f32 v[24:25], v[30:31], v[24:25] neg_lo:[0,1] neg_hi:[0,1]
	v_pk_add_f32 v[80:81], v[8:9], v[20:21]
	v_pk_add_f32 v[28:29], v[2:3], v[24:25] op_sel:[0,1] op_sel_hi:[1,0]
	v_pk_add_f32 v[2:3], v[2:3], v[24:25] op_sel:[0,1] op_sel_hi:[1,0] neg_lo:[0,1] neg_hi:[0,1]
	v_mov_b32_e32 v24, v28
	v_mov_b32_e32 v25, v3
	v_mov_b32_e32 v3, v29
	ds_write_b64 v102, v[80:81] offset:4096
	ds_write_b64 v102, v[2:3] offset:12288
	v_pk_add_f32 v[2:3], v[8:9], v[20:21] neg_lo:[0,1] neg_hi:[0,1]
	ds_write_b64 v102, v[2:3] offset:20480
	ds_write_b64 v102, v[24:25] offset:28672
	v_pk_mul_f32 v[2:3], v[10:11], v[26:27] op_sel:[1,0]
	s_nop 0
	v_pk_fma_f32 v[8:9], v[0:1], v[26:27], v[2:3] op_sel:[0,0,1] op_sel_hi:[1,1,0]
	v_pk_fma_f32 v[2:3], v[0:1], v[26:27], v[2:3] op_sel:[0,0,1] op_sel_hi:[0,1,0] neg_lo:[0,0,1] neg_hi:[0,0,1]
	v_mov_b32_e32 v9, v3
	v_pk_mul_f32 v[2:3], v[14:15], v[22:23] op_sel_hi:[0,1]
	v_pk_fma_f32 v[20:21], v[4:5], v[22:23], v[2:3] op_sel:[0,0,1] op_sel_hi:[1,1,0]
	v_pk_fma_f32 v[2:3], v[4:5], v[22:23], v[2:3] op_sel:[0,0,1] op_sel_hi:[0,1,0] neg_lo:[0,0,1] neg_hi:[0,0,1]
	v_mov_b32_e32 v21, v3
	v_pk_mul_f32 v[2:3], v[18:19], v[16:17]
	s_nop 0
	v_pk_fma_f32 v[22:23], v[12:13], v[16:17], v[2:3] op_sel:[0,0,1] op_sel_hi:[1,1,0]
	v_pk_fma_f32 v[2:3], v[12:13], v[16:17], v[2:3] op_sel:[0,0,1] op_sel_hi:[1,1,0] neg_lo:[0,0,1] neg_hi:[0,0,1]
	s_nop 0
	v_mov_b32_e32 v23, v3
	v_pk_add_f32 v[2:3], v[6:7], v[20:21]
	v_pk_add_f32 v[16:17], v[8:9], v[22:23]
	v_pk_add_f32 v[6:7], v[6:7], v[20:21] neg_lo:[0,1] neg_hi:[0,1]
	v_pk_add_f32 v[8:9], v[8:9], v[22:23] neg_lo:[0,1] neg_hi:[0,1]
	v_pk_add_f32 v[24:25], v[2:3], v[16:17]
	v_pk_add_f32 v[20:21], v[6:7], v[8:9] op_sel:[0,1] op_sel_hi:[1,0]
	v_pk_add_f32 v[6:7], v[6:7], v[8:9] op_sel:[0,1] op_sel_hi:[1,0] neg_lo:[0,1] neg_hi:[0,1]
	v_pk_add_f32 v[2:3], v[2:3], v[16:17] neg_lo:[0,1] neg_hi:[0,1]
	v_mov_b32_e32 v8, v20
	v_mov_b32_e32 v9, v7
	v_mov_b32_e32 v7, v21
	ds_write_b64 v102, v[24:25] offset:36864
	ds_write_b64 v102, v[6:7] offset:45056
	ds_write_b64 v102, v[2:3] offset:53248
	ds_write_b64 v102, v[8:9] offset:61440
	ds_read_b64 v[2:3], v113
	ds_read_b64 v[6:7], v114
	ds_read_b64 v[8:9], v115
	ds_read_b64 v[16:17], v116
	s_waitcnt lgkmcnt(2)
; HD float2 cmul(float2 a, float2 b){ return make_float2(a.x*b.x - a.y*b.y, a.x*b.y + a.y*b.x); }
; template<bool INV, int LQ, bool BARRIER=true>
; HD void fft_pass(float2* Z, const float2* twA, const float2* twB, int tid){
;     ...
;     _Pragma("unroll") for (int e=0;e<2;++e){ int j=tid+512*e; int k=j*tws;
;       float2 w1=cmul(twA[k>>6],twB[k&63]), w2=cmul(w1,w1), w3=cmul(w2,w1);
;       _Pragma("unroll") for (int ip=0;ip<4;++ip){ int base=ip*4096+j; bf4c<INV,false>(Z,base,base+q,base+2*q,base+3*q,w1,w2,w3); } }
; __device__ __forceinline__ void phase_hyena(KP kp_, int hf){ asm volatile("" : "+s"(kp_)); const Params p=load_params(kp_);
;     ...
;         if (st==1){ int tq=tid; asm volatile("" : "+v"(tq));
;           _Pragma("unroll 4") for (int i=0;i<8;++i){ int tb=tq+512*i; float2 xr[2]; inv12_half(Z,twA,twB,tb,xr[0],xr[1]);
;             _Pragma("unroll") for (int hh=0;hh<2;++hh){ int t=tb+hh*4096;
	v_pk_mul_f32 v[20:21], v[10:11], v[6:7] op_sel:[1,0]
	s_nop 0
	v_pk_fma_f32 v[22:23], v[0:1], v[6:7], v[20:21] op_sel:[0,0,1] op_sel_hi:[1,1,0]
	v_pk_fma_f32 v[6:7], v[0:1], v[6:7], v[20:21] op_sel:[0,0,1] op_sel_hi:[0,1,0] neg_lo:[0,0,1] neg_hi:[0,0,1]
	v_mov_b32_e32 v23, v7
	s_waitcnt lgkmcnt(1)
	v_pk_mul_f32 v[6:7], v[14:15], v[8:9] op_sel_hi:[0,1]
	v_pk_fma_f32 v[20:21], v[4:5], v[8:9], v[6:7] op_sel:[0,0,1] op_sel_hi:[1,1,0]
	v_pk_fma_f32 v[6:7], v[4:5], v[8:9], v[6:7] op_sel:[0,0,1] op_sel_hi:[0,1,0] neg_lo:[0,0,1] neg_hi:[0,0,1]
	v_mov_b32_e32 v21, v7
	s_waitcnt lgkmcnt(0)
	v_pk_mul_f32 v[6:7], v[18:19], v[16:17]
	s_nop 0
	v_pk_fma_f32 v[8:9], v[12:13], v[16:17], v[6:7] op_sel:[0,0,1] op_sel_hi:[1,1,0]
	v_pk_fma_f32 v[6:7], v[12:13], v[16:17], v[6:7] op_sel:[0,0,1] op_sel_hi:[1,1,0] neg_lo:[0,0,1] neg_hi:[0,0,1]
	s_nop 0
	v_mov_b32_e32 v9, v7
	v_pk_add_f32 v[6:7], v[2:3], v[20:21]
	v_pk_add_f32 v[16:17], v[22:23], v[8:9]
	v_pk_add_f32 v[2:3], v[2:3], v[20:21] neg_lo:[0,1] neg_hi:[0,1]
	v_pk_add_f32 v[8:9], v[22:23], v[8:9] neg_lo:[0,1] neg_hi:[0,1]
	v_pk_add_f32 v[24:25], v[6:7], v[16:17]
	v_pk_add_f32 v[20:21], v[2:3], v[8:9] op_sel:[0,1] op_sel_hi:[1,0]
	v_pk_add_f32 v[2:3], v[2:3], v[8:9] op_sel:[0,1] op_sel_hi:[1,0] neg_lo:[0,1] neg_hi:[0,1]
	v_mov_b32_e32 v8, v20
	v_mov_b32_e32 v9, v3
	v_mov_b32_e32 v3, v21
	ds_write_b64 v113, v[24:25]
	ds_write_b64 v114, v[2:3]
	v_pk_add_f32 v[2:3], v[6:7], v[16:17] neg_lo:[0,1] neg_hi:[0,1]
	ds_write_b64 v115, v[2:3]
	ds_write_b64 v116, v[8:9]
	ds_read_b64 v[2:3], v117
	ds_read_b64 v[6:7], v118
	ds_read_b64 v[8:9], v119
	ds_read_b64 v[16:17], v120
	s_waitcnt lgkmcnt(2)
	v_pk_mul_f32 v[10:11], v[10:11], v[6:7] op_sel:[1,0]
	s_nop 0
	v_pk_fma_f32 v[20:21], v[0:1], v[6:7], v[10:11] op_sel:[0,0,1] op_sel_hi:[1,1,0]
	v_pk_fma_f32 v[0:1], v[0:1], v[6:7], v[10:11] op_sel:[0,0,1] op_sel_hi:[0,1,0] neg_lo:[0,0,1] neg_hi:[0,0,1]
	v_mov_b32_e32 v21, v1
	s_waitcnt lgkmcnt(1)
	v_pk_mul_f32 v[0:1], v[14:15], v[8:9] op_sel_hi:[0,1]
	v_pk_fma_f32 v[6:7], v[4:5], v[8:9], v[0:1] op_sel:[0,0,1] op_sel_hi:[1,1,0]
	v_pk_fma_f32 v[0:1], v[4:5], v[8:9], v[0:1] op_sel:[0,0,1] op_sel_hi:[0,1,0] neg_lo:[0,0,1] neg_hi:[0,0,1]
	v_mov_b32_e32 v7, v1
	s_waitcnt lgkmcnt(0)
	v_pk_mul_f32 v[0:1], v[18:19], v[16:17]
	s_nop 0
	v_pk_fma_f32 v[4:5], v[12:13], v[16:17], v[0:1] op_sel:[0,0,1] op_sel_hi:[1,1,0]
	v_pk_fma_f32 v[0:1], v[12:13], v[16:17], v[0:1] op_sel:[0,0,1] op_sel_hi:[1,1,0] neg_lo:[0,0,1] neg_hi:[0,0,1]
	s_nop 0
	v_mov_b32_e32 v5, v1
	v_pk_add_f32 v[0:1], v[2:3], v[6:7]
	v_pk_add_f32 v[8:9], v[20:21], v[4:5]
	v_pk_add_f32 v[2:3], v[2:3], v[6:7] neg_lo:[0,1] neg_hi:[0,1]
	v_pk_add_f32 v[4:5], v[20:21], v[4:5] neg_lo:[0,1] neg_hi:[0,1]
	v_pk_add_f32 v[10:11], v[0:1], v[8:9]
	v_pk_add_f32 v[6:7], v[2:3], v[4:5] op_sel:[0,1] op_sel_hi:[1,0]
	v_pk_add_f32 v[2:3], v[2:3], v[4:5] op_sel:[0,1] op_sel_hi:[1,0] neg_lo:[0,1] neg_hi:[0,1]
	v_pk_add_f32 v[0:1], v[0:1], v[8:9] neg_lo:[0,1] neg_hi:[0,1]
	v_mov_b32_e32 v4, v6
	v_mov_b32_e32 v5, v3
	v_mov_b32_e32 v3, v7
	ds_write_b64 v117, v[10:11]
	ds_write_b64 v118, v[2:3]
	ds_write_b64 v119, v[0:1]
	ds_write_b64 v120, v[4:5]
	s_waitcnt lgkmcnt(0)
	s_barrier
	s_cbranch_vccz .LBB0_1340
	v_mov_b32_e32 v0, v86
	s_mov_b64 s[50:51], 0
	v_and_b32_e32 v1, 63, v0
	v_lshl_add_u32 v30, v1, 3, s91
	v_ashrrev_i32_e32 v1, 31, v0
	v_lshlrev_b64 v[6:7], 1, v[0:1]
	v_lshl_add_u64 v[2:3], v[76:77], 0, v[6:7]
	v_lshl_add_u64 v[4:5], s[14:15], 0, v[6:7]
	v_lshl_add_u64 v[6:7], s[54:55], 0, v[6:7]
	v_lshl_add_u32 v31, v0, 3, 0

; __global__ void __launch_bounds__(NTH) mega(Params p_arg){
	.amdhsa_kernel _Z4mega6Params
		.amdhsa_group_segment_fixed_size 0
		.amdhsa_private_segment_fixed_size 0
		.amdhsa_kernarg_size 496
		.amdhsa_user_sgpr_count 2
		.amdhsa_user_sgpr_dispatch_ptr 0
		.amdhsa_user_sgpr_queue_ptr 0
		.amdhsa_user_sgpr_kernarg_segment_ptr 1
		.amdhsa_user_sgpr_dispatch_id 0
		.amdhsa_user_sgpr_kernarg_preload_length 0
		.amdhsa_user_sgpr_kernarg_preload_offset 0
		.amdhsa_user_sgpr_private_segment_size 0
		.amdhsa_uses_dynamic_stack 0
		.amdhsa_enable_private_segment 0
		.amdhsa_system_sgpr_workgroup_id_x 1
		.amdhsa_system_sgpr_workgroup_id_y 0
		.amdhsa_system_sgpr_workgroup_id_z 0
		.amdhsa_system_sgpr_workgroup_info 0
		.amdhsa_system_vgpr_workitem_id 2
		.amdhsa_next_free_vgpr 255
		.amdhsa_next_free_sgpr 102
		.amdhsa_accum_offset 256
		.amdhsa_reserve_vcc 1
		.amdhsa_float_round_mode_32 0
		.amdhsa_float_round_mode_16_64 0
		.amdhsa_float_denorm_mode_32 3
		.amdhsa_float_denorm_mode_16_64 3
		.amdhsa_dx10_clamp 1
		.amdhsa_ieee_mode 1
		.amdhsa_fp16_overflow 0
		.amdhsa_tg_split 0
		.amdhsa_exception_fp_ieee_invalid_op 0
		.amdhsa_exception_fp_denorm_src 0
		.amdhsa_exception_fp_ieee_div_zero 0
		.amdhsa_exception_fp_ieee_overflow 0
		.amdhsa_exception_fp_ieee_underflow 0
		.amdhsa_exception_fp_ieee_inexact 0
		.amdhsa_exception_int_div_zero 0
	.end_amdhsa_kernel

; __global__ void __launch_bounds__(NTH) mega(Params p_arg){
amdhsa.kernels:
  - .agpr_count:     0
    .args:
      - .offset:         0
        .size:           240
        .value_kind:     by_value
      - .offset:         240
        .size:           4
        .value_kind:     hidden_block_count_x
      - .offset:         244
        .size:           4
        .value_kind:     hidden_block_count_y
      - .offset:         248
        .size:           4
        .value_kind:     hidden_block_count_z
      - .offset:         252
        .size:           2
        .value_kind:     hidden_group_size_x
      - .offset:         254
        .size:           2
        .value_kind:     hidden_group_size_y
      - .offset:         256
        .size:           2
        .value_kind:     hidden_group_size_z
      - .offset:         258
        .size:           2
        .value_kind:     hidden_remainder_x
      - .offset:         260
        .size:           2
        .value_kind:     hidden_remainder_y
      - .offset:         262
        .size:           2
        .value_kind:     hidden_remainder_z
      - .offset:         280
        .size:           8
        .value_kind:     hidden_global_offset_x
      - .offset:         288
        .size:           8
        .value_kind:     hidden_global_offset_y
      - .offset:         296
        .size:           8
        .value_kind:     hidden_global_offset_z
      - .offset:         304
        .size:           2
        .value_kind:     hidden_grid_dims
      - .offset:         328
        .size:           8
        .value_kind:     hidden_multigrid_sync_arg
      - .offset:         360
        .size:           4
        .value_kind:     hidden_dynamic_lds_size
    .group_segment_fixed_size: 0
    .kernarg_segment_align: 8
    .kernarg_segment_size: 496
    .language:       OpenCL C
    .language_version:
      - 2
      - 0
    .max_flat_workgroup_size: 512
    .name:           _Z4mega6Params
    .private_segment_fixed_size: 0
    .sgpr_count:     108
    .sgpr_spill_count: 197
    .symbol:         _Z4mega6Params.kd
    .uniform_work_group_size: 1
    .uses_dynamic_stack: false
    .vgpr_count:     255
    .vgpr_spill_count: 0
    .wavefront_size: 64
